# v9_allnt
# speedup vs baseline: 1.0103x; 1.0038x over previous
; __device__ __forceinline__ void gemm_tile(const Params& P, const GArgs& ga, const TileDesc& td, int wid_s) {
;     ...
;   } else if (mode == M_PART) {
;     u16* __restrict__ pp = WSU(PART) + ((size_t)sp * NS + (rbase - NP)) * DM + c4;
;     static_for<32>([&](auto ic) __attribute__((always_inline)) {
;       EPI_IDX;
;       uint2 o; o.x = pack2(acc[ai][0][m][0][j], acc[ai][0][m][1][j]); o.y = pack2(acc[ai][1][m][0][j], acc[ai][1][m][1][j]);
;       *reinterpret_cast<uint2*>(pp + (size_t)rl * DM) = o;
;       if constexpr ((idx & 7) == 7) __builtin_amdgcn_sched_barrier(0);
;     });
.Lnt_skip:
	s_mov_b32 s17, 0x358637bd
	v_mov_b32_e32 v0, v200
	s_mov_b64 s[0:1], -1
	v_ashrrev_i32_e32 v130, 2, v0
	v_and_b32_e32 v203, 15, v0
	v_and_b32_e32 v130, 0xffffffc0, v130
	v_lshrrev_b32_e32 v131, 2, v0
	v_and_b32_e32 v0, 0xc0, v0
	v_add_u32_e32 v130, s84, v130
	v_lshl_or_b32 v0, v203, 2, v0
	v_and_or_b32 v166, v131, 12, v130
	v_or_b32_e32 v168, s92, v0
	s_mov_b64 s[84:85], 0
	s_cmp_lt_i32 s79, 2
	s_mov_b64 s[8:9], 0
	s_cbranch_scc1 .LBB0_597
	s_cmp_gt_i32 s79, 2
	s_cbranch_scc0 .LBB0_323
	s_cmp_gt_i32 s79, 4
	s_cbranch_scc0 .LBB0_319
	s_cmp_eq_u32 s79, 5
	s_mov_b64 s[8:9], -1
	s_cbranch_scc0 .LBB0_318
	s_lshl_b32 s0, s87, 22
	v_readlane_b32 s4, v231, 62
	v_ashrrev_i32_e32 v167, 31, v166
	v_readlane_b32 s5, v231, 63
	s_add_u32 s0, s4, s0
	v_lshlrev_b64 v[130:131], 12, v[166:167]
	s_addc_u32 s1, s5, 0
	v_lshl_add_u64 v[130:131], s[0:1], 0, v[130:131]
	v_ashrrev_i32_e32 v169, 31, v168
	v_lshl_add_u64 v[130:131], v[168:169], 1, v[130:131]
	s_mov_b32 s0, 0xfc001000
	v_add_co_u32_e32 v134, vcc, s0, v130
	v_cvt_pk_bf16_f32 v132, v114, v118
	v_cvt_pk_bf16_f32 v133, v126, v122
	v_addc_co_u32_e32 v135, vcc, -1, v131, vcc
	global_store_dwordx2 v[134:135], v[132:133], off offset:-4096 nt
	v_cvt_pk_bf16_f32 v132, v115, v119
	v_cvt_pk_bf16_f32 v133, v127, v123
	s_mov_b32 s0, 0xfc003000
	global_store_dwordx2 v[134:135], v[132:133], off nt
	v_add_co_u32_e32 v134, vcc, s0, v130
	v_cvt_pk_bf16_f32 v132, v116, v120
	v_cvt_pk_bf16_f32 v133, v128, v124
	v_addc_co_u32_e32 v135, vcc, -1, v131, vcc
	global_store_dwordx2 v[134:135], v[132:133], off offset:-4096 nt
	v_cvt_pk_bf16_f32 v132, v117, v121
	v_cvt_pk_bf16_f32 v133, v129, v125
	s_mov_b32 s0, 0xfc011000
	global_store_dwordx2 v[134:135], v[132:133], off nt
	v_add_co_u32_e32 v134, vcc, s0, v130
	v_cvt_pk_bf16_f32 v132, v98, v102
	v_cvt_pk_bf16_f32 v133, v110, v106
	v_addc_co_u32_e32 v135, vcc, -1, v131, vcc
	global_store_dwordx2 v[134:135], v[132:133], off offset:-4096 nt
	v_cvt_pk_bf16_f32 v132, v99, v103
	v_cvt_pk_bf16_f32 v133, v111, v107
	s_mov_b32 s0, 0xfc013000
	global_store_dwordx2 v[134:135], v[132:133], off nt
	v_add_co_u32_e32 v134, vcc, s0, v130
	v_cvt_pk_bf16_f32 v132, v100, v104
	v_cvt_pk_bf16_f32 v133, v112, v108
	v_addc_co_u32_e32 v135, vcc, -1, v131, vcc
	global_store_dwordx2 v[134:135], v[132:133], off offset:-4096 nt
	v_cvt_pk_bf16_f32 v132, v101, v105
	v_cvt_pk_bf16_f32 v133, v113, v109
	global_store_dwordx2 v[134:135], v[132:133], off nt
	s_mov_b32 s0, 0xfc021000
	v_add_co_u32_e32 v134, vcc, s0, v130
	v_cvt_pk_bf16_f32 v132, v82, v86
	v_cvt_pk_bf16_f32 v133, v94, v90
	v_addc_co_u32_e32 v135, vcc, -1, v131, vcc
	global_store_dwordx2 v[134:135], v[132:133], off offset:-4096 nt
	v_cvt_pk_bf16_f32 v132, v83, v87
	v_cvt_pk_bf16_f32 v133, v95, v91
	s_mov_b32 s0, 0xfc023000
	global_store_dwordx2 v[134:135], v[132:133], off nt
	v_add_co_u32_e32 v134, vcc, s0, v130
	v_cvt_pk_bf16_f32 v132, v84, v88
	v_cvt_pk_bf16_f32 v133, v96, v92
	v_addc_co_u32_e32 v135, vcc, -1, v131, vcc
	global_store_dwordx2 v[134:135], v[132:133], off offset:-4096 nt
	v_cvt_pk_bf16_f32 v132, v85, v89
	v_cvt_pk_bf16_f32 v133, v97, v93
	s_mov_b32 s0, 0xfc031000
	global_store_dwordx2 v[134:135], v[132:133], off nt
	v_add_co_u32_e32 v134, vcc, s0, v130
	v_cvt_pk_bf16_f32 v132, v66, v70
	v_cvt_pk_bf16_f32 v133, v78, v74
	v_addc_co_u32_e32 v135, vcc, -1, v131, vcc
	global_store_dwordx2 v[134:135], v[132:133], off offset:-4096 nt
	v_cvt_pk_bf16_f32 v132, v67, v71
	v_cvt_pk_bf16_f32 v133, v79, v75
	s_mov_b32 s0, 0xfc033000
	global_store_dwordx2 v[134:135], v[132:133], off nt
	v_add_co_u32_e32 v134, vcc, s0, v130
	v_cvt_pk_bf16_f32 v132, v68, v72
	v_cvt_pk_bf16_f32 v133, v80, v76
	v_addc_co_u32_e32 v135, vcc, -1, v131, vcc
	global_store_dwordx2 v[134:135], v[132:133], off offset:-4096 nt
	v_cvt_pk_bf16_f32 v132, v69, v73
	v_cvt_pk_bf16_f32 v133, v81, v77
	global_store_dwordx2 v[134:135], v[132:133], off nt
	s_mov_b32 s0, 0xfc081000
	v_add_co_u32_e32 v134, vcc, s0, v130
	v_cvt_pk_bf16_f32 v132, v50, v54
	v_cvt_pk_bf16_f32 v133, v62, v58
	v_addc_co_u32_e32 v135, vcc, -1, v131, vcc
	global_store_dwordx2 v[134:135], v[132:133], off offset:-4096 nt
	v_cvt_pk_bf16_f32 v132, v51, v55
	v_cvt_pk_bf16_f32 v133, v63, v59
	s_mov_b32 s0, 0xfc083000
	global_store_dwordx2 v[134:135], v[132:133], off nt
	v_add_co_u32_e32 v134, vcc, s0, v130
	v_cvt_pk_bf16_f32 v132, v52, v56
	v_cvt_pk_bf16_f32 v133, v64, v60
	v_addc_co_u32_e32 v135, vcc, -1, v131, vcc
	global_store_dwordx2 v[134:135], v[132:133], off offset:-4096 nt
	v_cvt_pk_bf16_f32 v132, v53, v57
	v_cvt_pk_bf16_f32 v133, v65, v61
	s_mov_b32 s0, 0xfc091000
	global_store_dwordx2 v[134:135], v[132:133], off nt
	v_add_co_u32_e32 v134, vcc, s0, v130
	v_cvt_pk_bf16_f32 v132, v34, v38
	v_cvt_pk_bf16_f32 v133, v46, v42
	v_addc_co_u32_e32 v135, vcc, -1, v131, vcc
	global_store_dwordx2 v[134:135], v[132:133], off offset:-4096 nt
	v_cvt_pk_bf16_f32 v132, v35, v39
	v_cvt_pk_bf16_f32 v133, v47, v43
	s_mov_b32 s0, 0xfc093000
	global_store_dwordx2 v[134:135], v[132:133], off nt
	v_add_co_u32_e32 v134, vcc, s0, v130
	v_cvt_pk_bf16_f32 v132, v36, v40
	v_cvt_pk_bf16_f32 v133, v48, v44
	v_addc_co_u32_e32 v135, vcc, -1, v131, vcc
	global_store_dwordx2 v[134:135], v[132:133], off offset:-4096 nt
	v_cvt_pk_bf16_f32 v132, v37, v41
	v_cvt_pk_bf16_f32 v133, v49, v45
	global_store_dwordx2 v[134:135], v[132:133], off nt
	s_mov_b32 s0, 0xfc0a1000
	v_add_co_u32_e32 v134, vcc, s0, v130
	v_cvt_pk_bf16_f32 v132, v18, v22
	v_cvt_pk_bf16_f32 v133, v30, v26
	v_addc_co_u32_e32 v135, vcc, -1, v131, vcc
	global_store_dwordx2 v[134:135], v[132:133], off offset:-4096 nt
	v_cvt_pk_bf16_f32 v132, v19, v23
	v_cvt_pk_bf16_f32 v133, v31, v27
	s_mov_b32 s0, 0xfc0a3000
	global_store_dwordx2 v[134:135], v[132:133], off nt
	v_add_co_u32_e32 v134, vcc, s0, v130
	v_cvt_pk_bf16_f32 v132, v20, v24
	v_cvt_pk_bf16_f32 v133, v32, v28
	v_addc_co_u32_e32 v135, vcc, -1, v131, vcc
	global_store_dwordx2 v[134:135], v[132:133], off offset:-4096 nt
	v_cvt_pk_bf16_f32 v132, v21, v25
	v_cvt_pk_bf16_f32 v133, v33, v29
	s_mov_b32 s0, 0xfc0b1000
	global_store_dwordx2 v[134:135], v[132:133], off nt
	v_add_co_u32_e32 v134, vcc, s0, v130
	v_cvt_pk_bf16_f32 v132, v2, v6
	v_cvt_pk_bf16_f32 v133, v14, v10
	v_addc_co_u32_e32 v135, vcc, -1, v131, vcc
	global_store_dwordx2 v[134:135], v[132:133], off offset:-4096 nt
	v_cvt_pk_bf16_f32 v132, v3, v7
	v_cvt_pk_bf16_f32 v133, v15, v11
	s_mov_b32 s0, 0xfc0b2000
	global_store_dwordx2 v[134:135], v[132:133], off nt
	v_add_co_u32_e32 v134, vcc, s0, v130
	v_cvt_pk_bf16_f32 v132, v4, v8
	s_nop 0
	v_addc_co_u32_e32 v135, vcc, -1, v131, vcc
	v_cvt_pk_bf16_f32 v133, v16, v12
	v_add_co_u32_e32 v130, vcc, 0xfc0b3000, v130
	global_store_dwordx2 v[134:135], v[132:133], off nt
	v_cvt_pk_bf16_f32 v132, v5, v9
	v_cvt_pk_bf16_f32 v133, v17, v13
	v_addc_co_u32_e32 v131, vcc, -1, v131, vcc
	global_store_dwordx2 v[130:131], v[132:133], off nt
	s_mov_b64 s[8:9], 0

; __device__ __forceinline__ void gemm_tile(const Params& P, const GArgs& ga, const TileDesc& td, int wid_s) {
;     ...
;   } else if (mode == M_PE) {
;     u16* __restrict__ pd = WSU(PEB) + (size_t)rbase * DM + c4;
;     static_for<32>([&](auto ic) __attribute__((always_inline)) {
;       EPI_IDX;
;       uint2 o; o.x = pack2(acc[ai][0][m][0][j], acc[ai][0][m][1][j]); o.y = pack2(acc[ai][1][m][0][j], acc[ai][1][m][1][j]);
;       *reinterpret_cast<uint2*>(pd + (size_t)rl * DM) = o;
;       if constexpr ((idx & 7) == 7) __builtin_amdgcn_sched_barrier(0);
;     });
.LBB0_319:
	s_and_b64 vcc, exec, s[0:1]
	s_cbranch_vccz .LBB0_322
	s_cmp_eq_u32 s79, 3
	s_mov_b64 s[8:9], -1
	s_cbranch_scc0 .LBB0_322
	v_ashrrev_i32_e32 v167, 31, v166
	v_lshlrev_b64 v[130:131], 12, v[166:167]
	v_lshl_add_u64 v[130:131], s[62:63], 0, v[130:131]
	v_ashrrev_i32_e32 v169, 31, v168
	v_lshl_add_u64 v[130:131], v[168:169], 1, v[130:131]
	v_cvt_pk_bf16_f32 v132, v114, v118
	v_cvt_pk_bf16_f32 v133, v126, v122
	v_add_co_u32_e32 v134, vcc, s2, v130
	global_store_dwordx2 v[130:131], v[132:133], off nt
	v_cvt_pk_bf16_f32 v132, v115, v119
	v_cvt_pk_bf16_f32 v133, v127, v123
	v_addc_co_u32_e32 v135, vcc, 0, v131, vcc
	global_store_dwordx2 v[134:135], v[132:133], off offset:-4096 nt
	v_cvt_pk_bf16_f32 v132, v116, v120
	v_cvt_pk_bf16_f32 v133, v128, v124
	global_store_dwordx2 v[134:135], v[132:133], off nt
	v_add_co_u32_e32 v134, vcc, s55, v130
	v_cvt_pk_bf16_f32 v132, v117, v121
	v_cvt_pk_bf16_f32 v133, v129, v125
	v_addc_co_u32_e32 v135, vcc, 0, v131, vcc
	global_store_dwordx2 v[134:135], v[132:133], off nt
	v_add_co_u32_e32 v134, vcc, s13, v130
	v_cvt_pk_bf16_f32 v132, v98, v102
	v_cvt_pk_bf16_f32 v133, v110, v106
	v_addc_co_u32_e32 v135, vcc, 0, v131, vcc
	global_store_dwordx2 v[134:135], v[132:133], off offset:-4096 nt
	v_cvt_pk_bf16_f32 v132, v99, v103
	v_cvt_pk_bf16_f32 v133, v111, v107
	global_store_dwordx2 v[134:135], v[132:133], off nt
	v_add_co_u32_e32 v134, vcc, s14, v130
	v_cvt_pk_bf16_f32 v132, v100, v104
	v_cvt_pk_bf16_f32 v133, v112, v108
	v_addc_co_u32_e32 v135, vcc, 0, v131, vcc
	global_store_dwordx2 v[134:135], v[132:133], off offset:-4096 nt
	v_cvt_pk_bf16_f32 v132, v101, v105
	v_cvt_pk_bf16_f32 v133, v113, v109
	global_store_dwordx2 v[134:135], v[132:133], off nt
	s_mov_b32 s0, 0x21000
	v_add_co_u32_e32 v134, vcc, s0, v130
	v_cvt_pk_bf16_f32 v132, v82, v86
	v_cvt_pk_bf16_f32 v133, v94, v90
	v_addc_co_u32_e32 v135, vcc, 0, v131, vcc
	global_store_dwordx2 v[134:135], v[132:133], off offset:-4096 nt
	v_cvt_pk_bf16_f32 v132, v83, v87
	v_cvt_pk_bf16_f32 v133, v95, v91
	s_mov_b32 s0, 0x23000
	global_store_dwordx2 v[134:135], v[132:133], off nt
	v_add_co_u32_e32 v134, vcc, s0, v130
	v_cvt_pk_bf16_f32 v132, v84, v88
	v_cvt_pk_bf16_f32 v133, v96, v92
	v_addc_co_u32_e32 v135, vcc, 0, v131, vcc
	global_store_dwordx2 v[134:135], v[132:133], off offset:-4096 nt
	v_cvt_pk_bf16_f32 v132, v85, v89
	v_cvt_pk_bf16_f32 v133, v97, v93
	global_store_dwordx2 v[134:135], v[132:133], off nt
	v_add_co_u32_e32 v134, vcc, s19, v130
	v_cvt_pk_bf16_f32 v132, v66, v70
	v_cvt_pk_bf16_f32 v133, v78, v74
	v_addc_co_u32_e32 v135, vcc, 0, v131, vcc
	global_store_dwordx2 v[134:135], v[132:133], off offset:-4096 nt
	v_cvt_pk_bf16_f32 v132, v67, v71
	v_cvt_pk_bf16_f32 v133, v79, v75
	s_mov_b32 s0, 0x33000
	global_store_dwordx2 v[134:135], v[132:133], off nt
	v_add_co_u32_e32 v134, vcc, s0, v130
	v_cvt_pk_bf16_f32 v132, v68, v72
	v_cvt_pk_bf16_f32 v133, v80, v76
	v_addc_co_u32_e32 v135, vcc, 0, v131, vcc
	global_store_dwordx2 v[134:135], v[132:133], off offset:-4096 nt
	v_cvt_pk_bf16_f32 v132, v69, v73
	v_cvt_pk_bf16_f32 v133, v81, v77
	global_store_dwordx2 v[134:135], v[132:133], off nt
	s_mov_b32 s0, 0x81000
	v_add_co_u32_e32 v134, vcc, s0, v130
	v_cvt_pk_bf16_f32 v132, v50, v54
	v_cvt_pk_bf16_f32 v133, v62, v58
	v_addc_co_u32_e32 v135, vcc, 0, v131, vcc
	global_store_dwordx2 v[134:135], v[132:133], off offset:-4096 nt
	v_cvt_pk_bf16_f32 v132, v51, v55
	v_cvt_pk_bf16_f32 v133, v63, v59
	s_mov_b32 s0, 0x83000
	global_store_dwordx2 v[134:135], v[132:133], off nt
	v_add_co_u32_e32 v134, vcc, s0, v130
	v_cvt_pk_bf16_f32 v132, v52, v56
	v_cvt_pk_bf16_f32 v133, v64, v60
	v_addc_co_u32_e32 v135, vcc, 0, v131, vcc
	global_store_dwordx2 v[134:135], v[132:133], off offset:-4096 nt
	v_cvt_pk_bf16_f32 v132, v53, v57
	v_cvt_pk_bf16_f32 v133, v65, v61
	s_mov_b32 s0, 0x91000
	global_store_dwordx2 v[134:135], v[132:133], off nt
	v_add_co_u32_e32 v134, vcc, s0, v130
	v_cvt_pk_bf16_f32 v132, v34, v38
	v_cvt_pk_bf16_f32 v133, v46, v42
	v_addc_co_u32_e32 v135, vcc, 0, v131, vcc
	global_store_dwordx2 v[134:135], v[132:133], off offset:-4096 nt
	v_cvt_pk_bf16_f32 v132, v35, v39
	v_cvt_pk_bf16_f32 v133, v47, v43
	s_mov_b32 s0, 0x93000
	global_store_dwordx2 v[134:135], v[132:133], off nt
	v_add_co_u32_e32 v134, vcc, s0, v130
	v_cvt_pk_bf16_f32 v132, v36, v40
	v_cvt_pk_bf16_f32 v133, v48, v44
	v_addc_co_u32_e32 v135, vcc, 0, v131, vcc
	global_store_dwordx2 v[134:135], v[132:133], off offset:-4096 nt
	v_cvt_pk_bf16_f32 v132, v37, v41
	v_cvt_pk_bf16_f32 v133, v49, v45
	global_store_dwordx2 v[134:135], v[132:133], off nt
	s_mov_b32 s0, 0xa1000
	v_add_co_u32_e32 v134, vcc, s0, v130
	v_cvt_pk_bf16_f32 v132, v18, v22
	v_cvt_pk_bf16_f32 v133, v30, v26
	v_addc_co_u32_e32 v135, vcc, 0, v131, vcc
	global_store_dwordx2 v[134:135], v[132:133], off offset:-4096 nt
	v_cvt_pk_bf16_f32 v132, v19, v23
	v_cvt_pk_bf16_f32 v133, v31, v27
	s_mov_b32 s0, 0xa3000
	global_store_dwordx2 v[134:135], v[132:133], off nt
	v_add_co_u32_e32 v134, vcc, s0, v130
	v_cvt_pk_bf16_f32 v132, v20, v24
	v_cvt_pk_bf16_f32 v133, v32, v28
	v_addc_co_u32_e32 v135, vcc, 0, v131, vcc
	global_store_dwordx2 v[134:135], v[132:133], off offset:-4096 nt
	v_cvt_pk_bf16_f32 v132, v21, v25
	v_cvt_pk_bf16_f32 v133, v33, v29
	s_mov_b32 s0, 0xb1000
	global_store_dwordx2 v[134:135], v[132:133], off nt
	v_add_co_u32_e32 v134, vcc, s0, v130
	v_cvt_pk_bf16_f32 v132, v2, v6
	v_cvt_pk_bf16_f32 v133, v14, v10
	v_addc_co_u32_e32 v135, vcc, 0, v131, vcc
	global_store_dwordx2 v[134:135], v[132:133], off offset:-4096 nt
	v_cvt_pk_bf16_f32 v132, v3, v7
	v_cvt_pk_bf16_f32 v133, v15, v11
	s_mov_b32 s0, 0xb2000
	global_store_dwordx2 v[134:135], v[132:133], off nt
	v_add_co_u32_e32 v134, vcc, s0, v130
	v_cvt_pk_bf16_f32 v132, v4, v8
	s_nop 0
	v_addc_co_u32_e32 v135, vcc, 0, v131, vcc
	v_cvt_pk_bf16_f32 v133, v16, v12
	v_add_co_u32_e32 v130, vcc, 0xb3000, v130
	global_store_dwordx2 v[134:135], v[132:133], off nt
	v_cvt_pk_bf16_f32 v132, v5, v9
	v_cvt_pk_bf16_f32 v133, v17, v13
	v_addc_co_u32_e32 v131, vcc, 0, v131, vcc
	global_store_dwordx2 v[130:131], v[132:133], off nt
	s_mov_b64 s[8:9], 0

; __device__ __forceinline__ void gemm_tile(const Params& P, const GArgs& ga, const TileDesc& td, int wid_s) {
;     ...
;     static_for<32>([&](auto ic) __attribute__((always_inline)) {
;       EPI_IDX;
;       const float rs = rsv[idx];
;       float v0 = rs * acc[ai][0][m][0][j], v1 = rs * acc[ai][0][m][1][j];
;       float v2 = rs * acc[ai][1][m][0][j], v3 = rs * acc[ai][1][m][1][j];
;       if (act) { v0 = gelu_t(v0); v1 = gelu_t(v1); v2 = gelu_t(v2); v3 = gelu_t(v3); }
;       uint2 o; o.x = pack2(v0, v1); o.y = pack2(v2, v3);
;       *reinterpret_cast<uint2*>(bdst + (size_t)rl * SBW) = o;
;       if (fdst) stnt4(fdst + (size_t)rl * SBW, make_float4(v0, v1, v2, v3));
.LBB0_341:
	v_lshlrev_b64 v[170:171], 10, v[166:167]
	s_and_b32 s33, s92, 0x300
	v_or3_b32 v170, v0, s33, v170
	s_cmp_lg_u64 s[0:1], 0
	v_lshl_add_u64 v[172:173], v[170:171], 1, s[6:7]
	v_lshl_add_u64 v[170:171], v[170:171], 2, s[0:1]
	v_cvt_pk_bf16_f32 v174, v162, v163
	v_cvt_pk_bf16_f32 v175, v164, v165
	s_cselect_b64 s[98:99], -1, 0
	s_cmp_eq_u64 s[0:1], 0
	global_store_dwordx2 v[172:173], v[174:175], off nt
	s_cbranch_scc1 .LBB0_343
	global_store_dwordx4 v[170:171], v[162:165], off nt

; __device__ __forceinline__ void gemm_tile(const Params& P, const GArgs& ga, const TileDesc& td, int wid_s) {
;     ...
;       uint2 o; o.x = pack2(v0, v1); o.y = pack2(v2, v3);
;       *reinterpret_cast<uint2*>(bdst + (size_t)rl * SBW) = o;
;       if (fdst) stnt4(fdst + (size_t)rl * SBW, make_float4(v0, v1, v2, v3));
.LBB0_349:
	v_cvt_pk_bf16_f32 v158, v162, v163
	v_cvt_pk_bf16_f32 v159, v164, v165
	global_store_dwordx2 v[172:173], v[158:159], off offset:2048 nt
	v_cndmask_b32_e64 v158, 0, 1, s[98:99]
	v_cmp_ne_u32_e64 s[0:1], 1, v158
	s_andn2_b64 vcc, exec, s[98:99]
	s_cbranch_vccnz .LBB0_351
	v_add_co_u32_e32 v158, vcc, 0x1000, v170
	s_nop 1
	v_addc_co_u32_e32 v159, vcc, 0, v171, vcc
	global_store_dwordx4 v[158:159], v[162:165], off nt

; __device__ __forceinline__ void gemm_tile(const Params& P, const GArgs& ga, const TileDesc& td, int wid_s) {
;     ...
;       uint2 o; o.x = pack2(v0, v1); o.y = pack2(v2, v3);
;       *reinterpret_cast<uint2*>(bdst + (size_t)rl * SBW) = o;
;       if (fdst) stnt4(fdst + (size_t)rl * SBW, make_float4(v0, v1, v2, v3));
.LBB0_357:
	v_add_co_u32_e32 v174, vcc, 0x1000, v172
	v_cvt_pk_bf16_f32 v158, v162, v163
	s_nop 0
	v_addc_co_u32_e32 v175, vcc, 0, v173, vcc
	v_cvt_pk_bf16_f32 v159, v164, v165
	s_and_b64 vcc, exec, s[0:1]
	global_store_dwordx2 v[174:175], v[158:159], off nt
	s_cbranch_vccnz .LBB0_359
	v_add_co_u32_e32 v158, vcc, 0x2000, v170
	s_nop 1
	v_addc_co_u32_e32 v159, vcc, 0, v171, vcc
	global_store_dwordx4 v[158:159], v[162:165], off nt

; __device__ __forceinline__ void gemm_tile(const Params& P, const GArgs& ga, const TileDesc& td, int wid_s) {
;     ...
;       uint2 o; o.x = pack2(v0, v1); o.y = pack2(v2, v3);
;       *reinterpret_cast<uint2*>(bdst + (size_t)rl * SBW) = o;
;       if (fdst) stnt4(fdst + (size_t)rl * SBW, make_float4(v0, v1, v2, v3));
.LBB0_365:
	v_add_co_u32_e32 v164, vcc, 0x1000, v172
	v_cvt_pk_bf16_f32 v162, v158, v159
	s_nop 0
	v_addc_co_u32_e32 v165, vcc, 0, v173, vcc
	v_cvt_pk_bf16_f32 v163, v160, v161
	s_and_b64 vcc, exec, s[0:1]
	global_store_dwordx2 v[164:165], v[162:163], off offset:2048 nt
	s_cbranch_vccnz .LBB0_367
	v_add_co_u32_e32 v162, vcc, 0x3000, v170
	s_nop 1
	v_addc_co_u32_e32 v163, vcc, 0, v171, vcc
	global_store_dwordx4 v[162:163], v[158:161], off nt

; __device__ __forceinline__ void gemm_tile(const Params& P, const GArgs& ga, const TileDesc& td, int wid_s) {
;     ...
;       uint2 o; o.x = pack2(v0, v1); o.y = pack2(v2, v3);
;       *reinterpret_cast<uint2*>(bdst + (size_t)rl * SBW) = o;
;       if (fdst) stnt4(fdst + (size_t)rl * SBW, make_float4(v0, v1, v2, v3));
.LBB0_373:
	v_add_co_u32_e32 v164, vcc, 0x8000, v172
	v_cvt_pk_bf16_f32 v162, v158, v159
	s_nop 0
	v_addc_co_u32_e32 v165, vcc, 0, v173, vcc
	v_cvt_pk_bf16_f32 v163, v160, v161
	s_and_b64 vcc, exec, s[0:1]
	global_store_dwordx2 v[164:165], v[162:163], off nt
	s_cbranch_vccnz .LBB0_375
	v_add_co_u32_e32 v162, vcc, 0x10000, v170
	s_nop 1
	v_addc_co_u32_e32 v163, vcc, 0, v171, vcc
	global_store_dwordx4 v[162:163], v[158:161], off nt

; __device__ __forceinline__ void gemm_tile(const Params& P, const GArgs& ga, const TileDesc& td, int wid_s) {
;     ...
;       uint2 o; o.x = pack2(v0, v1); o.y = pack2(v2, v3);
;       *reinterpret_cast<uint2*>(bdst + (size_t)rl * SBW) = o;
;       if (fdst) stnt4(fdst + (size_t)rl * SBW, make_float4(v0, v1, v2, v3));
.LBB0_381:
	v_add_co_u32_e32 v162, vcc, 0x8000, v172
	v_cvt_pk_bf16_f32 v154, v158, v159
	s_nop 0
	v_addc_co_u32_e32 v163, vcc, 0, v173, vcc
	v_cvt_pk_bf16_f32 v155, v160, v161
	s_and_b64 vcc, exec, s[0:1]
	global_store_dwordx2 v[162:163], v[154:155], off offset:2048 nt
	s_cbranch_vccnz .LBB0_383
	v_add_co_u32_e32 v154, vcc, 0x11000, v170
	s_nop 1
	v_addc_co_u32_e32 v155, vcc, 0, v171, vcc
	global_store_dwordx4 v[154:155], v[158:161], off nt

; __device__ __forceinline__ void gemm_tile(const Params& P, const GArgs& ga, const TileDesc& td, int wid_s) {
;     ...
;       uint2 o; o.x = pack2(v0, v1); o.y = pack2(v2, v3);
;       *reinterpret_cast<uint2*>(bdst + (size_t)rl * SBW) = o;
;       if (fdst) stnt4(fdst + (size_t)rl * SBW, make_float4(v0, v1, v2, v3));
.LBB0_389:
	v_add_co_u32_e32 v162, vcc, 0x9000, v172
	v_cvt_pk_bf16_f32 v154, v158, v159
	s_nop 0
	v_addc_co_u32_e32 v163, vcc, 0, v173, vcc
	v_cvt_pk_bf16_f32 v155, v160, v161
	s_and_b64 vcc, exec, s[0:1]
	global_store_dwordx2 v[162:163], v[154:155], off nt
	s_cbranch_vccnz .LBB0_391
	v_add_co_u32_e32 v154, vcc, 0x12000, v170
	s_nop 1
	v_addc_co_u32_e32 v155, vcc, 0, v171, vcc
	global_store_dwordx4 v[154:155], v[158:161], off nt

; __device__ __forceinline__ void gemm_tile(const Params& P, const GArgs& ga, const TileDesc& td, int wid_s) {
;     ...
;       uint2 o; o.x = pack2(v0, v1); o.y = pack2(v2, v3);
;       *reinterpret_cast<uint2*>(bdst + (size_t)rl * SBW) = o;
;       if (fdst) stnt4(fdst + (size_t)rl * SBW, make_float4(v0, v1, v2, v3));
.LBB0_397:
	v_add_co_u32_e32 v160, vcc, 0x9000, v172
	v_cvt_pk_bf16_f32 v158, v154, v155
	s_nop 0
	v_addc_co_u32_e32 v161, vcc, 0, v173, vcc
	v_cvt_pk_bf16_f32 v159, v156, v157
	s_and_b64 vcc, exec, s[0:1]
	global_store_dwordx2 v[160:161], v[158:159], off offset:2048 nt
	s_cbranch_vccnz .LBB0_399
	v_add_co_u32_e32 v158, vcc, 0x13000, v170
	s_nop 1
	v_addc_co_u32_e32 v159, vcc, 0, v171, vcc
	global_store_dwordx4 v[158:159], v[154:157], off nt

; __device__ __forceinline__ void gemm_tile(const Params& P, const GArgs& ga, const TileDesc& td, int wid_s) {
;     ...
;       uint2 o; o.x = pack2(v0, v1); o.y = pack2(v2, v3);
;       *reinterpret_cast<uint2*>(bdst + (size_t)rl * SBW) = o;
;       if (fdst) stnt4(fdst + (size_t)rl * SBW, make_float4(v0, v1, v2, v3));
.LBB0_405:
	v_add_co_u32_e32 v160, vcc, 0x10000, v172
	v_cvt_pk_bf16_f32 v158, v154, v155
	s_nop 0
	v_addc_co_u32_e32 v161, vcc, 0, v173, vcc
	v_cvt_pk_bf16_f32 v159, v156, v157
	s_and_b64 vcc, exec, s[0:1]
	global_store_dwordx2 v[160:161], v[158:159], off nt
	s_cbranch_vccnz .LBB0_407
	v_add_co_u32_e32 v158, vcc, 0x20000, v170
	s_nop 1
	v_addc_co_u32_e32 v159, vcc, 0, v171, vcc
	global_store_dwordx4 v[158:159], v[154:157], off nt

; __device__ __forceinline__ void gemm_tile(const Params& P, const GArgs& ga, const TileDesc& td, int wid_s) {
;     ...
;       uint2 o; o.x = pack2(v0, v1); o.y = pack2(v2, v3);
;       *reinterpret_cast<uint2*>(bdst + (size_t)rl * SBW) = o;
;       if (fdst) stnt4(fdst + (size_t)rl * SBW, make_float4(v0, v1, v2, v3));
.LBB0_413:
	v_add_co_u32_e32 v158, vcc, 0x10000, v172
	v_cvt_pk_bf16_f32 v150, v154, v155
	s_nop 0
	v_addc_co_u32_e32 v159, vcc, 0, v173, vcc
	v_cvt_pk_bf16_f32 v151, v156, v157
	s_and_b64 vcc, exec, s[0:1]
	global_store_dwordx2 v[158:159], v[150:151], off offset:2048 nt
	s_cbranch_vccnz .LBB0_415
	v_add_co_u32_e32 v150, vcc, 0x21000, v170
	s_nop 1
	v_addc_co_u32_e32 v151, vcc, 0, v171, vcc
	global_store_dwordx4 v[150:151], v[154:157], off nt

; __device__ __forceinline__ void gemm_tile(const Params& P, const GArgs& ga, const TileDesc& td, int wid_s) {
;     ...
;       uint2 o; o.x = pack2(v0, v1); o.y = pack2(v2, v3);
;       *reinterpret_cast<uint2*>(bdst + (size_t)rl * SBW) = o;
;       if (fdst) stnt4(fdst + (size_t)rl * SBW, make_float4(v0, v1, v2, v3));
.LBB0_421:
	v_add_co_u32_e32 v158, vcc, 0x11000, v172
	v_cvt_pk_bf16_f32 v150, v154, v155
	s_nop 0
	v_addc_co_u32_e32 v159, vcc, 0, v173, vcc
	v_cvt_pk_bf16_f32 v151, v156, v157
	s_and_b64 vcc, exec, s[0:1]
	global_store_dwordx2 v[158:159], v[150:151], off nt
	s_cbranch_vccnz .LBB0_423
	v_add_co_u32_e32 v150, vcc, 0x22000, v170
	s_nop 1
	v_addc_co_u32_e32 v151, vcc, 0, v171, vcc
	global_store_dwordx4 v[150:151], v[154:157], off nt

; __device__ __forceinline__ void gemm_tile(const Params& P, const GArgs& ga, const TileDesc& td, int wid_s) {
;     ...
;       uint2 o; o.x = pack2(v0, v1); o.y = pack2(v2, v3);
;       *reinterpret_cast<uint2*>(bdst + (size_t)rl * SBW) = o;
;       if (fdst) stnt4(fdst + (size_t)rl * SBW, make_float4(v0, v1, v2, v3));
.LBB0_429:
	v_add_co_u32_e32 v156, vcc, 0x11000, v172
	v_cvt_pk_bf16_f32 v154, v150, v151
	s_nop 0
	v_addc_co_u32_e32 v157, vcc, 0, v173, vcc
	v_cvt_pk_bf16_f32 v155, v152, v153
	s_and_b64 vcc, exec, s[0:1]
	global_store_dwordx2 v[156:157], v[154:155], off offset:2048 nt
	s_cbranch_vccnz .LBB0_431
	v_add_co_u32_e32 v154, vcc, 0x23000, v170
	s_nop 1
	v_addc_co_u32_e32 v155, vcc, 0, v171, vcc
	global_store_dwordx4 v[154:155], v[150:153], off nt

; __device__ __forceinline__ void gemm_tile(const Params& P, const GArgs& ga, const TileDesc& td, int wid_s) {
;     ...
;       uint2 o; o.x = pack2(v0, v1); o.y = pack2(v2, v3);
;       *reinterpret_cast<uint2*>(bdst + (size_t)rl * SBW) = o;
;       if (fdst) stnt4(fdst + (size_t)rl * SBW, make_float4(v0, v1, v2, v3));
.LBB0_437:
	v_add_co_u32_e32 v156, vcc, 0x18000, v172
	v_cvt_pk_bf16_f32 v154, v150, v151
	s_nop 0
	v_addc_co_u32_e32 v157, vcc, 0, v173, vcc
	v_cvt_pk_bf16_f32 v155, v152, v153
	s_and_b64 vcc, exec, s[0:1]
	global_store_dwordx2 v[156:157], v[154:155], off nt
	s_cbranch_vccnz .LBB0_439
	v_add_co_u32_e32 v154, vcc, 0x30000, v170
	s_nop 1
	v_addc_co_u32_e32 v155, vcc, 0, v171, vcc
	global_store_dwordx4 v[154:155], v[150:153], off nt

; __device__ __forceinline__ void gemm_tile(const Params& P, const GArgs& ga, const TileDesc& td, int wid_s) {
;     ...
;       uint2 o; o.x = pack2(v0, v1); o.y = pack2(v2, v3);
;       *reinterpret_cast<uint2*>(bdst + (size_t)rl * SBW) = o;
;       if (fdst) stnt4(fdst + (size_t)rl * SBW, make_float4(v0, v1, v2, v3));
.LBB0_445:
	v_add_co_u32_e32 v154, vcc, 0x18000, v172
	v_cvt_pk_bf16_f32 v146, v150, v151
	s_nop 0
	v_addc_co_u32_e32 v155, vcc, 0, v173, vcc
	v_cvt_pk_bf16_f32 v147, v152, v153
	s_and_b64 vcc, exec, s[0:1]
	global_store_dwordx2 v[154:155], v[146:147], off offset:2048 nt
	s_cbranch_vccnz .LBB0_447
	v_add_co_u32_e32 v146, vcc, 0x31000, v170
	s_nop 1
	v_addc_co_u32_e32 v147, vcc, 0, v171, vcc
	global_store_dwordx4 v[146:147], v[150:153], off nt

; __device__ __forceinline__ void gemm_tile(const Params& P, const GArgs& ga, const TileDesc& td, int wid_s) {
;     ...
;       uint2 o; o.x = pack2(v0, v1); o.y = pack2(v2, v3);
;       *reinterpret_cast<uint2*>(bdst + (size_t)rl * SBW) = o;
;       if (fdst) stnt4(fdst + (size_t)rl * SBW, make_float4(v0, v1, v2, v3));
.LBB0_453:
	v_add_co_u32_e32 v154, vcc, 0x19000, v172
	v_cvt_pk_bf16_f32 v146, v150, v151
	s_nop 0
	v_addc_co_u32_e32 v155, vcc, 0, v173, vcc
	v_cvt_pk_bf16_f32 v147, v152, v153
	s_and_b64 vcc, exec, s[0:1]
	global_store_dwordx2 v[154:155], v[146:147], off nt
	s_cbranch_vccnz .LBB0_455
	v_add_co_u32_e32 v146, vcc, 0x32000, v170
	s_nop 1
	v_addc_co_u32_e32 v147, vcc, 0, v171, vcc
	global_store_dwordx4 v[146:147], v[150:153], off nt

; __device__ __forceinline__ void gemm_tile(const Params& P, const GArgs& ga, const TileDesc& td, int wid_s) {
;     ...
;       uint2 o; o.x = pack2(v0, v1); o.y = pack2(v2, v3);
;       *reinterpret_cast<uint2*>(bdst + (size_t)rl * SBW) = o;
;       if (fdst) stnt4(fdst + (size_t)rl * SBW, make_float4(v0, v1, v2, v3));
.LBB0_461:
	v_add_co_u32_e32 v152, vcc, 0x19000, v172
	v_cvt_pk_bf16_f32 v150, v146, v147
	s_nop 0
	v_addc_co_u32_e32 v153, vcc, 0, v173, vcc
	v_cvt_pk_bf16_f32 v151, v148, v149
	s_and_b64 vcc, exec, s[0:1]
	global_store_dwordx2 v[152:153], v[150:151], off offset:2048 nt
	s_cbranch_vccnz .LBB0_463
	v_add_co_u32_e32 v150, vcc, 0x33000, v170
	s_nop 1
	v_addc_co_u32_e32 v151, vcc, 0, v171, vcc
	global_store_dwordx4 v[150:151], v[146:149], off nt

; __device__ __forceinline__ void gemm_tile(const Params& P, const GArgs& ga, const TileDesc& td, int wid_s) {
;     ...
;       uint2 o; o.x = pack2(v0, v1); o.y = pack2(v2, v3);
;       *reinterpret_cast<uint2*>(bdst + (size_t)rl * SBW) = o;
;       if (fdst) stnt4(fdst + (size_t)rl * SBW, make_float4(v0, v1, v2, v3));
.LBB0_469:
	v_add_co_u32_e32 v152, vcc, 0x40000, v172
	v_cvt_pk_bf16_f32 v150, v146, v147
	s_nop 0
	v_addc_co_u32_e32 v153, vcc, 0, v173, vcc
	v_cvt_pk_bf16_f32 v151, v148, v149
	s_and_b64 vcc, exec, s[0:1]
	global_store_dwordx2 v[152:153], v[150:151], off nt
	s_cbranch_vccnz .LBB0_471
	v_add_co_u32_e32 v150, vcc, 0x80000, v170
	s_nop 1
	v_addc_co_u32_e32 v151, vcc, 0, v171, vcc
	global_store_dwordx4 v[150:151], v[146:149], off nt

; __device__ __forceinline__ void gemm_tile(const Params& P, const GArgs& ga, const TileDesc& td, int wid_s) {
;     ...
;       uint2 o; o.x = pack2(v0, v1); o.y = pack2(v2, v3);
;       *reinterpret_cast<uint2*>(bdst + (size_t)rl * SBW) = o;
;       if (fdst) stnt4(fdst + (size_t)rl * SBW, make_float4(v0, v1, v2, v3));
.LBB0_477:
	v_add_co_u32_e32 v150, vcc, 0x40000, v172
	v_cvt_pk_bf16_f32 v142, v146, v147
	s_nop 0
	v_addc_co_u32_e32 v151, vcc, 0, v173, vcc
	v_cvt_pk_bf16_f32 v143, v148, v149
	s_and_b64 vcc, exec, s[0:1]
	global_store_dwordx2 v[150:151], v[142:143], off offset:2048 nt
	s_cbranch_vccnz .LBB0_479
	v_add_co_u32_e32 v142, vcc, 0x81000, v170
	s_nop 1
	v_addc_co_u32_e32 v143, vcc, 0, v171, vcc
	global_store_dwordx4 v[142:143], v[146:149], off nt

; __device__ __forceinline__ void gemm_tile(const Params& P, const GArgs& ga, const TileDesc& td, int wid_s) {
;     ...
;       uint2 o; o.x = pack2(v0, v1); o.y = pack2(v2, v3);
;       *reinterpret_cast<uint2*>(bdst + (size_t)rl * SBW) = o;
;       if (fdst) stnt4(fdst + (size_t)rl * SBW, make_float4(v0, v1, v2, v3));
.LBB0_485:
	v_add_co_u32_e32 v150, vcc, 0x41000, v172
	v_cvt_pk_bf16_f32 v142, v146, v147
	s_nop 0
	v_addc_co_u32_e32 v151, vcc, 0, v173, vcc
	v_cvt_pk_bf16_f32 v143, v148, v149
	s_and_b64 vcc, exec, s[0:1]
	global_store_dwordx2 v[150:151], v[142:143], off nt
	s_cbranch_vccnz .LBB0_487
	v_add_co_u32_e32 v142, vcc, 0x82000, v170
	s_nop 1
	v_addc_co_u32_e32 v143, vcc, 0, v171, vcc
	global_store_dwordx4 v[142:143], v[146:149], off nt

; __device__ __forceinline__ void gemm_tile(const Params& P, const GArgs& ga, const TileDesc& td, int wid_s) {
;     ...
;       uint2 o; o.x = pack2(v0, v1); o.y = pack2(v2, v3);
;       *reinterpret_cast<uint2*>(bdst + (size_t)rl * SBW) = o;
;       if (fdst) stnt4(fdst + (size_t)rl * SBW, make_float4(v0, v1, v2, v3));
.LBB0_493:
	v_add_co_u32_e32 v148, vcc, 0x41000, v172
	v_cvt_pk_bf16_f32 v146, v142, v143
	s_nop 0
	v_addc_co_u32_e32 v149, vcc, 0, v173, vcc
	v_cvt_pk_bf16_f32 v147, v144, v145
	s_and_b64 vcc, exec, s[0:1]
	global_store_dwordx2 v[148:149], v[146:147], off offset:2048 nt
	s_cbranch_vccnz .LBB0_495
	v_add_co_u32_e32 v146, vcc, 0x83000, v170
	s_nop 1
	v_addc_co_u32_e32 v147, vcc, 0, v171, vcc
	global_store_dwordx4 v[146:147], v[142:145], off nt

; __device__ __forceinline__ void gemm_tile(const Params& P, const GArgs& ga, const TileDesc& td, int wid_s) {
;     ...
;       uint2 o; o.x = pack2(v0, v1); o.y = pack2(v2, v3);
;       *reinterpret_cast<uint2*>(bdst + (size_t)rl * SBW) = o;
;       if (fdst) stnt4(fdst + (size_t)rl * SBW, make_float4(v0, v1, v2, v3));
.LBB0_501:
	v_add_co_u32_e32 v148, vcc, 0x48000, v172
	v_cvt_pk_bf16_f32 v146, v142, v143
	s_nop 0
	v_addc_co_u32_e32 v149, vcc, 0, v173, vcc
	v_cvt_pk_bf16_f32 v147, v144, v145
	s_and_b64 vcc, exec, s[0:1]
	global_store_dwordx2 v[148:149], v[146:147], off nt
	s_cbranch_vccnz .LBB0_503
	v_add_co_u32_e32 v146, vcc, 0x90000, v170
	s_nop 1
	v_addc_co_u32_e32 v147, vcc, 0, v171, vcc
	global_store_dwordx4 v[146:147], v[142:145], off nt

; __device__ __forceinline__ void gemm_tile(const Params& P, const GArgs& ga, const TileDesc& td, int wid_s) {
;     ...
;       uint2 o; o.x = pack2(v0, v1); o.y = pack2(v2, v3);
;       *reinterpret_cast<uint2*>(bdst + (size_t)rl * SBW) = o;
;       if (fdst) stnt4(fdst + (size_t)rl * SBW, make_float4(v0, v1, v2, v3));
.LBB0_509:
	v_add_co_u32_e32 v146, vcc, 0x48000, v172
	v_cvt_pk_bf16_f32 v138, v142, v143
	s_nop 0
	v_addc_co_u32_e32 v147, vcc, 0, v173, vcc
	v_cvt_pk_bf16_f32 v139, v144, v145
	s_and_b64 vcc, exec, s[0:1]
	global_store_dwordx2 v[146:147], v[138:139], off offset:2048 nt
	s_cbranch_vccnz .LBB0_511
	v_add_co_u32_e32 v138, vcc, 0x91000, v170
	s_nop 1
	v_addc_co_u32_e32 v139, vcc, 0, v171, vcc
	global_store_dwordx4 v[138:139], v[142:145], off nt

; __device__ __forceinline__ void gemm_tile(const Params& P, const GArgs& ga, const TileDesc& td, int wid_s) {
;     ...
;       uint2 o; o.x = pack2(v0, v1); o.y = pack2(v2, v3);
;       *reinterpret_cast<uint2*>(bdst + (size_t)rl * SBW) = o;
;       if (fdst) stnt4(fdst + (size_t)rl * SBW, make_float4(v0, v1, v2, v3));
.LBB0_517:
	v_add_co_u32_e32 v146, vcc, 0x49000, v172
	v_cvt_pk_bf16_f32 v138, v142, v143
	s_nop 0
	v_addc_co_u32_e32 v147, vcc, 0, v173, vcc
	v_cvt_pk_bf16_f32 v139, v144, v145
	s_and_b64 vcc, exec, s[0:1]
	global_store_dwordx2 v[146:147], v[138:139], off nt
	s_cbranch_vccnz .LBB0_519
	v_add_co_u32_e32 v138, vcc, 0x92000, v170
	s_nop 1
	v_addc_co_u32_e32 v139, vcc, 0, v171, vcc
	global_store_dwordx4 v[138:139], v[142:145], off nt

; __device__ __forceinline__ void gemm_tile(const Params& P, const GArgs& ga, const TileDesc& td, int wid_s) {
;     ...
;       uint2 o; o.x = pack2(v0, v1); o.y = pack2(v2, v3);
;       *reinterpret_cast<uint2*>(bdst + (size_t)rl * SBW) = o;
;       if (fdst) stnt4(fdst + (size_t)rl * SBW, make_float4(v0, v1, v2, v3));
.LBB0_525:
	v_add_co_u32_e32 v144, vcc, 0x49000, v172
	v_cvt_pk_bf16_f32 v142, v138, v139
	s_nop 0
	v_addc_co_u32_e32 v145, vcc, 0, v173, vcc
	v_cvt_pk_bf16_f32 v143, v140, v141
	s_and_b64 vcc, exec, s[0:1]
	global_store_dwordx2 v[144:145], v[142:143], off offset:2048 nt
	s_cbranch_vccnz .LBB0_527
	v_add_co_u32_e32 v142, vcc, 0x93000, v170
	s_nop 1
	v_addc_co_u32_e32 v143, vcc, 0, v171, vcc
	global_store_dwordx4 v[142:143], v[138:141], off nt

; __device__ __forceinline__ void gemm_tile(const Params& P, const GArgs& ga, const TileDesc& td, int wid_s) {
;     ...
;       uint2 o; o.x = pack2(v0, v1); o.y = pack2(v2, v3);
;       *reinterpret_cast<uint2*>(bdst + (size_t)rl * SBW) = o;
;       if (fdst) stnt4(fdst + (size_t)rl * SBW, make_float4(v0, v1, v2, v3));
.LBB0_533:
	v_add_co_u32_e32 v144, vcc, 0x50000, v172
	v_cvt_pk_bf16_f32 v142, v138, v139
	s_nop 0
	v_addc_co_u32_e32 v145, vcc, 0, v173, vcc
	v_cvt_pk_bf16_f32 v143, v140, v141
	s_and_b64 vcc, exec, s[0:1]
	global_store_dwordx2 v[144:145], v[142:143], off nt
	s_cbranch_vccnz .LBB0_535
	v_add_co_u32_e32 v142, vcc, 0xa0000, v170
	s_nop 1
	v_addc_co_u32_e32 v143, vcc, 0, v171, vcc
	global_store_dwordx4 v[142:143], v[138:141], off nt

; __device__ __forceinline__ void gemm_tile(const Params& P, const GArgs& ga, const TileDesc& td, int wid_s) {
;     ...
;       uint2 o; o.x = pack2(v0, v1); o.y = pack2(v2, v3);
;       *reinterpret_cast<uint2*>(bdst + (size_t)rl * SBW) = o;
;       if (fdst) stnt4(fdst + (size_t)rl * SBW, make_float4(v0, v1, v2, v3));
.LBB0_541:
	v_add_co_u32_e32 v142, vcc, 0x50000, v172
	v_cvt_pk_bf16_f32 v134, v138, v139
	s_nop 0
	v_addc_co_u32_e32 v143, vcc, 0, v173, vcc
	v_cvt_pk_bf16_f32 v135, v140, v141
	s_and_b64 vcc, exec, s[0:1]
	global_store_dwordx2 v[142:143], v[134:135], off offset:2048 nt
	s_cbranch_vccnz .LBB0_543
	v_add_co_u32_e32 v134, vcc, 0xa1000, v170
	s_nop 1
	v_addc_co_u32_e32 v135, vcc, 0, v171, vcc
	global_store_dwordx4 v[134:135], v[138:141], off nt

; __device__ __forceinline__ void gemm_tile(const Params& P, const GArgs& ga, const TileDesc& td, int wid_s) {
;     ...
;       uint2 o; o.x = pack2(v0, v1); o.y = pack2(v2, v3);
;       *reinterpret_cast<uint2*>(bdst + (size_t)rl * SBW) = o;
;       if (fdst) stnt4(fdst + (size_t)rl * SBW, make_float4(v0, v1, v2, v3));
.LBB0_549:
	v_add_co_u32_e32 v142, vcc, 0x51000, v172
	v_cvt_pk_bf16_f32 v134, v138, v139
	s_nop 0
	v_addc_co_u32_e32 v143, vcc, 0, v173, vcc
	v_cvt_pk_bf16_f32 v135, v140, v141
	s_and_b64 vcc, exec, s[0:1]
	global_store_dwordx2 v[142:143], v[134:135], off nt
	s_cbranch_vccnz .LBB0_551
	v_add_co_u32_e32 v134, vcc, 0xa2000, v170
	s_nop 1
	v_addc_co_u32_e32 v135, vcc, 0, v171, vcc
	global_store_dwordx4 v[134:135], v[138:141], off nt

; __device__ __forceinline__ void gemm_tile(const Params& P, const GArgs& ga, const TileDesc& td, int wid_s) {
;     ...
;       uint2 o; o.x = pack2(v0, v1); o.y = pack2(v2, v3);
;       *reinterpret_cast<uint2*>(bdst + (size_t)rl * SBW) = o;
;       if (fdst) stnt4(fdst + (size_t)rl * SBW, make_float4(v0, v1, v2, v3));
.LBB0_557:
	v_add_co_u32_e32 v140, vcc, 0x51000, v172
	v_cvt_pk_bf16_f32 v138, v134, v135
	s_nop 0
	v_addc_co_u32_e32 v141, vcc, 0, v173, vcc
	v_cvt_pk_bf16_f32 v139, v136, v137
	s_and_b64 vcc, exec, s[0:1]
	global_store_dwordx2 v[140:141], v[138:139], off offset:2048 nt
	s_cbranch_vccnz .LBB0_559
	v_add_co_u32_e32 v138, vcc, 0xa3000, v170
	s_nop 1
	v_addc_co_u32_e32 v139, vcc, 0, v171, vcc
	global_store_dwordx4 v[138:139], v[134:137], off nt

; __device__ __forceinline__ void gemm_tile(const Params& P, const GArgs& ga, const TileDesc& td, int wid_s) {
;     ...
;       uint2 o; o.x = pack2(v0, v1); o.y = pack2(v2, v3);
;       *reinterpret_cast<uint2*>(bdst + (size_t)rl * SBW) = o;
;       if (fdst) stnt4(fdst + (size_t)rl * SBW, make_float4(v0, v1, v2, v3));
.LBB0_565:
	v_add_co_u32_e32 v140, vcc, 0x58000, v172
	v_cvt_pk_bf16_f32 v138, v134, v135
	s_nop 0
	v_addc_co_u32_e32 v141, vcc, 0, v173, vcc
	v_cvt_pk_bf16_f32 v139, v136, v137
	s_and_b64 vcc, exec, s[0:1]
	global_store_dwordx2 v[140:141], v[138:139], off nt
	s_cbranch_vccnz .LBB0_567
	v_add_co_u32_e32 v138, vcc, 0xb0000, v170
	s_nop 1
	v_addc_co_u32_e32 v139, vcc, 0, v171, vcc
	global_store_dwordx4 v[138:139], v[134:137], off nt

; __device__ __forceinline__ void gemm_tile(const Params& P, const GArgs& ga, const TileDesc& td, int wid_s) {
;     ...
;       uint2 o; o.x = pack2(v0, v1); o.y = pack2(v2, v3);
;       *reinterpret_cast<uint2*>(bdst + (size_t)rl * SBW) = o;
;       if (fdst) stnt4(fdst + (size_t)rl * SBW, make_float4(v0, v1, v2, v3));
.LBB0_573:
	v_add_co_u32_e32 v138, vcc, 0x58000, v172
	v_cvt_pk_bf16_f32 v130, v134, v135
	s_nop 0
	v_addc_co_u32_e32 v139, vcc, 0, v173, vcc
	v_cvt_pk_bf16_f32 v131, v136, v137
	s_and_b64 vcc, exec, s[0:1]
	global_store_dwordx2 v[138:139], v[130:131], off offset:2048 nt
	s_cbranch_vccnz .LBB0_575
	v_add_co_u32_e32 v130, vcc, 0xb1000, v170
	s_nop 1
	v_addc_co_u32_e32 v131, vcc, 0, v171, vcc
	global_store_dwordx4 v[130:131], v[134:137], off nt

; __device__ __forceinline__ void gemm_tile(const Params& P, const GArgs& ga, const TileDesc& td, int wid_s) {
;     ...
;       uint2 o; o.x = pack2(v0, v1); o.y = pack2(v2, v3);
;       *reinterpret_cast<uint2*>(bdst + (size_t)rl * SBW) = o;
;       if (fdst) stnt4(fdst + (size_t)rl * SBW, make_float4(v0, v1, v2, v3));
.LBB0_581:
	v_add_co_u32_e32 v138, vcc, 0x59000, v172
	v_cvt_pk_bf16_f32 v130, v134, v135
	s_nop 0
	v_addc_co_u32_e32 v139, vcc, 0, v173, vcc
	v_cvt_pk_bf16_f32 v131, v136, v137
	s_and_b64 vcc, exec, s[0:1]
	global_store_dwordx2 v[138:139], v[130:131], off nt
	s_cbranch_vccnz .LBB0_583
	v_add_co_u32_e32 v130, vcc, 0xb2000, v170
	s_nop 1
	v_addc_co_u32_e32 v131, vcc, 0, v171, vcc
	global_store_dwordx4 v[130:131], v[134:137], off nt

; __device__ __forceinline__ void gemm_tile(const Params& P, const GArgs& ga, const TileDesc& td, int wid_s) {
;     ...
;       uint2 o; o.x = pack2(v0, v1); o.y = pack2(v2, v3);
;       *reinterpret_cast<uint2*>(bdst + (size_t)rl * SBW) = o;
;       if (fdst) stnt4(fdst + (size_t)rl * SBW, make_float4(v0, v1, v2, v3));
.LBB0_589:
	v_add_co_u32_e32 v136, vcc, 0x59000, v172
	v_cvt_pk_bf16_f32 v134, v130, v131
	s_nop 0
	v_addc_co_u32_e32 v137, vcc, 0, v173, vcc
	v_cvt_pk_bf16_f32 v135, v132, v133
	s_and_b64 vcc, exec, s[0:1]
	global_store_dwordx2 v[136:137], v[134:135], off offset:2048 nt
	s_cbranch_vccnz .LBB0_591
	v_add_co_u32_e32 v134, vcc, 0xb3000, v170
	s_nop 1
	v_addc_co_u32_e32 v135, vcc, 0, v171, vcc
	global_store_dwordx4 v[134:135], v[130:133], off nt

; __device__ __forceinline__ void gemm_tile(const Params& P, const GArgs& ga, const TileDesc& td, int wid_s) {
;     ...
;       static_for<8>([&](auto ic2) __attribute__((always_inline)) {
;         constexpr int idx = b0 + decltype(ic2)::v; constexpr int ai = idx >> 4, m = (idx >> 2) & 3, j = idx & 3;
;         constexpr int rl = ai * HALF + m * 16 + j; constexpr int q = decltype(ic2)::v;
;         float4 v;
;         v.x = r[q].x + scale * acc[ai][0][m][0][j]; v.y = r[q].y + scale * acc[ai][0][m][1][j];
;         v.z = r[q].z + scale * acc[ai][1][m][0][j]; v.w = r[q].w + scale * acc[ai][1][m][1][j];
;         uint2 o; o.x = pack2(v.x, v.y); o.y = pack2(v.z, v.w);
;         *reinterpret_cast<uint2*>(hb + (size_t)rl * DM) = o;
;         float s = red16(v.x * v.x + v.y * v.y + v.z * v.z + v.w * v.w);
;         if (efr == 0) unsafeAtomicAdd(sso + rl, s);
;       });
.LBB0_603:
	v_lshl_add_u64 v[164:165], v[166:167], 2, s[70:71]
	v_mov_b32_e32 v172, v114
	v_mov_b32_e32 v173, v118
	s_waitcnt vmcnt(7)
	v_pk_fma_f32 v[134:135], s[20:21], v[172:173], v[134:135]
	v_mov_b32_e32 v172, v126
	v_mov_b32_e32 v173, v122
	v_pk_fma_f32 v[136:137], s[20:21], v[172:173], v[136:137]
	v_cvt_pk_bf16_f32 v172, v134, v135
	v_pk_mul_f32 v[134:135], v[134:135], v[134:135]
	v_cvt_pk_bf16_f32 v173, v136, v137
	v_pk_mul_f32 v[136:137], v[136:137], v[136:137]
	v_add_f32_e32 v134, v135, v134
	v_add_f32_e32 v134, v136, v134
	v_add_f32_e32 v134, v137, v134
	v_cmp_eq_u32_e64 s[0:1], 0, v203
	global_store_dwordx2 v[162:163], v[172:173], off nt
	v_add_f32_dpp v134, v134, v134 quad_perm:[1,0,3,2] row_mask:0xf bank_mask:0xf bound_ctrl:1
	s_nop 1
	v_add_f32_dpp v134, v134, v134 quad_perm:[2,3,0,1] row_mask:0xf bank_mask:0xf bound_ctrl:1
	s_nop 1
	v_add_f32_dpp v134, v134, v134 row_ror:4 row_mask:0xf bank_mask:0xf bound_ctrl:1
	s_nop 1
	v_mov_b32_dpp v135, v134 row_ror:8 row_mask:0xf bank_mask:0xf bound_ctrl:1
	s_and_saveexec_b64 s[6:7], s[0:1]
	s_cbranch_execz .LBB0_605
	v_add_f32_e32 v134, v134, v135
	global_atomic_add_f32 v[164:165], v134, off
.LBB0_605:
	s_or_b64 exec, exec, s[6:7]
	v_mov_b32_e32 v134, v115
	v_mov_b32_e32 v135, v119
	s_waitcnt vmcnt(7)
	v_pk_fma_f32 v[130:131], s[20:21], v[134:135], v[130:131]
	v_mov_b32_e32 v134, v127
	v_mov_b32_e32 v135, v123
	v_pk_fma_f32 v[132:133], s[20:21], v[134:135], v[132:133]
	v_cvt_pk_bf16_f32 v134, v130, v131
	v_pk_mul_f32 v[130:131], v[130:131], v[130:131]
	v_cvt_pk_bf16_f32 v135, v132, v133
	v_pk_mul_f32 v[132:133], v[132:133], v[132:133]
	v_add_f32_e32 v130, v131, v130
	v_add_f32_e32 v130, v132, v130
	v_add_f32_e32 v130, v133, v130
	s_movk_i32 s6, 0x1000
	v_add_co_u32_e32 v136, vcc, s6, v162
	v_add_f32_dpp v130, v130, v130 quad_perm:[1,0,3,2] row_mask:0xf bank_mask:0xf bound_ctrl:1
	s_nop 0
	v_addc_co_u32_e32 v137, vcc, 0, v163, vcc
	v_add_f32_dpp v130, v130, v130 quad_perm:[2,3,0,1] row_mask:0xf bank_mask:0xf bound_ctrl:1
	global_store_dwordx2 v[136:137], v[134:135], off nt
	s_nop 0
	v_add_f32_dpp v130, v130, v130 row_ror:4 row_mask:0xf bank_mask:0xf bound_ctrl:1
	s_nop 1
	v_mov_b32_dpp v131, v130 row_ror:8 row_mask:0xf bank_mask:0xf bound_ctrl:1
	s_and_saveexec_b64 s[6:7], s[0:1]
	s_cbranch_execz .LBB0_607
	v_add_f32_e32 v130, v130, v131
	global_atomic_add_f32 v[164:165], v130, off offset:4
.LBB0_607:
	s_or_b64 exec, exec, s[6:7]
	v_mov_b32_e32 v130, v116
	v_mov_b32_e32 v131, v120
	s_waitcnt vmcnt(7)
	v_pk_fma_f32 v[130:131], s[20:21], v[130:131], v[146:147]
	v_mov_b32_e32 v132, v128
	v_mov_b32_e32 v133, v124
	v_pk_fma_f32 v[132:133], s[20:21], v[132:133], v[148:149]
	v_cvt_pk_bf16_f32 v134, v130, v131
	v_pk_mul_f32 v[130:131], v[130:131], v[130:131]
	v_cvt_pk_bf16_f32 v135, v132, v133
	v_pk_mul_f32 v[132:133], v[132:133], v[132:133]
	v_add_f32_e32 v130, v131, v130
	v_add_f32_e32 v130, v132, v130
	v_add_f32_e32 v130, v133, v130
	v_add_co_u32_e32 v136, vcc, s2, v162
	s_nop 0
	v_add_f32_dpp v130, v130, v130 quad_perm:[1,0,3,2] row_mask:0xf bank_mask:0xf bound_ctrl:1
	v_addc_co_u32_e32 v137, vcc, 0, v163, vcc
	s_nop 0
	v_add_f32_dpp v130, v130, v130 quad_perm:[2,3,0,1] row_mask:0xf bank_mask:0xf bound_ctrl:1
	global_store_dwordx2 v[136:137], v[134:135], off nt
	s_nop 0
	v_add_f32_dpp v130, v130, v130 row_ror:4 row_mask:0xf bank_mask:0xf bound_ctrl:1
	s_nop 1
	v_mov_b32_dpp v131, v130 row_ror:8 row_mask:0xf bank_mask:0xf bound_ctrl:1
	s_and_saveexec_b64 s[6:7], s[0:1]
	s_cbranch_execz .LBB0_609
	v_add_f32_e32 v130, v130, v131
	global_atomic_add_f32 v[164:165], v130, off offset:8
.LBB0_609:
	s_or_b64 exec, exec, s[6:7]
	v_mov_b32_e32 v130, v117
	v_mov_b32_e32 v131, v121
	s_waitcnt vmcnt(7)
	v_pk_fma_f32 v[130:131], s[20:21], v[130:131], v[138:139]
	v_mov_b32_e32 v132, v129
	v_mov_b32_e32 v133, v125
	v_pk_fma_f32 v[132:133], s[20:21], v[132:133], v[140:141]
	v_cvt_pk_bf16_f32 v134, v130, v131
	v_pk_mul_f32 v[130:131], v[130:131], v[130:131]
	v_cvt_pk_bf16_f32 v135, v132, v133
	v_pk_mul_f32 v[132:133], v[132:133], v[132:133]
	v_add_f32_e32 v130, v131, v130
	v_add_f32_e32 v130, v132, v130
	v_add_f32_e32 v130, v133, v130
	v_add_co_u32_e32 v136, vcc, s55, v162
	s_nop 0
	v_add_f32_dpp v130, v130, v130 quad_perm:[1,0,3,2] row_mask:0xf bank_mask:0xf bound_ctrl:1
	v_addc_co_u32_e32 v137, vcc, 0, v163, vcc
	s_nop 0
	v_add_f32_dpp v130, v130, v130 quad_perm:[2,3,0,1] row_mask:0xf bank_mask:0xf bound_ctrl:1
	global_store_dwordx2 v[136:137], v[134:135], off nt
	s_nop 0
	v_add_f32_dpp v130, v130, v130 row_ror:4 row_mask:0xf bank_mask:0xf bound_ctrl:1
	s_nop 1
	v_mov_b32_dpp v131, v130 row_ror:8 row_mask:0xf bank_mask:0xf bound_ctrl:1
	s_and_saveexec_b64 s[6:7], s[0:1]
	s_cbranch_execz .LBB0_611
	v_add_f32_e32 v130, v130, v131
	global_atomic_add_f32 v[164:165], v130, off offset:12
; __device__ __forceinline__ void gemm_tile(const Params& P, const GArgs& ga, const TileDesc& td, int wid_s) {
;     ...
;       static_for<8>([&](auto ic2) __attribute__((always_inline)) {
;         constexpr int idx = b0 + decltype(ic2)::v; constexpr int ai = idx >> 4, m = (idx >> 2) & 3, j = idx & 3;
;         constexpr int rl = ai * HALF + m * 16 + j; constexpr int q = decltype(ic2)::v;
;         float4 v;
;         v.x = r[q].x + scale * acc[ai][0][m][0][j]; v.y = r[q].y + scale * acc[ai][0][m][1][j];
;         v.z = r[q].z + scale * acc[ai][1][m][0][j]; v.w = r[q].w + scale * acc[ai][1][m][1][j];
;         uint2 o; o.x = pack2(v.x, v.y); o.y = pack2(v.z, v.w);
;         *reinterpret_cast<uint2*>(hb + (size_t)rl * DM) = o;
;         float s = red16(v.x * v.x + v.y * v.y + v.z * v.z + v.w * v.w);
;         if (efr == 0) unsafeAtomicAdd(sso + rl, s);
;       });
.LBB0_611:
	s_or_b64 exec, exec, s[6:7]
	v_mov_b32_e32 v130, v98
	v_mov_b32_e32 v131, v102
	s_waitcnt vmcnt(7)
	v_pk_fma_f32 v[130:131], s[20:21], v[130:131], v[154:155]
	v_mov_b32_e32 v132, v110
	v_mov_b32_e32 v133, v106
	v_pk_fma_f32 v[132:133], s[20:21], v[132:133], v[156:157]
	v_cvt_pk_bf16_f32 v134, v130, v131
	v_pk_mul_f32 v[130:131], v[130:131], v[130:131]
	v_cvt_pk_bf16_f32 v135, v132, v133
	v_pk_mul_f32 v[132:133], v[132:133], v[132:133]
	v_add_f32_e32 v130, v131, v130
	v_add_f32_e32 v130, v132, v130
	v_add_f32_e32 v130, v133, v130
	s_mov_b32 s6, 0x10000
	v_add_co_u32_e32 v136, vcc, s6, v162
	v_add_f32_dpp v130, v130, v130 quad_perm:[1,0,3,2] row_mask:0xf bank_mask:0xf bound_ctrl:1
	s_nop 0
	v_addc_co_u32_e32 v137, vcc, 0, v163, vcc
	v_add_f32_dpp v130, v130, v130 quad_perm:[2,3,0,1] row_mask:0xf bank_mask:0xf bound_ctrl:1
	global_store_dwordx2 v[136:137], v[134:135], off nt
	s_nop 0
	v_add_f32_dpp v130, v130, v130 row_ror:4 row_mask:0xf bank_mask:0xf bound_ctrl:1
	s_nop 1
	v_mov_b32_dpp v131, v130 row_ror:8 row_mask:0xf bank_mask:0xf bound_ctrl:1
	s_and_saveexec_b64 s[6:7], s[0:1]
	s_cbranch_execz .LBB0_613
	v_add_f32_e32 v130, v130, v131
	global_atomic_add_f32 v[164:165], v130, off offset:64
.LBB0_613:
	s_or_b64 exec, exec, s[6:7]
	v_mov_b32_e32 v130, v99
	v_mov_b32_e32 v131, v103
	s_waitcnt vmcnt(7)
	v_pk_fma_f32 v[130:131], s[20:21], v[130:131], v[142:143]
	v_mov_b32_e32 v132, v111
	v_mov_b32_e32 v133, v107
	v_pk_fma_f32 v[132:133], s[20:21], v[132:133], v[144:145]
	v_cvt_pk_bf16_f32 v134, v130, v131
	v_pk_mul_f32 v[130:131], v[130:131], v[130:131]
	v_cvt_pk_bf16_f32 v135, v132, v133
	v_pk_mul_f32 v[132:133], v[132:133], v[132:133]
	v_add_f32_e32 v130, v131, v130
	v_add_f32_e32 v130, v132, v130
	v_add_f32_e32 v130, v133, v130
	v_add_co_u32_e32 v136, vcc, s13, v162
	s_nop 0
	v_add_f32_dpp v130, v130, v130 quad_perm:[1,0,3,2] row_mask:0xf bank_mask:0xf bound_ctrl:1
	v_addc_co_u32_e32 v137, vcc, 0, v163, vcc
	s_nop 0
	v_add_f32_dpp v130, v130, v130 quad_perm:[2,3,0,1] row_mask:0xf bank_mask:0xf bound_ctrl:1
	global_store_dwordx2 v[136:137], v[134:135], off nt
	s_nop 0
	v_add_f32_dpp v130, v130, v130 row_ror:4 row_mask:0xf bank_mask:0xf bound_ctrl:1
	s_nop 1
	v_mov_b32_dpp v131, v130 row_ror:8 row_mask:0xf bank_mask:0xf bound_ctrl:1
	s_and_saveexec_b64 s[6:7], s[0:1]
	s_cbranch_execz .LBB0_615
	v_add_f32_e32 v130, v130, v131
	global_atomic_add_f32 v[164:165], v130, off offset:68
.LBB0_615:
	s_or_b64 exec, exec, s[6:7]
	v_mov_b32_e32 v130, v100
	v_mov_b32_e32 v131, v104
	s_waitcnt vmcnt(7)
	v_pk_fma_f32 v[130:131], s[20:21], v[130:131], v[150:151]
	v_mov_b32_e32 v132, v112
	v_mov_b32_e32 v133, v108
	v_pk_fma_f32 v[132:133], s[20:21], v[132:133], v[152:153]
	v_cvt_pk_bf16_f32 v134, v130, v131
	v_pk_mul_f32 v[130:131], v[130:131], v[130:131]
	v_cvt_pk_bf16_f32 v135, v132, v133
	v_pk_mul_f32 v[132:133], v[132:133], v[132:133]
	v_add_f32_e32 v130, v131, v130
	v_add_f32_e32 v130, v132, v130
	v_add_f32_e32 v130, v133, v130
	v_add_co_u32_e32 v136, vcc, s67, v162
	s_nop 0
	v_add_f32_dpp v130, v130, v130 quad_perm:[1,0,3,2] row_mask:0xf bank_mask:0xf bound_ctrl:1
	v_addc_co_u32_e32 v137, vcc, 0, v163, vcc
	s_nop 0
	v_add_f32_dpp v130, v130, v130 quad_perm:[2,3,0,1] row_mask:0xf bank_mask:0xf bound_ctrl:1
	global_store_dwordx2 v[136:137], v[134:135], off nt
	s_nop 0
	v_add_f32_dpp v130, v130, v130 row_ror:4 row_mask:0xf bank_mask:0xf bound_ctrl:1
	s_nop 1
	v_mov_b32_dpp v131, v130 row_ror:8 row_mask:0xf bank_mask:0xf bound_ctrl:1
	s_and_saveexec_b64 s[6:7], s[0:1]
	s_cbranch_execz .LBB0_617
	v_add_f32_e32 v130, v130, v131
	global_atomic_add_f32 v[164:165], v130, off offset:72
.LBB0_617:
	s_or_b64 exec, exec, s[6:7]
	v_mov_b32_e32 v130, v101
	v_mov_b32_e32 v131, v105
	s_waitcnt vmcnt(7)
	v_pk_fma_f32 v[130:131], s[20:21], v[130:131], v[158:159]
	v_mov_b32_e32 v132, v113
	v_mov_b32_e32 v133, v109
	v_pk_fma_f32 v[132:133], s[20:21], v[132:133], v[160:161]
	v_cvt_pk_bf16_f32 v134, v130, v131
	v_pk_mul_f32 v[130:131], v[130:131], v[130:131]
	v_cvt_pk_bf16_f32 v135, v132, v133
	v_pk_mul_f32 v[132:133], v[132:133], v[132:133]
	v_add_f32_e32 v130, v131, v130
	v_add_f32_e32 v130, v132, v130
	v_add_f32_e32 v130, v133, v130
	v_add_co_u32_e32 v136, vcc, s14, v162
	s_nop 0
	v_add_f32_dpp v130, v130, v130 quad_perm:[1,0,3,2] row_mask:0xf bank_mask:0xf bound_ctrl:1
	v_addc_co_u32_e32 v137, vcc, 0, v163, vcc
	s_nop 0
	v_add_f32_dpp v130, v130, v130 quad_perm:[2,3,0,1] row_mask:0xf bank_mask:0xf bound_ctrl:1
	global_store_dwordx2 v[136:137], v[134:135], off nt
	s_nop 0
	v_add_f32_dpp v130, v130, v130 row_ror:4 row_mask:0xf bank_mask:0xf bound_ctrl:1
	s_nop 1
	v_mov_b32_dpp v131, v130 row_ror:8 row_mask:0xf bank_mask:0xf bound_ctrl:1
	s_and_saveexec_b64 s[6:7], s[0:1]
	s_cbranch_execz .LBB0_619
	v_add_f32_e32 v130, v130, v131
	global_atomic_add_f32 v[164:165], v130, off offset:76

; __device__ __forceinline__ void gemm_tile(const Params& P, const GArgs& ga, const TileDesc& td, int wid_s) {
;     ...
;       static_for<8>([&](auto ic2) __attribute__((always_inline)) {
;         constexpr int idx = b0 + decltype(ic2)::v; constexpr int ai = idx >> 4, m = (idx >> 2) & 3, j = idx & 3;
;         constexpr int rl = ai * HALF + m * 16 + j; constexpr int q = decltype(ic2)::v;
;         float4 v;
;         v.x = r[q].x + scale * acc[ai][0][m][0][j]; v.y = r[q].y + scale * acc[ai][0][m][1][j];
;         v.z = r[q].z + scale * acc[ai][1][m][0][j]; v.w = r[q].w + scale * acc[ai][1][m][1][j];
;         uint2 o; o.x = pack2(v.x, v.y); o.y = pack2(v.z, v.w);
;         *reinterpret_cast<uint2*>(hb + (size_t)rl * DM) = o;
;         float s = red16(v.x * v.x + v.y * v.y + v.z * v.z + v.w * v.w);
;         if (efr == 0) unsafeAtomicAdd(sso + rl, s);
;       });
.LBB0_623:
	v_mov_b32_e32 v172, v82
	v_mov_b32_e32 v173, v86
	s_waitcnt vmcnt(7)
	v_pk_fma_f32 v[158:159], s[20:21], v[172:173], v[158:159]
	v_mov_b32_e32 v172, v94
	v_mov_b32_e32 v173, v90
	v_pk_fma_f32 v[160:161], s[20:21], v[172:173], v[160:161]
	v_cvt_pk_bf16_f32 v172, v158, v159
	v_pk_mul_f32 v[158:159], v[158:159], v[158:159]
	v_cvt_pk_bf16_f32 v173, v160, v161
	v_pk_mul_f32 v[160:161], v[160:161], v[160:161]
	v_add_f32_e32 v158, v159, v158
	v_add_f32_e32 v158, v160, v158
	v_add_f32_e32 v158, v161, v158
	v_add_co_u32_e32 v174, vcc, s11, v162
	s_nop 0
	v_add_f32_dpp v158, v158, v158 quad_perm:[1,0,3,2] row_mask:0xf bank_mask:0xf bound_ctrl:1
	v_addc_co_u32_e32 v175, vcc, 0, v163, vcc
	s_nop 0
	v_add_f32_dpp v158, v158, v158 quad_perm:[2,3,0,1] row_mask:0xf bank_mask:0xf bound_ctrl:1
	global_store_dwordx2 v[174:175], v[172:173], off nt
	s_nop 0
	v_add_f32_dpp v158, v158, v158 row_ror:4 row_mask:0xf bank_mask:0xf bound_ctrl:1
	s_nop 1
	v_mov_b32_dpp v159, v158 row_ror:8 row_mask:0xf bank_mask:0xf bound_ctrl:1
	s_and_saveexec_b64 s[6:7], s[0:1]
	s_cbranch_execz .LBB0_625
	v_add_f32_e32 v158, v158, v159
	global_atomic_add_f32 v[164:165], v158, off offset:128
.LBB0_625:
	s_or_b64 exec, exec, s[6:7]
	v_mov_b32_e32 v158, v83
	v_mov_b32_e32 v159, v87
	s_waitcnt vmcnt(7)
	v_pk_fma_f32 v[154:155], s[20:21], v[158:159], v[154:155]
	v_mov_b32_e32 v158, v95
	v_mov_b32_e32 v159, v91
	v_pk_fma_f32 v[156:157], s[20:21], v[158:159], v[156:157]
	v_cvt_pk_bf16_f32 v158, v154, v155
	v_pk_mul_f32 v[154:155], v[154:155], v[154:155]
	v_cvt_pk_bf16_f32 v159, v156, v157
	v_pk_mul_f32 v[156:157], v[156:157], v[156:157]
	v_add_f32_e32 v154, v155, v154
	v_add_f32_e32 v154, v156, v154
	v_add_f32_e32 v154, v157, v154
	s_mov_b32 s6, 0x21000
	v_add_co_u32_e32 v160, vcc, s6, v162
	v_add_f32_dpp v154, v154, v154 quad_perm:[1,0,3,2] row_mask:0xf bank_mask:0xf bound_ctrl:1
	s_nop 0
	v_addc_co_u32_e32 v161, vcc, 0, v163, vcc
	v_add_f32_dpp v154, v154, v154 quad_perm:[2,3,0,1] row_mask:0xf bank_mask:0xf bound_ctrl:1
	global_store_dwordx2 v[160:161], v[158:159], off nt
	s_nop 0
	v_add_f32_dpp v154, v154, v154 row_ror:4 row_mask:0xf bank_mask:0xf bound_ctrl:1
	s_nop 1
	v_mov_b32_dpp v155, v154 row_ror:8 row_mask:0xf bank_mask:0xf bound_ctrl:1
	s_and_saveexec_b64 s[6:7], s[0:1]
	s_cbranch_execz .LBB0_627
	v_add_f32_e32 v154, v154, v155
	global_atomic_add_f32 v[164:165], v154, off offset:132
.LBB0_627:
	s_or_b64 exec, exec, s[6:7]
	v_mov_b32_e32 v154, v84
	v_mov_b32_e32 v155, v88
	s_waitcnt vmcnt(7)
	v_pk_fma_f32 v[150:151], s[20:21], v[154:155], v[150:151]
	v_mov_b32_e32 v154, v96
	v_mov_b32_e32 v155, v92
	v_pk_fma_f32 v[152:153], s[20:21], v[154:155], v[152:153]
	v_cvt_pk_bf16_f32 v154, v150, v151
	v_pk_mul_f32 v[150:151], v[150:151], v[150:151]
	v_cvt_pk_bf16_f32 v155, v152, v153
	v_pk_mul_f32 v[152:153], v[152:153], v[152:153]
	v_add_f32_e32 v150, v151, v150
	v_add_f32_e32 v150, v152, v150
	v_add_f32_e32 v150, v153, v150
	s_mov_b32 s6, 0x22000
	v_add_co_u32_e32 v156, vcc, s6, v162
	v_add_f32_dpp v150, v150, v150 quad_perm:[1,0,3,2] row_mask:0xf bank_mask:0xf bound_ctrl:1
	s_nop 0
	v_addc_co_u32_e32 v157, vcc, 0, v163, vcc
	v_add_f32_dpp v150, v150, v150 quad_perm:[2,3,0,1] row_mask:0xf bank_mask:0xf bound_ctrl:1
	global_store_dwordx2 v[156:157], v[154:155], off nt
	s_nop 0
	v_add_f32_dpp v150, v150, v150 row_ror:4 row_mask:0xf bank_mask:0xf bound_ctrl:1
	s_nop 1
	v_mov_b32_dpp v151, v150 row_ror:8 row_mask:0xf bank_mask:0xf bound_ctrl:1
	s_and_saveexec_b64 s[6:7], s[0:1]
	s_cbranch_execz .LBB0_629
	v_add_f32_e32 v150, v150, v151
	global_atomic_add_f32 v[164:165], v150, off offset:136
.LBB0_629:
	s_or_b64 exec, exec, s[6:7]
	v_mov_b32_e32 v150, v85
	v_mov_b32_e32 v151, v89
	s_waitcnt vmcnt(7)
	v_pk_fma_f32 v[146:147], s[20:21], v[150:151], v[146:147]
	v_mov_b32_e32 v150, v97
	v_mov_b32_e32 v151, v93
	v_pk_fma_f32 v[148:149], s[20:21], v[150:151], v[148:149]
	v_cvt_pk_bf16_f32 v150, v146, v147
	v_pk_mul_f32 v[146:147], v[146:147], v[146:147]
	v_cvt_pk_bf16_f32 v151, v148, v149
	v_pk_mul_f32 v[148:149], v[148:149], v[148:149]
	v_add_f32_e32 v146, v147, v146
	v_add_f32_e32 v146, v148, v146
	v_add_f32_e32 v146, v149, v146
	s_mov_b32 s6, 0x23000
	v_add_co_u32_e32 v152, vcc, s6, v162
	v_add_f32_dpp v146, v146, v146 quad_perm:[1,0,3,2] row_mask:0xf bank_mask:0xf bound_ctrl:1
	s_nop 0
	v_addc_co_u32_e32 v153, vcc, 0, v163, vcc
	v_add_f32_dpp v146, v146, v146 quad_perm:[2,3,0,1] row_mask:0xf bank_mask:0xf bound_ctrl:1
	global_store_dwordx2 v[152:153], v[150:151], off nt
	s_nop 0
	v_add_f32_dpp v146, v146, v146 row_ror:4 row_mask:0xf bank_mask:0xf bound_ctrl:1
	s_nop 1
	v_mov_b32_dpp v147, v146 row_ror:8 row_mask:0xf bank_mask:0xf bound_ctrl:1
	s_and_saveexec_b64 s[6:7], s[0:1]
	s_cbranch_execz .LBB0_631
	v_add_f32_e32 v146, v146, v147
	global_atomic_add_f32 v[164:165], v146, off offset:140
; __device__ __forceinline__ void gemm_tile(const Params& P, const GArgs& ga, const TileDesc& td, int wid_s) {
;     ...
;       static_for<8>([&](auto ic2) __attribute__((always_inline)) {
;         constexpr int idx = b0 + decltype(ic2)::v; constexpr int ai = idx >> 4, m = (idx >> 2) & 3, j = idx & 3;
;         constexpr int rl = ai * HALF + m * 16 + j; constexpr int q = decltype(ic2)::v;
;         float4 v;
;         v.x = r[q].x + scale * acc[ai][0][m][0][j]; v.y = r[q].y + scale * acc[ai][0][m][1][j];
;         v.z = r[q].z + scale * acc[ai][1][m][0][j]; v.w = r[q].w + scale * acc[ai][1][m][1][j];
;         uint2 o; o.x = pack2(v.x, v.y); o.y = pack2(v.z, v.w);
;         *reinterpret_cast<uint2*>(hb + (size_t)rl * DM) = o;
;         float s = red16(v.x * v.x + v.y * v.y + v.z * v.z + v.w * v.w);
;         if (efr == 0) unsafeAtomicAdd(sso + rl, s);
;       });
.LBB0_631:
	s_or_b64 exec, exec, s[6:7]
	v_mov_b32_e32 v146, v66
	v_mov_b32_e32 v147, v70
	s_waitcnt vmcnt(7)
	v_pk_fma_f32 v[142:143], s[20:21], v[146:147], v[142:143]
	v_mov_b32_e32 v146, v78
	v_mov_b32_e32 v147, v74
	v_pk_fma_f32 v[144:145], s[20:21], v[146:147], v[144:145]
	v_cvt_pk_bf16_f32 v146, v142, v143
	v_pk_mul_f32 v[142:143], v[142:143], v[142:143]
	v_cvt_pk_bf16_f32 v147, v144, v145
	v_pk_mul_f32 v[144:145], v[144:145], v[144:145]
	v_add_f32_e32 v142, v143, v142
	v_add_f32_e32 v142, v144, v142
	v_add_f32_e32 v142, v145, v142
	s_mov_b32 s6, 0x30000
	v_add_co_u32_e32 v148, vcc, s6, v162
	v_add_f32_dpp v142, v142, v142 quad_perm:[1,0,3,2] row_mask:0xf bank_mask:0xf bound_ctrl:1
	s_nop 0
	v_addc_co_u32_e32 v149, vcc, 0, v163, vcc
	v_add_f32_dpp v142, v142, v142 quad_perm:[2,3,0,1] row_mask:0xf bank_mask:0xf bound_ctrl:1
	global_store_dwordx2 v[148:149], v[146:147], off nt
	s_nop 0
	v_add_f32_dpp v142, v142, v142 row_ror:4 row_mask:0xf bank_mask:0xf bound_ctrl:1
	s_nop 1
	v_mov_b32_dpp v143, v142 row_ror:8 row_mask:0xf bank_mask:0xf bound_ctrl:1
	s_and_saveexec_b64 s[6:7], s[0:1]
	s_cbranch_execz .LBB0_633
	v_add_f32_e32 v142, v142, v143
	global_atomic_add_f32 v[164:165], v142, off offset:192
.LBB0_633:
	s_or_b64 exec, exec, s[6:7]
	v_mov_b32_e32 v142, v67
	v_mov_b32_e32 v143, v71
	s_waitcnt vmcnt(7)
	v_pk_fma_f32 v[138:139], s[20:21], v[142:143], v[138:139]
	v_mov_b32_e32 v142, v79
	v_mov_b32_e32 v143, v75
	v_pk_fma_f32 v[140:141], s[20:21], v[142:143], v[140:141]
	v_cvt_pk_bf16_f32 v142, v138, v139
	v_pk_mul_f32 v[138:139], v[138:139], v[138:139]
	v_cvt_pk_bf16_f32 v143, v140, v141
	v_pk_mul_f32 v[140:141], v[140:141], v[140:141]
	v_add_f32_e32 v138, v139, v138
	v_add_f32_e32 v138, v140, v138
	v_add_f32_e32 v138, v141, v138
	v_add_co_u32_e32 v144, vcc, s19, v162
	s_nop 0
	v_add_f32_dpp v138, v138, v138 quad_perm:[1,0,3,2] row_mask:0xf bank_mask:0xf bound_ctrl:1
	v_addc_co_u32_e32 v145, vcc, 0, v163, vcc
	s_nop 0
	v_add_f32_dpp v138, v138, v138 quad_perm:[2,3,0,1] row_mask:0xf bank_mask:0xf bound_ctrl:1
	global_store_dwordx2 v[144:145], v[142:143], off nt
	s_nop 0
	v_add_f32_dpp v138, v138, v138 row_ror:4 row_mask:0xf bank_mask:0xf bound_ctrl:1
	s_nop 1
	v_mov_b32_dpp v139, v138 row_ror:8 row_mask:0xf bank_mask:0xf bound_ctrl:1
	s_and_saveexec_b64 s[6:7], s[0:1]
	s_cbranch_execz .LBB0_635
	v_add_f32_e32 v138, v138, v139
	global_atomic_add_f32 v[164:165], v138, off offset:196
.LBB0_635:
	s_or_b64 exec, exec, s[6:7]
	v_mov_b32_e32 v138, v68
	v_mov_b32_e32 v139, v72
	s_waitcnt vmcnt(7)
	v_pk_fma_f32 v[134:135], s[20:21], v[138:139], v[134:135]
	v_mov_b32_e32 v138, v80
	v_mov_b32_e32 v139, v76
	v_pk_fma_f32 v[136:137], s[20:21], v[138:139], v[136:137]
	v_cvt_pk_bf16_f32 v138, v134, v135
	v_pk_mul_f32 v[134:135], v[134:135], v[134:135]
	v_cvt_pk_bf16_f32 v139, v136, v137
	v_pk_mul_f32 v[136:137], v[136:137], v[136:137]
	v_add_f32_e32 v134, v135, v134
	v_add_f32_e32 v134, v136, v134
	v_add_f32_e32 v134, v137, v134
	s_mov_b32 s6, 0x32000
	v_add_co_u32_e32 v140, vcc, s6, v162
	v_add_f32_dpp v134, v134, v134 quad_perm:[1,0,3,2] row_mask:0xf bank_mask:0xf bound_ctrl:1
	s_nop 0
	v_addc_co_u32_e32 v141, vcc, 0, v163, vcc
	v_add_f32_dpp v134, v134, v134 quad_perm:[2,3,0,1] row_mask:0xf bank_mask:0xf bound_ctrl:1
	global_store_dwordx2 v[140:141], v[138:139], off nt
	s_nop 0
	v_add_f32_dpp v134, v134, v134 row_ror:4 row_mask:0xf bank_mask:0xf bound_ctrl:1
	s_nop 1
	v_mov_b32_dpp v135, v134 row_ror:8 row_mask:0xf bank_mask:0xf bound_ctrl:1
	s_and_saveexec_b64 s[6:7], s[0:1]
	s_cbranch_execz .LBB0_637
	v_add_f32_e32 v134, v134, v135
	global_atomic_add_f32 v[164:165], v134, off offset:200
.LBB0_637:
	s_or_b64 exec, exec, s[6:7]
	v_mov_b32_e32 v134, v69
	v_mov_b32_e32 v135, v73
	s_waitcnt vmcnt(7)
	v_pk_fma_f32 v[130:131], s[20:21], v[134:135], v[130:131]
	v_mov_b32_e32 v134, v81
	v_mov_b32_e32 v135, v77
	v_pk_fma_f32 v[132:133], s[20:21], v[134:135], v[132:133]
	v_cvt_pk_bf16_f32 v134, v130, v131
	v_pk_mul_f32 v[130:131], v[130:131], v[130:131]
	v_cvt_pk_bf16_f32 v135, v132, v133
	v_pk_mul_f32 v[132:133], v[132:133], v[132:133]
	v_add_f32_e32 v130, v131, v130
	v_add_f32_e32 v130, v132, v130
	v_add_f32_e32 v130, v133, v130
	s_mov_b32 s6, 0x33000
	v_add_co_u32_e32 v136, vcc, s6, v162
	v_add_f32_dpp v130, v130, v130 quad_perm:[1,0,3,2] row_mask:0xf bank_mask:0xf bound_ctrl:1
	s_nop 0
	v_addc_co_u32_e32 v137, vcc, 0, v163, vcc
	v_add_f32_dpp v130, v130, v130 quad_perm:[2,3,0,1] row_mask:0xf bank_mask:0xf bound_ctrl:1
	global_store_dwordx2 v[136:137], v[134:135], off nt
	s_nop 0
	v_add_f32_dpp v130, v130, v130 row_ror:4 row_mask:0xf bank_mask:0xf bound_ctrl:1
	s_nop 1
	v_mov_b32_dpp v131, v130 row_ror:8 row_mask:0xf bank_mask:0xf bound_ctrl:1
	s_and_saveexec_b64 s[6:7], s[0:1]
	s_cbranch_execz .LBB0_639
	v_add_f32_e32 v130, v130, v131
	global_atomic_add_f32 v[164:165], v130, off offset:204

; __device__ __forceinline__ void gemm_tile(const Params& P, const GArgs& ga, const TileDesc& td, int wid_s) {
;     ...
;       static_for<8>([&](auto ic2) __attribute__((always_inline)) {
;         constexpr int idx = b0 + decltype(ic2)::v; constexpr int ai = idx >> 4, m = (idx >> 2) & 3, j = idx & 3;
;         constexpr int rl = ai * HALF + m * 16 + j; constexpr int q = decltype(ic2)::v;
;         float4 v;
;         v.x = r[q].x + scale * acc[ai][0][m][0][j]; v.y = r[q].y + scale * acc[ai][0][m][1][j];
;         v.z = r[q].z + scale * acc[ai][1][m][0][j]; v.w = r[q].w + scale * acc[ai][1][m][1][j];
;         uint2 o; o.x = pack2(v.x, v.y); o.y = pack2(v.z, v.w);
;         *reinterpret_cast<uint2*>(hb + (size_t)rl * DM) = o;
;         float s = red16(v.x * v.x + v.y * v.y + v.z * v.z + v.w * v.w);
;         if (efr == 0) unsafeAtomicAdd(sso + rl, s);
;       });
.LBB0_643:
	v_mov_b32_e32 v172, v50
	v_mov_b32_e32 v173, v54
	s_waitcnt vmcnt(7)
	v_pk_fma_f32 v[158:159], s[20:21], v[172:173], v[158:159]
	v_mov_b32_e32 v172, v62
	v_mov_b32_e32 v173, v58
	v_pk_fma_f32 v[160:161], s[20:21], v[172:173], v[160:161]
	v_cvt_pk_bf16_f32 v172, v158, v159
	v_pk_mul_f32 v[158:159], v[158:159], v[158:159]
	v_cvt_pk_bf16_f32 v173, v160, v161
	v_pk_mul_f32 v[160:161], v[160:161], v[160:161]
	v_add_f32_e32 v158, v159, v158
	v_add_f32_e32 v158, v160, v158
	v_add_f32_e32 v158, v161, v158
	s_mov_b32 s6, 0x80000
	v_add_co_u32_e32 v174, vcc, s6, v162
	v_add_f32_dpp v158, v158, v158 quad_perm:[1,0,3,2] row_mask:0xf bank_mask:0xf bound_ctrl:1
	s_nop 0
	v_addc_co_u32_e32 v175, vcc, 0, v163, vcc
	v_add_f32_dpp v158, v158, v158 quad_perm:[2,3,0,1] row_mask:0xf bank_mask:0xf bound_ctrl:1
	global_store_dwordx2 v[174:175], v[172:173], off nt
	s_nop 0
	v_add_f32_dpp v158, v158, v158 row_ror:4 row_mask:0xf bank_mask:0xf bound_ctrl:1
	s_nop 1
	v_mov_b32_dpp v159, v158 row_ror:8 row_mask:0xf bank_mask:0xf bound_ctrl:1
	s_and_saveexec_b64 s[6:7], s[0:1]
	s_cbranch_execz .LBB0_645
	v_add_f32_e32 v158, v158, v159
	global_atomic_add_f32 v[164:165], v158, off offset:512
.LBB0_645:
	s_or_b64 exec, exec, s[6:7]
	v_mov_b32_e32 v158, v51
	v_mov_b32_e32 v159, v55
	s_waitcnt vmcnt(7)
	v_pk_fma_f32 v[154:155], s[20:21], v[158:159], v[154:155]
	v_mov_b32_e32 v158, v63
	v_mov_b32_e32 v159, v59
	v_pk_fma_f32 v[156:157], s[20:21], v[158:159], v[156:157]
	v_cvt_pk_bf16_f32 v158, v154, v155
	v_pk_mul_f32 v[154:155], v[154:155], v[154:155]
	v_cvt_pk_bf16_f32 v159, v156, v157
	v_pk_mul_f32 v[156:157], v[156:157], v[156:157]
	v_add_f32_e32 v154, v155, v154
	v_add_f32_e32 v154, v156, v154
	v_add_f32_e32 v154, v157, v154
	s_mov_b32 s6, 0x81000
	v_add_co_u32_e32 v160, vcc, s6, v162
	v_add_f32_dpp v154, v154, v154 quad_perm:[1,0,3,2] row_mask:0xf bank_mask:0xf bound_ctrl:1
	s_nop 0
	v_addc_co_u32_e32 v161, vcc, 0, v163, vcc
	v_add_f32_dpp v154, v154, v154 quad_perm:[2,3,0,1] row_mask:0xf bank_mask:0xf bound_ctrl:1
	global_store_dwordx2 v[160:161], v[158:159], off nt
	s_nop 0
	v_add_f32_dpp v154, v154, v154 row_ror:4 row_mask:0xf bank_mask:0xf bound_ctrl:1
	s_nop 1
	v_mov_b32_dpp v155, v154 row_ror:8 row_mask:0xf bank_mask:0xf bound_ctrl:1
	s_and_saveexec_b64 s[6:7], s[0:1]
	s_cbranch_execz .LBB0_647
	v_add_f32_e32 v154, v154, v155
	global_atomic_add_f32 v[164:165], v154, off offset:516
.LBB0_647:
	s_or_b64 exec, exec, s[6:7]
	v_mov_b32_e32 v154, v52
	v_mov_b32_e32 v155, v56
	s_waitcnt vmcnt(7)
	v_pk_fma_f32 v[150:151], s[20:21], v[154:155], v[150:151]
	v_mov_b32_e32 v154, v64
	v_mov_b32_e32 v155, v60
	v_pk_fma_f32 v[152:153], s[20:21], v[154:155], v[152:153]
	v_cvt_pk_bf16_f32 v154, v150, v151
	v_pk_mul_f32 v[150:151], v[150:151], v[150:151]
	v_cvt_pk_bf16_f32 v155, v152, v153
	v_pk_mul_f32 v[152:153], v[152:153], v[152:153]
	v_add_f32_e32 v150, v151, v150
	v_add_f32_e32 v150, v152, v150
	v_add_f32_e32 v150, v153, v150
	s_mov_b32 s6, 0x82000
	v_add_co_u32_e32 v156, vcc, s6, v162
	v_add_f32_dpp v150, v150, v150 quad_perm:[1,0,3,2] row_mask:0xf bank_mask:0xf bound_ctrl:1
	s_nop 0
	v_addc_co_u32_e32 v157, vcc, 0, v163, vcc
	v_add_f32_dpp v150, v150, v150 quad_perm:[2,3,0,1] row_mask:0xf bank_mask:0xf bound_ctrl:1
	global_store_dwordx2 v[156:157], v[154:155], off nt
	s_nop 0
	v_add_f32_dpp v150, v150, v150 row_ror:4 row_mask:0xf bank_mask:0xf bound_ctrl:1
	s_nop 1
	v_mov_b32_dpp v151, v150 row_ror:8 row_mask:0xf bank_mask:0xf bound_ctrl:1
	s_and_saveexec_b64 s[6:7], s[0:1]
	s_cbranch_execz .LBB0_649
	v_add_f32_e32 v150, v150, v151
	global_atomic_add_f32 v[164:165], v150, off offset:520
.LBB0_649:
	s_or_b64 exec, exec, s[6:7]
	v_mov_b32_e32 v150, v53
	v_mov_b32_e32 v151, v57
	s_waitcnt vmcnt(7)
	v_pk_fma_f32 v[146:147], s[20:21], v[150:151], v[146:147]
	v_mov_b32_e32 v150, v65
	v_mov_b32_e32 v151, v61
	v_pk_fma_f32 v[148:149], s[20:21], v[150:151], v[148:149]
	v_cvt_pk_bf16_f32 v150, v146, v147
	v_pk_mul_f32 v[146:147], v[146:147], v[146:147]
	v_cvt_pk_bf16_f32 v151, v148, v149
	v_pk_mul_f32 v[148:149], v[148:149], v[148:149]
	v_add_f32_e32 v146, v147, v146
	v_add_f32_e32 v146, v148, v146
	v_add_f32_e32 v146, v149, v146
	s_mov_b32 s6, 0x83000
	v_add_co_u32_e32 v152, vcc, s6, v162
	v_add_f32_dpp v146, v146, v146 quad_perm:[1,0,3,2] row_mask:0xf bank_mask:0xf bound_ctrl:1
	s_nop 0
	v_addc_co_u32_e32 v153, vcc, 0, v163, vcc
	v_add_f32_dpp v146, v146, v146 quad_perm:[2,3,0,1] row_mask:0xf bank_mask:0xf bound_ctrl:1
	global_store_dwordx2 v[152:153], v[150:151], off nt
	s_nop 0
	v_add_f32_dpp v146, v146, v146 row_ror:4 row_mask:0xf bank_mask:0xf bound_ctrl:1
	s_nop 1
	v_mov_b32_dpp v147, v146 row_ror:8 row_mask:0xf bank_mask:0xf bound_ctrl:1
	s_and_saveexec_b64 s[6:7], s[0:1]
	s_cbranch_execz .LBB0_651
	v_add_f32_e32 v146, v146, v147
	global_atomic_add_f32 v[164:165], v146, off offset:524
; __device__ __forceinline__ void gemm_tile(const Params& P, const GArgs& ga, const TileDesc& td, int wid_s) {
;     ...
;       static_for<8>([&](auto ic2) __attribute__((always_inline)) {
;         constexpr int idx = b0 + decltype(ic2)::v; constexpr int ai = idx >> 4, m = (idx >> 2) & 3, j = idx & 3;
;         constexpr int rl = ai * HALF + m * 16 + j; constexpr int q = decltype(ic2)::v;
;         float4 v;
;         v.x = r[q].x + scale * acc[ai][0][m][0][j]; v.y = r[q].y + scale * acc[ai][0][m][1][j];
;         v.z = r[q].z + scale * acc[ai][1][m][0][j]; v.w = r[q].w + scale * acc[ai][1][m][1][j];
;         uint2 o; o.x = pack2(v.x, v.y); o.y = pack2(v.z, v.w);
;         *reinterpret_cast<uint2*>(hb + (size_t)rl * DM) = o;
;         float s = red16(v.x * v.x + v.y * v.y + v.z * v.z + v.w * v.w);
;         if (efr == 0) unsafeAtomicAdd(sso + rl, s);
;       });
.LBB0_651:
	s_or_b64 exec, exec, s[6:7]
	v_mov_b32_e32 v146, v34
	v_mov_b32_e32 v147, v38
	s_waitcnt vmcnt(7)
	v_pk_fma_f32 v[142:143], s[20:21], v[146:147], v[142:143]
	v_mov_b32_e32 v146, v46
	v_mov_b32_e32 v147, v42
	v_pk_fma_f32 v[144:145], s[20:21], v[146:147], v[144:145]
	v_cvt_pk_bf16_f32 v146, v142, v143
	v_pk_mul_f32 v[142:143], v[142:143], v[142:143]
	v_cvt_pk_bf16_f32 v147, v144, v145
	v_pk_mul_f32 v[144:145], v[144:145], v[144:145]
	v_add_f32_e32 v142, v143, v142
	v_add_f32_e32 v142, v144, v142
	v_add_f32_e32 v142, v145, v142
	s_mov_b32 s6, 0x90000
	v_add_co_u32_e32 v148, vcc, s6, v162
	v_add_f32_dpp v142, v142, v142 quad_perm:[1,0,3,2] row_mask:0xf bank_mask:0xf bound_ctrl:1
	s_nop 0
	v_addc_co_u32_e32 v149, vcc, 0, v163, vcc
	v_add_f32_dpp v142, v142, v142 quad_perm:[2,3,0,1] row_mask:0xf bank_mask:0xf bound_ctrl:1
	global_store_dwordx2 v[148:149], v[146:147], off nt
	s_nop 0
	v_add_f32_dpp v142, v142, v142 row_ror:4 row_mask:0xf bank_mask:0xf bound_ctrl:1
	s_nop 1
	v_mov_b32_dpp v143, v142 row_ror:8 row_mask:0xf bank_mask:0xf bound_ctrl:1
	s_and_saveexec_b64 s[6:7], s[0:1]
	s_cbranch_execz .LBB0_653
	v_add_f32_e32 v142, v142, v143
	global_atomic_add_f32 v[164:165], v142, off offset:576
.LBB0_653:
	s_or_b64 exec, exec, s[6:7]
	v_mov_b32_e32 v142, v35
	v_mov_b32_e32 v143, v39
	s_waitcnt vmcnt(7)
	v_pk_fma_f32 v[138:139], s[20:21], v[142:143], v[138:139]
	v_mov_b32_e32 v142, v47
	v_mov_b32_e32 v143, v43
	v_pk_fma_f32 v[140:141], s[20:21], v[142:143], v[140:141]
	v_cvt_pk_bf16_f32 v142, v138, v139
	v_pk_mul_f32 v[138:139], v[138:139], v[138:139]
	v_cvt_pk_bf16_f32 v143, v140, v141
	v_pk_mul_f32 v[140:141], v[140:141], v[140:141]
	v_add_f32_e32 v138, v139, v138
	v_add_f32_e32 v138, v140, v138
	v_add_f32_e32 v138, v141, v138
	s_mov_b32 s6, 0x91000
	v_add_co_u32_e32 v144, vcc, s6, v162
	v_add_f32_dpp v138, v138, v138 quad_perm:[1,0,3,2] row_mask:0xf bank_mask:0xf bound_ctrl:1
	s_nop 0
	v_addc_co_u32_e32 v145, vcc, 0, v163, vcc
	v_add_f32_dpp v138, v138, v138 quad_perm:[2,3,0,1] row_mask:0xf bank_mask:0xf bound_ctrl:1
	global_store_dwordx2 v[144:145], v[142:143], off nt
	s_nop 0
	v_add_f32_dpp v138, v138, v138 row_ror:4 row_mask:0xf bank_mask:0xf bound_ctrl:1
	s_nop 1
	v_mov_b32_dpp v139, v138 row_ror:8 row_mask:0xf bank_mask:0xf bound_ctrl:1
	s_and_saveexec_b64 s[6:7], s[0:1]
	s_cbranch_execz .LBB0_655
	v_add_f32_e32 v138, v138, v139
	global_atomic_add_f32 v[164:165], v138, off offset:580
.LBB0_655:
	s_or_b64 exec, exec, s[6:7]
	v_mov_b32_e32 v138, v36
	v_mov_b32_e32 v139, v40
	s_waitcnt vmcnt(7)
	v_pk_fma_f32 v[134:135], s[20:21], v[138:139], v[134:135]
	v_mov_b32_e32 v138, v48
	v_mov_b32_e32 v139, v44
	v_pk_fma_f32 v[136:137], s[20:21], v[138:139], v[136:137]
	v_cvt_pk_bf16_f32 v138, v134, v135
	v_pk_mul_f32 v[134:135], v[134:135], v[134:135]
	v_cvt_pk_bf16_f32 v139, v136, v137
	v_pk_mul_f32 v[136:137], v[136:137], v[136:137]
	v_add_f32_e32 v134, v135, v134
	v_add_f32_e32 v134, v136, v134
	v_add_f32_e32 v134, v137, v134
	s_mov_b32 s6, 0x92000
	v_add_co_u32_e32 v140, vcc, s6, v162
	v_add_f32_dpp v134, v134, v134 quad_perm:[1,0,3,2] row_mask:0xf bank_mask:0xf bound_ctrl:1
	s_nop 0
	v_addc_co_u32_e32 v141, vcc, 0, v163, vcc
	v_add_f32_dpp v134, v134, v134 quad_perm:[2,3,0,1] row_mask:0xf bank_mask:0xf bound_ctrl:1
	global_store_dwordx2 v[140:141], v[138:139], off nt
	s_nop 0
	v_add_f32_dpp v134, v134, v134 row_ror:4 row_mask:0xf bank_mask:0xf bound_ctrl:1
	s_nop 1
	v_mov_b32_dpp v135, v134 row_ror:8 row_mask:0xf bank_mask:0xf bound_ctrl:1
	s_and_saveexec_b64 s[6:7], s[0:1]
	s_cbranch_execz .LBB0_657
	v_add_f32_e32 v134, v134, v135
	global_atomic_add_f32 v[164:165], v134, off offset:584
.LBB0_657:
	s_or_b64 exec, exec, s[6:7]
	v_mov_b32_e32 v134, v37
	v_mov_b32_e32 v135, v41
	s_waitcnt vmcnt(7)
	v_pk_fma_f32 v[130:131], s[20:21], v[134:135], v[130:131]
	v_mov_b32_e32 v134, v49
	v_mov_b32_e32 v135, v45
	v_pk_fma_f32 v[132:133], s[20:21], v[134:135], v[132:133]
	v_cvt_pk_bf16_f32 v134, v130, v131
	v_pk_mul_f32 v[130:131], v[130:131], v[130:131]
	v_cvt_pk_bf16_f32 v135, v132, v133
	v_pk_mul_f32 v[132:133], v[132:133], v[132:133]
	v_add_f32_e32 v130, v131, v130
	v_add_f32_e32 v130, v132, v130
	v_add_f32_e32 v130, v133, v130
	s_mov_b32 s6, 0x93000
	v_add_co_u32_e32 v136, vcc, s6, v162
	v_add_f32_dpp v130, v130, v130 quad_perm:[1,0,3,2] row_mask:0xf bank_mask:0xf bound_ctrl:1
	s_nop 0
	v_addc_co_u32_e32 v137, vcc, 0, v163, vcc
	v_add_f32_dpp v130, v130, v130 quad_perm:[2,3,0,1] row_mask:0xf bank_mask:0xf bound_ctrl:1
	global_store_dwordx2 v[136:137], v[134:135], off nt
	s_nop 0
	v_add_f32_dpp v130, v130, v130 row_ror:4 row_mask:0xf bank_mask:0xf bound_ctrl:1
	s_nop 1
	v_mov_b32_dpp v131, v130 row_ror:8 row_mask:0xf bank_mask:0xf bound_ctrl:1
	s_and_saveexec_b64 s[6:7], s[0:1]
	s_cbranch_execz .LBB0_659
	v_add_f32_e32 v130, v130, v131
	global_atomic_add_f32 v[164:165], v130, off offset:588

; __device__ __forceinline__ void gemm_tile(const Params& P, const GArgs& ga, const TileDesc& td, int wid_s) {
;     ...
;       static_for<8>([&](auto ic2) __attribute__((always_inline)) {
;         constexpr int idx = b0 + decltype(ic2)::v; constexpr int ai = idx >> 4, m = (idx >> 2) & 3, j = idx & 3;
;         constexpr int rl = ai * HALF + m * 16 + j; constexpr int q = decltype(ic2)::v;
;         float4 v;
;         v.x = r[q].x + scale * acc[ai][0][m][0][j]; v.y = r[q].y + scale * acc[ai][0][m][1][j];
;         v.z = r[q].z + scale * acc[ai][1][m][0][j]; v.w = r[q].w + scale * acc[ai][1][m][1][j];
;         uint2 o; o.x = pack2(v.x, v.y); o.y = pack2(v.z, v.w);
;         *reinterpret_cast<uint2*>(hb + (size_t)rl * DM) = o;
;         float s = red16(v.x * v.x + v.y * v.y + v.z * v.z + v.w * v.w);
;         if (efr == 0) unsafeAtomicAdd(sso + rl, s);
;       });
.LBB0_663:
	v_mov_b32_e32 v170, v18
	v_mov_b32_e32 v171, v22
	s_waitcnt vmcnt(7)
	v_pk_fma_f32 v[158:159], s[20:21], v[170:171], v[158:159]
	v_mov_b32_e32 v170, v30
	v_mov_b32_e32 v171, v26
	v_pk_fma_f32 v[160:161], s[20:21], v[170:171], v[160:161]
	v_cvt_pk_bf16_f32 v170, v158, v159
	v_pk_mul_f32 v[158:159], v[158:159], v[158:159]
	v_cvt_pk_bf16_f32 v171, v160, v161
	v_pk_mul_f32 v[160:161], v[160:161], v[160:161]
	v_add_f32_e32 v158, v159, v158
	v_add_f32_e32 v158, v160, v158
	v_add_f32_e32 v158, v161, v158
	s_mov_b32 s4, 0xa0000
	v_add_co_u32_e32 v172, vcc, s4, v162
	v_add_f32_dpp v158, v158, v158 quad_perm:[1,0,3,2] row_mask:0xf bank_mask:0xf bound_ctrl:1
	s_nop 0
	v_addc_co_u32_e32 v173, vcc, 0, v163, vcc
	v_add_f32_dpp v158, v158, v158 quad_perm:[2,3,0,1] row_mask:0xf bank_mask:0xf bound_ctrl:1
	global_store_dwordx2 v[172:173], v[170:171], off nt
	s_nop 0
	v_add_f32_dpp v158, v158, v158 row_ror:4 row_mask:0xf bank_mask:0xf bound_ctrl:1
	s_nop 1
	v_mov_b32_dpp v159, v158 row_ror:8 row_mask:0xf bank_mask:0xf bound_ctrl:1
	s_and_saveexec_b64 s[4:5], s[0:1]
	s_cbranch_execz .LBB0_665
	v_add_f32_e32 v158, v158, v159
	global_atomic_add_f32 v[164:165], v158, off offset:640
.LBB0_665:
	s_or_b64 exec, exec, s[4:5]
	v_mov_b32_e32 v158, v19
	v_mov_b32_e32 v159, v23
	s_waitcnt vmcnt(7)
	v_pk_fma_f32 v[154:155], s[20:21], v[158:159], v[154:155]
	v_mov_b32_e32 v158, v31
	v_mov_b32_e32 v159, v27
	v_pk_fma_f32 v[156:157], s[20:21], v[158:159], v[156:157]
	v_cvt_pk_bf16_f32 v158, v154, v155
	v_pk_mul_f32 v[154:155], v[154:155], v[154:155]
	v_cvt_pk_bf16_f32 v159, v156, v157
	v_pk_mul_f32 v[156:157], v[156:157], v[156:157]
	v_add_f32_e32 v154, v155, v154
	v_add_f32_e32 v154, v156, v154
	v_add_f32_e32 v154, v157, v154
	s_mov_b32 s4, 0xa1000
	v_add_co_u32_e32 v160, vcc, s4, v162
	v_add_f32_dpp v154, v154, v154 quad_perm:[1,0,3,2] row_mask:0xf bank_mask:0xf bound_ctrl:1
	s_nop 0
	v_addc_co_u32_e32 v161, vcc, 0, v163, vcc
	v_add_f32_dpp v154, v154, v154 quad_perm:[2,3,0,1] row_mask:0xf bank_mask:0xf bound_ctrl:1
	global_store_dwordx2 v[160:161], v[158:159], off nt
	s_nop 0
	v_add_f32_dpp v154, v154, v154 row_ror:4 row_mask:0xf bank_mask:0xf bound_ctrl:1
	s_nop 1
	v_mov_b32_dpp v155, v154 row_ror:8 row_mask:0xf bank_mask:0xf bound_ctrl:1
	s_and_saveexec_b64 s[4:5], s[0:1]
	s_cbranch_execz .LBB0_667
	v_add_f32_e32 v154, v154, v155
	global_atomic_add_f32 v[164:165], v154, off offset:644
.LBB0_667:
	s_or_b64 exec, exec, s[4:5]
	v_mov_b32_e32 v154, v20
	v_mov_b32_e32 v155, v24
	s_waitcnt vmcnt(7)
	v_pk_fma_f32 v[150:151], s[20:21], v[154:155], v[150:151]
	v_mov_b32_e32 v154, v32
	v_mov_b32_e32 v155, v28
	v_pk_fma_f32 v[152:153], s[20:21], v[154:155], v[152:153]
	v_cvt_pk_bf16_f32 v154, v150, v151
	v_pk_mul_f32 v[150:151], v[150:151], v[150:151]
	v_cvt_pk_bf16_f32 v155, v152, v153
	v_pk_mul_f32 v[152:153], v[152:153], v[152:153]
	v_add_f32_e32 v150, v151, v150
	v_add_f32_e32 v150, v152, v150
	v_add_f32_e32 v150, v153, v150
	s_mov_b32 s4, 0xa2000
	v_add_co_u32_e32 v156, vcc, s4, v162
	v_add_f32_dpp v150, v150, v150 quad_perm:[1,0,3,2] row_mask:0xf bank_mask:0xf bound_ctrl:1
	s_nop 0
	v_addc_co_u32_e32 v157, vcc, 0, v163, vcc
	v_add_f32_dpp v150, v150, v150 quad_perm:[2,3,0,1] row_mask:0xf bank_mask:0xf bound_ctrl:1
	global_store_dwordx2 v[156:157], v[154:155], off nt
	s_nop 0
	v_add_f32_dpp v150, v150, v150 row_ror:4 row_mask:0xf bank_mask:0xf bound_ctrl:1
	s_nop 1
	v_mov_b32_dpp v151, v150 row_ror:8 row_mask:0xf bank_mask:0xf bound_ctrl:1
	s_and_saveexec_b64 s[4:5], s[0:1]
	s_cbranch_execz .LBB0_669
	v_add_f32_e32 v150, v150, v151
	global_atomic_add_f32 v[164:165], v150, off offset:648
.LBB0_669:
	s_or_b64 exec, exec, s[4:5]
	v_mov_b32_e32 v150, v21
	v_mov_b32_e32 v151, v25
	s_waitcnt vmcnt(7)
	v_pk_fma_f32 v[146:147], s[20:21], v[150:151], v[146:147]
	v_mov_b32_e32 v150, v33
	v_mov_b32_e32 v151, v29
	v_pk_fma_f32 v[148:149], s[20:21], v[150:151], v[148:149]
	v_cvt_pk_bf16_f32 v150, v146, v147
	v_pk_mul_f32 v[146:147], v[146:147], v[146:147]
	v_cvt_pk_bf16_f32 v151, v148, v149
	v_pk_mul_f32 v[148:149], v[148:149], v[148:149]
	v_add_f32_e32 v146, v147, v146
	v_add_f32_e32 v146, v148, v146
	v_add_f32_e32 v146, v149, v146
	s_mov_b32 s4, 0xa3000
	v_add_co_u32_e32 v152, vcc, s4, v162
	v_add_f32_dpp v146, v146, v146 quad_perm:[1,0,3,2] row_mask:0xf bank_mask:0xf bound_ctrl:1
	s_nop 0
	v_addc_co_u32_e32 v153, vcc, 0, v163, vcc
	v_add_f32_dpp v146, v146, v146 quad_perm:[2,3,0,1] row_mask:0xf bank_mask:0xf bound_ctrl:1
	global_store_dwordx2 v[152:153], v[150:151], off nt
	s_nop 0
	v_add_f32_dpp v146, v146, v146 row_ror:4 row_mask:0xf bank_mask:0xf bound_ctrl:1
	s_nop 1
	v_mov_b32_dpp v147, v146 row_ror:8 row_mask:0xf bank_mask:0xf bound_ctrl:1
	s_and_saveexec_b64 s[4:5], s[0:1]
	s_cbranch_execz .LBB0_671
	v_add_f32_e32 v146, v146, v147
	global_atomic_add_f32 v[164:165], v146, off offset:652
; __device__ __forceinline__ void gemm_tile(const Params& P, const GArgs& ga, const TileDesc& td, int wid_s) {
;     ...
;       static_for<8>([&](auto ic2) __attribute__((always_inline)) {
;         constexpr int idx = b0 + decltype(ic2)::v; constexpr int ai = idx >> 4, m = (idx >> 2) & 3, j = idx & 3;
;         constexpr int rl = ai * HALF + m * 16 + j; constexpr int q = decltype(ic2)::v;
;         float4 v;
;         v.x = r[q].x + scale * acc[ai][0][m][0][j]; v.y = r[q].y + scale * acc[ai][0][m][1][j];
;         v.z = r[q].z + scale * acc[ai][1][m][0][j]; v.w = r[q].w + scale * acc[ai][1][m][1][j];
;         uint2 o; o.x = pack2(v.x, v.y); o.y = pack2(v.z, v.w);
;         *reinterpret_cast<uint2*>(hb + (size_t)rl * DM) = o;
;         float s = red16(v.x * v.x + v.y * v.y + v.z * v.z + v.w * v.w);
;         if (efr == 0) unsafeAtomicAdd(sso + rl, s);
;       });
.LBB0_671:
	s_or_b64 exec, exec, s[4:5]
	v_mov_b32_e32 v146, v2
	v_mov_b32_e32 v147, v6
	s_waitcnt vmcnt(7)
	v_pk_fma_f32 v[142:143], s[20:21], v[146:147], v[142:143]
	v_mov_b32_e32 v146, v14
	v_mov_b32_e32 v147, v10
	v_pk_fma_f32 v[144:145], s[20:21], v[146:147], v[144:145]
	v_cvt_pk_bf16_f32 v146, v142, v143
	v_pk_mul_f32 v[142:143], v[142:143], v[142:143]
	v_cvt_pk_bf16_f32 v147, v144, v145
	v_pk_mul_f32 v[144:145], v[144:145], v[144:145]
	v_add_f32_e32 v142, v143, v142
	v_add_f32_e32 v142, v144, v142
	v_add_f32_e32 v142, v145, v142
	s_mov_b32 s4, 0xb0000
	v_add_co_u32_e32 v148, vcc, s4, v162
	v_add_f32_dpp v142, v142, v142 quad_perm:[1,0,3,2] row_mask:0xf bank_mask:0xf bound_ctrl:1
	s_nop 0
	v_addc_co_u32_e32 v149, vcc, 0, v163, vcc
	v_add_f32_dpp v142, v142, v142 quad_perm:[2,3,0,1] row_mask:0xf bank_mask:0xf bound_ctrl:1
	global_store_dwordx2 v[148:149], v[146:147], off nt
	s_nop 0
	v_add_f32_dpp v142, v142, v142 row_ror:4 row_mask:0xf bank_mask:0xf bound_ctrl:1
	s_nop 1
	v_mov_b32_dpp v143, v142 row_ror:8 row_mask:0xf bank_mask:0xf bound_ctrl:1
	s_and_saveexec_b64 s[4:5], s[0:1]
	s_cbranch_execz .LBB0_673
	v_add_f32_e32 v142, v142, v143
	global_atomic_add_f32 v[164:165], v142, off offset:704
.LBB0_673:
	s_or_b64 exec, exec, s[4:5]
	v_mov_b32_e32 v142, v3
	v_mov_b32_e32 v143, v7
	s_waitcnt vmcnt(7)
	v_pk_fma_f32 v[138:139], s[20:21], v[142:143], v[138:139]
	v_mov_b32_e32 v142, v15
	v_mov_b32_e32 v143, v11
	v_pk_fma_f32 v[140:141], s[20:21], v[142:143], v[140:141]
	v_cvt_pk_bf16_f32 v142, v138, v139
	v_pk_mul_f32 v[138:139], v[138:139], v[138:139]
	v_cvt_pk_bf16_f32 v143, v140, v141
	v_pk_mul_f32 v[140:141], v[140:141], v[140:141]
	v_add_f32_e32 v138, v139, v138
	v_add_f32_e32 v138, v140, v138
	v_add_f32_e32 v138, v141, v138
	s_mov_b32 s4, 0xb1000
	v_add_co_u32_e32 v144, vcc, s4, v162
	v_add_f32_dpp v138, v138, v138 quad_perm:[1,0,3,2] row_mask:0xf bank_mask:0xf bound_ctrl:1
	s_nop 0
	v_addc_co_u32_e32 v145, vcc, 0, v163, vcc
	v_add_f32_dpp v138, v138, v138 quad_perm:[2,3,0,1] row_mask:0xf bank_mask:0xf bound_ctrl:1
	global_store_dwordx2 v[144:145], v[142:143], off nt
	s_nop 0
	v_add_f32_dpp v138, v138, v138 row_ror:4 row_mask:0xf bank_mask:0xf bound_ctrl:1
	s_nop 1
	v_mov_b32_dpp v139, v138 row_ror:8 row_mask:0xf bank_mask:0xf bound_ctrl:1
	s_and_saveexec_b64 s[4:5], s[0:1]
	s_cbranch_execz .LBB0_675
	v_add_f32_e32 v138, v138, v139
	global_atomic_add_f32 v[164:165], v138, off offset:708
.LBB0_675:
	s_or_b64 exec, exec, s[4:5]
	v_mov_b32_e32 v138, v4
	v_mov_b32_e32 v139, v8
	s_waitcnt vmcnt(7)
	v_pk_fma_f32 v[134:135], s[20:21], v[138:139], v[134:135]
	v_mov_b32_e32 v138, v16
	v_mov_b32_e32 v139, v12
	v_pk_fma_f32 v[136:137], s[20:21], v[138:139], v[136:137]
	v_cvt_pk_bf16_f32 v138, v134, v135
	v_pk_mul_f32 v[134:135], v[134:135], v[134:135]
	v_cvt_pk_bf16_f32 v139, v136, v137
	v_pk_mul_f32 v[136:137], v[136:137], v[136:137]
	v_add_f32_e32 v134, v135, v134
	v_add_f32_e32 v134, v136, v134
	v_add_f32_e32 v134, v137, v134
	s_mov_b32 s4, 0xb2000
	v_add_co_u32_e32 v140, vcc, s4, v162
	v_add_f32_dpp v134, v134, v134 quad_perm:[1,0,3,2] row_mask:0xf bank_mask:0xf bound_ctrl:1
	s_nop 0
	v_addc_co_u32_e32 v141, vcc, 0, v163, vcc
	v_add_f32_dpp v134, v134, v134 quad_perm:[2,3,0,1] row_mask:0xf bank_mask:0xf bound_ctrl:1
	global_store_dwordx2 v[140:141], v[138:139], off nt
	s_nop 0
	v_add_f32_dpp v134, v134, v134 row_ror:4 row_mask:0xf bank_mask:0xf bound_ctrl:1
	s_nop 1
	v_mov_b32_dpp v135, v134 row_ror:8 row_mask:0xf bank_mask:0xf bound_ctrl:1
	s_and_saveexec_b64 s[4:5], s[0:1]
	s_cbranch_execz .LBB0_677
	v_add_f32_e32 v134, v134, v135
	global_atomic_add_f32 v[164:165], v134, off offset:712
.LBB0_677:
	s_or_b64 exec, exec, s[4:5]
	v_mov_b32_e32 v134, v5
	v_mov_b32_e32 v135, v9
	s_waitcnt vmcnt(7)
	v_pk_fma_f32 v[130:131], s[20:21], v[134:135], v[130:131]
	v_mov_b32_e32 v134, v17
	v_mov_b32_e32 v135, v13
	v_pk_fma_f32 v[132:133], s[20:21], v[134:135], v[132:133]
	v_cvt_pk_bf16_f32 v134, v130, v131
	v_pk_mul_f32 v[130:131], v[130:131], v[130:131]
	v_cvt_pk_bf16_f32 v135, v132, v133
	v_pk_mul_f32 v[132:133], v[132:133], v[132:133]
	v_add_f32_e32 v130, v131, v130
	v_add_f32_e32 v130, v132, v130
	v_add_f32_e32 v130, v133, v130
	s_mov_b32 s4, 0xb3000
	v_add_co_u32_e32 v136, vcc, s4, v162
	v_add_f32_dpp v130, v130, v130 quad_perm:[1,0,3,2] row_mask:0xf bank_mask:0xf bound_ctrl:1
	s_nop 0
	v_addc_co_u32_e32 v137, vcc, 0, v163, vcc
	v_add_f32_dpp v130, v130, v130 quad_perm:[2,3,0,1] row_mask:0xf bank_mask:0xf bound_ctrl:1
	global_store_dwordx2 v[136:137], v[134:135], off nt
	s_nop 0
	v_add_f32_dpp v130, v130, v130 row_ror:4 row_mask:0xf bank_mask:0xf bound_ctrl:1
	s_nop 1
	v_mov_b32_dpp v131, v130 row_ror:8 row_mask:0xf bank_mask:0xf bound_ctrl:1
	s_and_saveexec_b64 s[4:5], s[0:1]
	s_cbranch_execz .LBB0_679
	v_add_f32_e32 v130, v130, v131
	global_atomic_add_f32 v[164:165], v130, off offset:716

; __device__ __forceinline__ float fdiv(float a, float b) { return a * __builtin_amdgcn_rcpf(b); }
; __device__ __forceinline__ float bf2f(u16 h) { return __uint_as_float(((unsigned)h) << 16); }
; __device__ __forceinline__ void gemm_tile(const Params& P, const GArgs& ga, const TileDesc& td, int wid_s) {
;     ...
;     static_for<4>([&](auto bc) __attribute__((always_inline)) {
;       constexpr int b0 = decltype(bc)::v * 8;
;       float4 r[8]; uint2 pe[8];
;       static_for<8>([&](auto ic2) __attribute__((always_inline)) {
;         constexpr int idx = b0 + decltype(ic2)::v; constexpr int ai = idx >> 4, m = (idx >> 2) & 3, j = idx & 3;
;         constexpr int rl = ai * HALF + m * 16 + j; constexpr int q = decltype(ic2)::v;
;         const uint2 t = *reinterpret_cast<const uint2*>(h3b + (size_t)rl * DM);
;         r[q] = make_float4(__uint_as_float(t.x << 16), __uint_as_float(t.x & 0xffff0000u),
;                            __uint_as_float(t.y << 16), __uint_as_float(t.y & 0xffff0000u));
;         pe[q] = *reinterpret_cast<const uint2*>(pd + (size_t)rl * DM);
;       });
;       __builtin_amdgcn_sched_barrier(0);
;       static_for<8>([&](auto ic2) __attribute__((always_inline)) {
;         constexpr int idx = b0 + decltype(ic2)::v; constexpr int ai = idx >> 4, m = (idx >> 2) & 3, j = idx & 3;
;         constexpr int rl = ai * HALF + m * 16 + j; constexpr int q = decltype(ic2)::v;
;         const float rs = rsv[idx];
;         float4 v;
;         v.x = r[q].x + fdiv(1.f, 1.f + __expf(-rs * acc[ai][0][m][0][j])) * bf2f((u16)(pe[q].x & 0xffff));
;         v.y = r[q].y + fdiv(1.f, 1.f + __expf(-rs * acc[ai][0][m][1][j])) * bf2f((u16)(pe[q].x >> 16));
;         v.z = r[q].z + fdiv(1.f, 1.f + __expf(-rs * acc[ai][1][m][0][j])) * bf2f((u16)(pe[q].y & 0xffff));
;         v.w = r[q].w + fdiv(1.f, 1.f + __expf(-rs * acc[ai][1][m][1][j])) * bf2f((u16)(pe[q].y >> 16));
;         uint2 o; o.x = pack2(v.x, v.y); o.y = pack2(v.z, v.w);
;         *reinterpret_cast<uint2*>(h4b + (size_t)rl * DM) = o;
;         float s = red16(v.x * v.x + v.y * v.y + v.z * v.z + v.w * v.w);
;         if (efr == 0) unsafeAtomicAdd(sso + rl, s);
;       });
.LBB0_682:
	s_and_b64 vcc, exec, s[8:9]
	v_ashrrev_i32_e32 v167, 31, v166
	s_cbranch_vccz .LBB0_748
	v_lshlrev_b64 v[162:163], 2, v[166:167]
	v_lshl_add_u64 v[130:131], s[72:73], 0, v[162:163]
	global_load_dwordx4 v[158:161], v[130:131], off
	global_load_dwordx4 v[154:157], v[130:131], off offset:64
	global_load_dwordx4 v[150:153], v[130:131], off offset:128
	global_load_dwordx4 v[146:149], v[130:131], off offset:192
	global_load_dwordx4 v[142:145], v[130:131], off offset:512
	global_load_dwordx4 v[138:141], v[130:131], off offset:576
	global_load_dwordx4 v[134:137], v[130:131], off offset:640
	s_nop 0
	global_load_dwordx4 v[130:133], v[130:131], off offset:704
	v_mov_b32_e32 v164, s17
	s_waitcnt vmcnt(7)
	v_fmamk_f32 v158, v158, 0x3a000000, v164
	v_rsq_f32_e32 v158, v158
	v_lshlrev_b64 v[172:173], 12, v[166:167]
	v_ashrrev_i32_e32 v169, 31, v168
	v_lshl_add_u64 v[164:165], s[80:81], 0, v[172:173]
	v_lshlrev_b64 v[168:169], 1, v[168:169]
	v_lshl_add_u64 v[170:171], v[164:165], 0, v[168:169]
	v_lshl_add_u64 v[164:165], s[24:25], 0, v[172:173]
	v_lshl_add_u64 v[172:173], s[62:63], 0, v[172:173]
	v_lshl_add_u64 v[164:165], v[164:165], 0, v[168:169]
	v_lshl_add_u64 v[168:169], v[172:173], 0, v[168:169]
	global_load_dwordx2 v[172:173], v[170:171], off
	global_load_dwordx2 v[204:205], v[168:169], off
	v_lshl_add_u64 v[162:163], s[70:71], 0, v[162:163]
	s_waitcnt vmcnt(1)
	v_lshlrev_b32_e32 v208, 16, v172
	v_and_b32_e32 v209, 0xffff0000, v172
	v_add_co_u32_e32 v172, vcc, s2, v170
	v_lshlrev_b32_e32 v210, 16, v173
	v_and_b32_e32 v211, 0xffff0000, v173
	v_addc_co_u32_e32 v173, vcc, 0, v171, vcc
	v_add_co_u32_e32 v174, vcc, s2, v168
	global_load_dwordx2 v[198:199], v[172:173], off offset:-4096
	s_nop 0
	v_addc_co_u32_e32 v175, vcc, 0, v169, vcc
	global_load_dwordx2 v[196:197], v[174:175], off offset:-4096
	global_load_dwordx2 v[194:195], v[172:173], off
	global_load_dwordx2 v[192:193], v[174:175], off
	v_add_co_u32_e32 v172, vcc, s55, v170
	s_nop 1
	v_addc_co_u32_e32 v173, vcc, 0, v171, vcc
	global_load_dwordx2 v[190:191], v[172:173], off
	v_add_co_u32_e32 v172, vcc, s55, v168
	s_nop 1
	v_addc_co_u32_e32 v173, vcc, 0, v169, vcc
	global_load_dwordx2 v[188:189], v[172:173], off
	v_add_co_u32_e32 v172, vcc, s13, v170
	s_nop 1
	v_addc_co_u32_e32 v173, vcc, 0, v171, vcc
	v_add_co_u32_e32 v174, vcc, s13, v168
	global_load_dwordx2 v[186:187], v[172:173], off offset:-4096
	s_nop 0
	v_addc_co_u32_e32 v175, vcc, 0, v169, vcc
	global_load_dwordx2 v[184:185], v[174:175], off offset:-4096
	global_load_dwordx2 v[182:183], v[172:173], off
	global_load_dwordx2 v[180:181], v[174:175], off
	v_add_co_u32_e32 v172, vcc, s14, v170
	s_nop 1
	v_addc_co_u32_e32 v173, vcc, 0, v171, vcc
	v_add_co_u32_e32 v206, vcc, s14, v168
	global_load_dwordx2 v[178:179], v[172:173], off offset:-4096
	s_nop 0
	v_addc_co_u32_e32 v207, vcc, 0, v169, vcc
	global_load_dwordx2 v[176:177], v[206:207], off offset:-4096
	global_load_dwordx2 v[174:175], v[172:173], off
	s_nop 0
	global_load_dwordx2 v[172:173], v[206:207], off
	v_mul_f32_e64 v206, v114, -v158
	v_mul_f32_e32 v206, 0x3fb8aa3b, v206
	v_exp_f32_e32 v206, v206
	s_waitcnt vmcnt(14)
	v_lshlrev_b32_e32 v207, 16, v204
	v_and_b32_e32 v204, 0xffff0000, v204
	v_cmp_eq_u32_e64 s[0:1], 0, v203
	v_add_f32_e32 v206, 1.0, v206
	v_rcp_f32_e32 v206, v206
	s_nop 0
	v_fmac_f32_e32 v208, v206, v207
	v_mul_f32_e64 v206, v118, -v158
	v_mul_f32_e32 v206, 0x3fb8aa3b, v206
	v_exp_f32_e32 v206, v206
	s_nop 0
	v_add_f32_e32 v206, 1.0, v206
	v_rcp_f32_e32 v206, v206
	s_nop 0
	v_fmac_f32_e32 v209, v206, v204
	v_mul_f32_e64 v204, v126, -v158
	v_mul_f32_e32 v204, 0x3fb8aa3b, v204
	v_mul_f32_e64 v158, v122, -v158
	v_exp_f32_e32 v204, v204
	v_mul_f32_e32 v158, 0x3fb8aa3b, v158
	v_exp_f32_e32 v158, v158
	v_lshlrev_b32_e32 v206, 16, v205
	v_add_f32_e32 v204, 1.0, v204
	v_rcp_f32_e32 v204, v204
	v_add_f32_e32 v158, 1.0, v158
	v_rcp_f32_e32 v158, v158
	v_fmac_f32_e32 v210, v204, v206
	v_and_b32_e32 v204, 0xffff0000, v205
	v_fmac_f32_e32 v211, v158, v204
	v_mul_f32_e32 v158, v209, v209
	v_fmac_f32_e32 v158, v208, v208
	v_fmac_f32_e32 v158, v210, v210
	v_fmac_f32_e32 v158, v211, v211
	v_cvt_pk_bf16_f32 v204, v208, v209
	v_cvt_pk_bf16_f32 v205, v210, v211
	v_add_f32_dpp v158, v158, v158 quad_perm:[1,0,3,2] row_mask:0xf bank_mask:0xf bound_ctrl:1
	global_store_dwordx2 v[164:165], v[204:205], off nt
	s_nop 0
	v_add_f32_dpp v158, v158, v158 quad_perm:[2,3,0,1] row_mask:0xf bank_mask:0xf bound_ctrl:1
	s_nop 1
	v_add_f32_dpp v158, v158, v158 row_ror:4 row_mask:0xf bank_mask:0xf bound_ctrl:1
	s_nop 1
	v_mov_b32_dpp v204, v158 row_ror:8 row_mask:0xf bank_mask:0xf bound_ctrl:1
	s_and_saveexec_b64 s[4:5], s[0:1]
	s_cbranch_execz .LBB0_685
	v_add_f32_e32 v158, v158, v204
	global_atomic_add_f32 v[162:163], v158, off
; __device__ __forceinline__ float fdiv(float a, float b) { return a * __builtin_amdgcn_rcpf(b); }
; __device__ __forceinline__ float bf2f(u16 h) { return __uint_as_float(((unsigned)h) << 16); }
; __device__ __forceinline__ void gemm_tile(const Params& P, const GArgs& ga, const TileDesc& td, int wid_s) {
;     ...
;       static_for<8>([&](auto ic2) __attribute__((always_inline)) {
;         constexpr int idx = b0 + decltype(ic2)::v; constexpr int ai = idx >> 4, m = (idx >> 2) & 3, j = idx & 3;
;         constexpr int rl = ai * HALF + m * 16 + j; constexpr int q = decltype(ic2)::v;
;         const float rs = rsv[idx];
;         float4 v;
;         v.x = r[q].x + fdiv(1.f, 1.f + __expf(-rs * acc[ai][0][m][0][j])) * bf2f((u16)(pe[q].x & 0xffff));
;         v.y = r[q].y + fdiv(1.f, 1.f + __expf(-rs * acc[ai][0][m][1][j])) * bf2f((u16)(pe[q].x >> 16));
;         v.z = r[q].z + fdiv(1.f, 1.f + __expf(-rs * acc[ai][1][m][0][j])) * bf2f((u16)(pe[q].y & 0xffff));
;         v.w = r[q].w + fdiv(1.f, 1.f + __expf(-rs * acc[ai][1][m][1][j])) * bf2f((u16)(pe[q].y >> 16));
;         uint2 o; o.x = pack2(v.x, v.y); o.y = pack2(v.z, v.w);
;         *reinterpret_cast<uint2*>(h4b + (size_t)rl * DM) = o;
;         float s = red16(v.x * v.x + v.y * v.y + v.z * v.z + v.w * v.w);
;         if (efr == 0) unsafeAtomicAdd(sso + rl, s);
;       });
.LBB0_685:
	s_or_b64 exec, exec, s[4:5]
	v_mov_b32_e32 v158, s17
	v_fmamk_f32 v158, v159, 0x3a000000, v158
	v_rsq_f32_e32 v203, v158
	s_waitcnt vmcnt(13)
	v_lshlrev_b32_e32 v206, 16, v196
	v_and_b32_e32 v207, 0xffff0000, v196
	v_lshlrev_b32_e32 v158, 16, v198
	v_mul_f32_e64 v204, v115, -v203
	v_mul_f32_e64 v205, v119, -v203
	v_mul_f32_e32 v204, 0x3fb8aa3b, v204
	v_mul_f32_e32 v205, 0x3fb8aa3b, v205
	v_exp_f32_e32 v204, v204
	v_exp_f32_e32 v205, v205
	v_mul_f32_e64 v196, v127, -v203
	v_mul_f32_e64 v203, v123, -v203
	v_mul_f32_e32 v196, 0x3fb8aa3b, v196
	v_mul_f32_e32 v203, 0x3fb8aa3b, v203
	v_add_f32_e32 v204, 1.0, v204
	v_add_f32_e32 v205, 1.0, v205
	v_exp_f32_e32 v196, v196
	v_exp_f32_e32 v203, v203
	v_rcp_f32_e32 v204, v204
	v_rcp_f32_e32 v205, v205
	v_and_b32_e32 v159, 0xffff0000, v198
	v_add_f32_e32 v196, 1.0, v196
	v_add_f32_e32 v203, 1.0, v203
	v_pk_fma_f32 v[158:159], v[204:205], v[206:207], v[158:159]
	v_rcp_f32_e32 v204, v196
	v_rcp_f32_e32 v205, v203
	v_lshlrev_b32_e32 v198, 16, v199
	v_and_b32_e32 v199, 0xffff0000, v199
	v_lshlrev_b32_e32 v196, 16, v197
	v_and_b32_e32 v197, 0xffff0000, v197
	v_pk_fma_f32 v[196:197], v[204:205], v[196:197], v[198:199]
	v_cvt_pk_bf16_f32 v198, v158, v159
	v_pk_mul_f32 v[158:159], v[158:159], v[158:159]
	v_cvt_pk_bf16_f32 v199, v196, v197
	v_pk_mul_f32 v[196:197], v[196:197], v[196:197]
	v_add_f32_e32 v158, v158, v159
	v_add_f32_e32 v158, v158, v196
	v_add_f32_e32 v158, v197, v158
	s_movk_i32 s4, 0x1000
	v_add_co_u32_e32 v204, vcc, s4, v164
	v_add_f32_dpp v158, v158, v158 quad_perm:[1,0,3,2] row_mask:0xf bank_mask:0xf bound_ctrl:1
	s_nop 0
	v_addc_co_u32_e32 v205, vcc, 0, v165, vcc
	v_add_f32_dpp v158, v158, v158 quad_perm:[2,3,0,1] row_mask:0xf bank_mask:0xf bound_ctrl:1
	global_store_dwordx2 v[204:205], v[198:199], off nt
	s_nop 0
	v_add_f32_dpp v158, v158, v158 row_ror:4 row_mask:0xf bank_mask:0xf bound_ctrl:1
	s_nop 1
	v_mov_b32_dpp v159, v158 row_ror:8 row_mask:0xf bank_mask:0xf bound_ctrl:1
	s_and_saveexec_b64 s[4:5], s[0:1]
	s_cbranch_execz .LBB0_687
	v_add_f32_e32 v158, v158, v159
	global_atomic_add_f32 v[162:163], v158, off offset:4
.LBB0_687:
	s_or_b64 exec, exec, s[4:5]
	v_mov_b32_e32 v158, s17
	v_fmamk_f32 v158, v160, 0x3a000000, v158
	v_rsq_f32_e32 v160, v158
	s_waitcnt vmcnt(12)
	v_lshlrev_b32_e32 v198, 16, v192
	v_and_b32_e32 v199, 0xffff0000, v192
	v_lshlrev_b32_e32 v158, 16, v194
	v_mul_f32_e64 v196, v116, -v160
	v_mul_f32_e64 v197, v120, -v160
	v_mul_f32_e32 v196, 0x3fb8aa3b, v196
	v_mul_f32_e32 v197, 0x3fb8aa3b, v197
	v_exp_f32_e32 v196, v196
	v_exp_f32_e32 v197, v197
	v_mul_f32_e64 v192, v128, -v160
	v_mul_f32_e64 v160, v124, -v160
	v_mul_f32_e32 v192, 0x3fb8aa3b, v192
	v_mul_f32_e32 v160, 0x3fb8aa3b, v160
	v_add_f32_e32 v196, 1.0, v196
	v_add_f32_e32 v197, 1.0, v197
	v_exp_f32_e32 v192, v192
	v_exp_f32_e32 v160, v160
	v_rcp_f32_e32 v196, v196
	v_rcp_f32_e32 v197, v197
	v_and_b32_e32 v159, 0xffff0000, v194
	v_add_f32_e32 v192, 1.0, v192
	v_add_f32_e32 v160, 1.0, v160
	v_pk_fma_f32 v[158:159], v[196:197], v[198:199], v[158:159]
	v_rcp_f32_e32 v196, v192
	v_rcp_f32_e32 v197, v160
	v_lshlrev_b32_e32 v194, 16, v195
	v_and_b32_e32 v195, 0xffff0000, v195
	v_lshlrev_b32_e32 v192, 16, v193
	v_and_b32_e32 v193, 0xffff0000, v193
	v_pk_fma_f32 v[192:193], v[196:197], v[192:193], v[194:195]
	v_cvt_pk_bf16_f32 v194, v158, v159
	v_pk_mul_f32 v[158:159], v[158:159], v[158:159]
	v_cvt_pk_bf16_f32 v195, v192, v193
	v_pk_mul_f32 v[192:193], v[192:193], v[192:193]
	v_add_f32_e32 v158, v158, v159
	v_add_f32_e32 v158, v158, v192
	v_add_f32_e32 v158, v193, v158
	v_add_co_u32_e32 v196, vcc, s2, v164
	s_nop 0
	v_add_f32_dpp v158, v158, v158 quad_perm:[1,0,3,2] row_mask:0xf bank_mask:0xf bound_ctrl:1
	v_addc_co_u32_e32 v197, vcc, 0, v165, vcc
	s_nop 0
	v_add_f32_dpp v158, v158, v158 quad_perm:[2,3,0,1] row_mask:0xf bank_mask:0xf bound_ctrl:1
	global_store_dwordx2 v[196:197], v[194:195], off nt
	s_nop 0
	v_add_f32_dpp v158, v158, v158 row_ror:4 row_mask:0xf bank_mask:0xf bound_ctrl:1
	s_nop 1
	v_mov_b32_dpp v159, v158 row_ror:8 row_mask:0xf bank_mask:0xf bound_ctrl:1
	s_and_saveexec_b64 s[4:5], s[0:1]
	s_cbranch_execz .LBB0_689
	v_add_f32_e32 v158, v158, v159
	global_atomic_add_f32 v[162:163], v158, off offset:8
.LBB0_689:
	s_or_b64 exec, exec, s[4:5]
	v_mov_b32_e32 v158, s17
	v_fmamk_f32 v158, v161, 0x3a000000, v158
	v_rsq_f32_e32 v194, v158
	s_waitcnt vmcnt(12)
	v_lshlrev_b32_e32 v158, 16, v190
	v_and_b32_e32 v159, 0xffff0000, v190
	v_lshlrev_b32_e32 v160, 16, v191
	v_and_b32_e32 v161, 0xffff0000, v191
	v_mul_f32_e64 v190, v117, -v194
	v_mul_f32_e64 v191, v121, -v194
	v_mul_f32_e32 v190, 0x3fb8aa3b, v190
	v_mul_f32_e32 v191, 0x3fb8aa3b, v191
	v_exp_f32_e32 v190, v190
	v_exp_f32_e32 v191, v191
	s_waitcnt vmcnt(11)
	v_lshlrev_b32_e32 v192, 16, v188
	v_and_b32_e32 v193, 0xffff0000, v188
	v_add_f32_e32 v190, 1.0, v190
	v_add_f32_e32 v191, 1.0, v191
	v_rcp_f32_e32 v190, v190
	v_rcp_f32_e32 v191, v191
	v_mul_f32_e64 v188, v129, -v194
	v_mul_f32_e32 v188, 0x3fb8aa3b, v188
	v_exp_f32_e32 v188, v188
	v_pk_fma_f32 v[158:159], v[190:191], v[192:193], v[158:159]
	v_mul_f32_e64 v191, v125, -v194
	v_mul_f32_e32 v191, 0x3fb8aa3b, v191
	v_exp_f32_e32 v191, v191
	v_add_f32_e32 v188, 1.0, v188
	v_rcp_f32_e32 v190, v188
	v_lshlrev_b32_e32 v188, 16, v189
	v_add_f32_e32 v191, 1.0, v191
	v_rcp_f32_e32 v191, v191
	v_and_b32_e32 v189, 0xffff0000, v189
	v_pk_fma_f32 v[160:161], v[190:191], v[188:189], v[160:161]
	v_cvt_pk_bf16_f32 v188, v158, v159
	v_pk_mul_f32 v[158:159], v[158:159], v[158:159]
	v_cvt_pk_bf16_f32 v189, v160, v161
	v_pk_mul_f32 v[160:161], v[160:161], v[160:161]
	v_add_f32_e32 v158, v158, v159
	v_add_f32_e32 v158, v158, v160
	v_add_f32_e32 v158, v161, v158
	v_add_co_u32_e32 v190, vcc, s55, v164
	s_nop 0
	v_add_f32_dpp v158, v158, v158 quad_perm:[1,0,3,2] row_mask:0xf bank_mask:0xf bound_ctrl:1
	v_addc_co_u32_e32 v191, vcc, 0, v165, vcc
	s_nop 0
	v_add_f32_dpp v158, v158, v158 quad_perm:[2,3,0,1] row_mask:0xf bank_mask:0xf bound_ctrl:1
	global_store_dwordx2 v[190:191], v[188:189], off nt
	s_nop 0
	v_add_f32_dpp v158, v158, v158 row_ror:4 row_mask:0xf bank_mask:0xf bound_ctrl:1
	s_nop 1
	v_mov_b32_dpp v159, v158 row_ror:8 row_mask:0xf bank_mask:0xf bound_ctrl:1
	s_and_saveexec_b64 s[4:5], s[0:1]
	s_cbranch_execz .LBB0_691
	v_add_f32_e32 v158, v158, v159
	global_atomic_add_f32 v[162:163], v158, off offset:12
; __device__ __forceinline__ float fdiv(float a, float b) { return a * __builtin_amdgcn_rcpf(b); }
; __device__ __forceinline__ float bf2f(u16 h) { return __uint_as_float(((unsigned)h) << 16); }
; __device__ __forceinline__ void gemm_tile(const Params& P, const GArgs& ga, const TileDesc& td, int wid_s) {
;     ...
;       static_for<8>([&](auto ic2) __attribute__((always_inline)) {
;         constexpr int idx = b0 + decltype(ic2)::v; constexpr int ai = idx >> 4, m = (idx >> 2) & 3, j = idx & 3;
;         constexpr int rl = ai * HALF + m * 16 + j; constexpr int q = decltype(ic2)::v;
;         const float rs = rsv[idx];
;         float4 v;
;         v.x = r[q].x + fdiv(1.f, 1.f + __expf(-rs * acc[ai][0][m][0][j])) * bf2f((u16)(pe[q].x & 0xffff));
;         v.y = r[q].y + fdiv(1.f, 1.f + __expf(-rs * acc[ai][0][m][1][j])) * bf2f((u16)(pe[q].x >> 16));
;         v.z = r[q].z + fdiv(1.f, 1.f + __expf(-rs * acc[ai][1][m][0][j])) * bf2f((u16)(pe[q].y & 0xffff));
;         v.w = r[q].w + fdiv(1.f, 1.f + __expf(-rs * acc[ai][1][m][1][j])) * bf2f((u16)(pe[q].y >> 16));
;         uint2 o; o.x = pack2(v.x, v.y); o.y = pack2(v.z, v.w);
;         *reinterpret_cast<uint2*>(h4b + (size_t)rl * DM) = o;
;         float s = red16(v.x * v.x + v.y * v.y + v.z * v.z + v.w * v.w);
;         if (efr == 0) unsafeAtomicAdd(sso + rl, s);
;       });
.LBB0_691:
	s_or_b64 exec, exec, s[4:5]
	v_mov_b32_e32 v158, s17
	v_fmamk_f32 v154, v154, 0x3a000000, v158
	v_rsq_f32_e32 v154, v154
	s_waitcnt vmcnt(11)
	v_lshlrev_b32_e32 v158, 16, v186
	v_and_b32_e32 v159, 0xffff0000, v186
	v_lshlrev_b32_e32 v160, 16, v187
	v_and_b32_e32 v161, 0xffff0000, v187
	v_mul_f32_e64 v186, v98, -v154
	v_mul_f32_e64 v187, v102, -v154
	v_mul_f32_e32 v186, 0x3fb8aa3b, v186
	v_mul_f32_e32 v187, 0x3fb8aa3b, v187
	v_exp_f32_e32 v186, v186
	v_exp_f32_e32 v187, v187
	s_waitcnt vmcnt(10)
	v_lshlrev_b32_e32 v188, 16, v184
	v_and_b32_e32 v189, 0xffff0000, v184
	v_mul_f32_e64 v184, v110, -v154
	v_mul_f32_e64 v154, v106, -v154
	v_mul_f32_e32 v184, 0x3fb8aa3b, v184
	v_mul_f32_e32 v154, 0x3fb8aa3b, v154
	v_add_f32_e32 v186, 1.0, v186
	v_add_f32_e32 v187, 1.0, v187
	v_exp_f32_e32 v184, v184
	v_exp_f32_e32 v154, v154
	v_rcp_f32_e32 v186, v186
	v_rcp_f32_e32 v187, v187
	v_add_f32_e32 v184, 1.0, v184
	v_add_f32_e32 v154, 1.0, v154
	s_mov_b32 s4, 0x10000
	v_pk_fma_f32 v[158:159], v[186:187], v[188:189], v[158:159]
	v_rcp_f32_e32 v186, v184
	v_rcp_f32_e32 v187, v154
	v_lshlrev_b32_e32 v184, 16, v185
	v_and_b32_e32 v185, 0xffff0000, v185
	v_pk_fma_f32 v[160:161], v[186:187], v[184:185], v[160:161]
	v_cvt_pk_bf16_f32 v184, v158, v159
	v_pk_mul_f32 v[158:159], v[158:159], v[158:159]
	v_cvt_pk_bf16_f32 v185, v160, v161
	v_pk_mul_f32 v[160:161], v[160:161], v[160:161]
	v_add_f32_e32 v154, v158, v159
	v_add_f32_e32 v154, v154, v160
	v_add_f32_e32 v154, v161, v154
	v_add_co_u32_e32 v186, vcc, s4, v164
	s_nop 0
	v_add_f32_dpp v154, v154, v154 quad_perm:[1,0,3,2] row_mask:0xf bank_mask:0xf bound_ctrl:1
	v_addc_co_u32_e32 v187, vcc, 0, v165, vcc
	s_nop 0
	v_add_f32_dpp v154, v154, v154 quad_perm:[2,3,0,1] row_mask:0xf bank_mask:0xf bound_ctrl:1
	global_store_dwordx2 v[186:187], v[184:185], off nt
	s_nop 0
	v_add_f32_dpp v154, v154, v154 row_ror:4 row_mask:0xf bank_mask:0xf bound_ctrl:1
	s_nop 1
	v_mov_b32_dpp v158, v154 row_ror:8 row_mask:0xf bank_mask:0xf bound_ctrl:1
	s_and_saveexec_b64 s[4:5], s[0:1]
	s_cbranch_execz .LBB0_693
	v_add_f32_e32 v154, v154, v158
	global_atomic_add_f32 v[162:163], v154, off offset:64
.LBB0_693:
	s_or_b64 exec, exec, s[4:5]
	v_mov_b32_e32 v154, s17
	v_fmamk_f32 v154, v155, 0x3a000000, v154
	v_rsq_f32_e32 v184, v154
	s_waitcnt vmcnt(10)
	v_lshlrev_b32_e32 v154, 16, v182
	v_and_b32_e32 v155, 0xffff0000, v182
	v_lshlrev_b32_e32 v158, 16, v183
	v_mul_f32_e64 v160, v99, -v184
	v_mul_f32_e64 v161, v103, -v184
	v_mul_f32_e32 v160, 0x3fb8aa3b, v160
	v_mul_f32_e32 v161, 0x3fb8aa3b, v161
	v_exp_f32_e32 v160, v160
	v_exp_f32_e32 v161, v161
	v_and_b32_e32 v159, 0xffff0000, v183
	s_waitcnt vmcnt(9)
	v_lshlrev_b32_e32 v182, 16, v180
	v_add_f32_e32 v160, 1.0, v160
	v_add_f32_e32 v161, 1.0, v161
	v_rcp_f32_e32 v160, v160
	v_rcp_f32_e32 v161, v161
	v_and_b32_e32 v183, 0xffff0000, v180
	v_lshlrev_b32_e32 v180, 16, v181
	v_and_b32_e32 v181, 0xffff0000, v181
	v_pk_fma_f32 v[154:155], v[160:161], v[182:183], v[154:155]
	v_mul_f32_e64 v160, v111, -v184
	v_mul_f32_e64 v161, v107, -v184
	v_mul_f32_e32 v160, 0x3fb8aa3b, v160
	v_mul_f32_e32 v161, 0x3fb8aa3b, v161
	v_exp_f32_e32 v160, v160
	v_exp_f32_e32 v161, v161
	v_add_f32_e32 v160, 1.0, v160
	v_add_f32_e32 v161, 1.0, v161
	v_rcp_f32_e32 v160, v160
	v_rcp_f32_e32 v161, v161
	s_nop 0
	v_pk_fma_f32 v[158:159], v[160:161], v[180:181], v[158:159]
	v_cvt_pk_bf16_f32 v160, v154, v155
	v_pk_mul_f32 v[154:155], v[154:155], v[154:155]
	v_cvt_pk_bf16_f32 v161, v158, v159
	v_pk_mul_f32 v[158:159], v[158:159], v[158:159]
	v_add_f32_e32 v154, v154, v155
	v_add_f32_e32 v154, v154, v158
	v_add_f32_e32 v154, v159, v154
	v_add_co_u32_e32 v180, vcc, s13, v164
	s_nop 0
	v_add_f32_dpp v154, v154, v154 quad_perm:[1,0,3,2] row_mask:0xf bank_mask:0xf bound_ctrl:1
	v_addc_co_u32_e32 v181, vcc, 0, v165, vcc
	s_nop 0
	v_add_f32_dpp v154, v154, v154 quad_perm:[2,3,0,1] row_mask:0xf bank_mask:0xf bound_ctrl:1
	global_store_dwordx2 v[180:181], v[160:161], off nt
	s_nop 0
	v_add_f32_dpp v154, v154, v154 row_ror:4 row_mask:0xf bank_mask:0xf bound_ctrl:1
	s_nop 1
	v_mov_b32_dpp v155, v154 row_ror:8 row_mask:0xf bank_mask:0xf bound_ctrl:1
	s_and_saveexec_b64 s[4:5], s[0:1]
	s_cbranch_execz .LBB0_695
	v_add_f32_e32 v154, v154, v155
	global_atomic_add_f32 v[162:163], v154, off offset:68
.LBB0_695:
	s_or_b64 exec, exec, s[4:5]
	v_mov_b32_e32 v154, s17
	v_fmamk_f32 v154, v156, 0x3a000000, v154
	v_rsq_f32_e32 v156, v154
	s_waitcnt vmcnt(9)
	v_lshlrev_b32_e32 v154, 16, v178
	v_and_b32_e32 v155, 0xffff0000, v178
	v_lshlrev_b32_e32 v158, 16, v179
	v_mul_f32_e64 v160, v100, -v156
	v_mul_f32_e64 v161, v104, -v156
	v_mul_f32_e32 v160, 0x3fb8aa3b, v160
	v_mul_f32_e32 v161, 0x3fb8aa3b, v161
	v_exp_f32_e32 v160, v160
	v_exp_f32_e32 v161, v161
	v_and_b32_e32 v159, 0xffff0000, v179
	s_waitcnt vmcnt(8)
	v_lshlrev_b32_e32 v178, 16, v176
	v_add_f32_e32 v160, 1.0, v160
	v_add_f32_e32 v161, 1.0, v161
	v_rcp_f32_e32 v160, v160
	v_rcp_f32_e32 v161, v161
	v_and_b32_e32 v179, 0xffff0000, v176
	v_lshlrev_b32_e32 v176, 16, v177
	v_and_b32_e32 v177, 0xffff0000, v177
	v_pk_fma_f32 v[154:155], v[160:161], v[178:179], v[154:155]
	v_mul_f32_e64 v160, v112, -v156
	v_mul_f32_e64 v156, v108, -v156
	v_mul_f32_e32 v160, 0x3fb8aa3b, v160
	v_mul_f32_e32 v156, 0x3fb8aa3b, v156
	v_exp_f32_e32 v160, v160
	v_exp_f32_e32 v156, v156
	v_add_f32_e32 v160, 1.0, v160
	v_add_f32_e32 v156, 1.0, v156
	v_rcp_f32_e32 v160, v160
	v_rcp_f32_e32 v161, v156
	s_nop 0
	v_pk_fma_f32 v[158:159], v[160:161], v[176:177], v[158:159]
	v_cvt_pk_bf16_f32 v160, v154, v155
	v_pk_mul_f32 v[154:155], v[154:155], v[154:155]
	v_cvt_pk_bf16_f32 v161, v158, v159
	v_pk_mul_f32 v[158:159], v[158:159], v[158:159]
	v_add_f32_e32 v154, v154, v155
	v_add_f32_e32 v154, v154, v158
	v_add_f32_e32 v154, v159, v154
	v_add_co_u32_e32 v176, vcc, s67, v164
	s_nop 0
	v_add_f32_dpp v154, v154, v154 quad_perm:[1,0,3,2] row_mask:0xf bank_mask:0xf bound_ctrl:1
	v_addc_co_u32_e32 v177, vcc, 0, v165, vcc
	s_nop 0
	v_add_f32_dpp v154, v154, v154 quad_perm:[2,3,0,1] row_mask:0xf bank_mask:0xf bound_ctrl:1
	global_store_dwordx2 v[176:177], v[160:161], off nt
	s_nop 0
	v_add_f32_dpp v154, v154, v154 row_ror:4 row_mask:0xf bank_mask:0xf bound_ctrl:1
	s_nop 1
	v_mov_b32_dpp v155, v154 row_ror:8 row_mask:0xf bank_mask:0xf bound_ctrl:1
	s_and_saveexec_b64 s[4:5], s[0:1]
	s_cbranch_execz .LBB0_697
	v_add_f32_e32 v154, v154, v155
	global_atomic_add_f32 v[162:163], v154, off offset:72
; __device__ __forceinline__ float fdiv(float a, float b) { return a * __builtin_amdgcn_rcpf(b); }
; __device__ __forceinline__ float bf2f(u16 h) { return __uint_as_float(((unsigned)h) << 16); }
; __device__ __forceinline__ void gemm_tile(const Params& P, const GArgs& ga, const TileDesc& td, int wid_s) {
;     ...
;     static_for<4>([&](auto bc) __attribute__((always_inline)) {
;       constexpr int b0 = decltype(bc)::v * 8;
;       float4 r[8]; uint2 pe[8];
;       static_for<8>([&](auto ic2) __attribute__((always_inline)) {
;         constexpr int idx = b0 + decltype(ic2)::v; constexpr int ai = idx >> 4, m = (idx >> 2) & 3, j = idx & 3;
;         constexpr int rl = ai * HALF + m * 16 + j; constexpr int q = decltype(ic2)::v;
;         const uint2 t = *reinterpret_cast<const uint2*>(h3b + (size_t)rl * DM);
;         r[q] = make_float4(__uint_as_float(t.x << 16), __uint_as_float(t.x & 0xffff0000u),
;                            __uint_as_float(t.y << 16), __uint_as_float(t.y & 0xffff0000u));
;         pe[q] = *reinterpret_cast<const uint2*>(pd + (size_t)rl * DM);
;       });
;       __builtin_amdgcn_sched_barrier(0);
;       static_for<8>([&](auto ic2) __attribute__((always_inline)) {
;         constexpr int idx = b0 + decltype(ic2)::v; constexpr int ai = idx >> 4, m = (idx >> 2) & 3, j = idx & 3;
;         constexpr int rl = ai * HALF + m * 16 + j; constexpr int q = decltype(ic2)::v;
;         const float rs = rsv[idx];
;         float4 v;
;         v.x = r[q].x + fdiv(1.f, 1.f + __expf(-rs * acc[ai][0][m][0][j])) * bf2f((u16)(pe[q].x & 0xffff));
;         v.y = r[q].y + fdiv(1.f, 1.f + __expf(-rs * acc[ai][0][m][1][j])) * bf2f((u16)(pe[q].x >> 16));
;         v.z = r[q].z + fdiv(1.f, 1.f + __expf(-rs * acc[ai][1][m][0][j])) * bf2f((u16)(pe[q].y & 0xffff));
;         v.w = r[q].w + fdiv(1.f, 1.f + __expf(-rs * acc[ai][1][m][1][j])) * bf2f((u16)(pe[q].y >> 16));
;         uint2 o; o.x = pack2(v.x, v.y); o.y = pack2(v.z, v.w);
;         *reinterpret_cast<uint2*>(h4b + (size_t)rl * DM) = o;
;         float s = red16(v.x * v.x + v.y * v.y + v.z * v.z + v.w * v.w);
;         if (efr == 0) unsafeAtomicAdd(sso + rl, s);
;       });
.LBB0_697:
	s_or_b64 exec, exec, s[4:5]
	v_mov_b32_e32 v154, s17
	v_fmamk_f32 v154, v157, 0x3a000000, v154
	v_rsq_f32_e32 v176, v154
	s_waitcnt vmcnt(8)
	v_lshlrev_b32_e32 v154, 16, v174
	v_and_b32_e32 v155, 0xffff0000, v174
	s_waitcnt vmcnt(7)
	v_lshlrev_b32_e32 v160, 16, v172
	v_mul_f32_e64 v158, v101, -v176
	v_mul_f32_e64 v159, v105, -v176
	v_mul_f32_e32 v158, 0x3fb8aa3b, v158
	v_mul_f32_e32 v159, 0x3fb8aa3b, v159
	v_exp_f32_e32 v158, v158
	v_exp_f32_e32 v159, v159
	v_and_b32_e32 v161, 0xffff0000, v172
	v_lshlrev_b32_e32 v156, 16, v175
	v_add_f32_e32 v158, 1.0, v158
	v_add_f32_e32 v159, 1.0, v159
	v_rcp_f32_e32 v158, v158
	v_rcp_f32_e32 v159, v159
	v_and_b32_e32 v157, 0xffff0000, v175
	v_pk_fma_f32 v[154:155], v[158:159], v[160:161], v[154:155]
	v_mul_f32_e64 v158, v113, -v176
	v_mul_f32_e64 v159, v109, -v176
	v_mul_f32_e32 v158, 0x3fb8aa3b, v158
	v_mul_f32_e32 v159, 0x3fb8aa3b, v159
	v_exp_f32_e32 v158, v158
	v_exp_f32_e32 v159, v159
	v_lshlrev_b32_e32 v160, 16, v173
	v_and_b32_e32 v161, 0xffff0000, v173
	v_add_f32_e32 v158, 1.0, v158
	v_add_f32_e32 v159, 1.0, v159
	v_rcp_f32_e32 v158, v158
	v_rcp_f32_e32 v159, v159
	s_nop 0
	v_pk_fma_f32 v[156:157], v[158:159], v[160:161], v[156:157]
	v_cvt_pk_bf16_f32 v158, v154, v155
	v_pk_mul_f32 v[154:155], v[154:155], v[154:155]
	v_cvt_pk_bf16_f32 v159, v156, v157
	v_pk_mul_f32 v[156:157], v[156:157], v[156:157]
	v_add_f32_e32 v154, v154, v155
	v_add_f32_e32 v154, v154, v156
	v_add_f32_e32 v154, v157, v154
	v_add_co_u32_e32 v160, vcc, s14, v164
	s_nop 0
	v_add_f32_dpp v154, v154, v154 quad_perm:[1,0,3,2] row_mask:0xf bank_mask:0xf bound_ctrl:1
	v_addc_co_u32_e32 v161, vcc, 0, v165, vcc
	s_nop 0
	v_add_f32_dpp v154, v154, v154 quad_perm:[2,3,0,1] row_mask:0xf bank_mask:0xf bound_ctrl:1
	global_store_dwordx2 v[160:161], v[158:159], off nt
	s_nop 0
	v_add_f32_dpp v154, v154, v154 row_ror:4 row_mask:0xf bank_mask:0xf bound_ctrl:1
	s_nop 1
	v_mov_b32_dpp v155, v154 row_ror:8 row_mask:0xf bank_mask:0xf bound_ctrl:1
	s_and_saveexec_b64 s[4:5], s[0:1]
	s_cbranch_execz .LBB0_699
	v_add_f32_e32 v154, v154, v155
	global_atomic_add_f32 v[162:163], v154, off offset:76
.LBB0_699:
	s_or_b64 exec, exec, s[4:5]
	v_mov_b32_e32 v154, s17
	v_fmamk_f32 v150, v150, 0x3a000000, v154
	v_rsq_f32_e32 v150, v150
	v_add_co_u32_e32 v154, vcc, 0x20000, v170
	s_nop 1
	v_addc_co_u32_e32 v155, vcc, 0, v171, vcc
	global_load_dwordx2 v[154:155], v[154:155], off
	s_waitcnt vmcnt(0)
	v_lshlrev_b32_e32 v196, 16, v154
	v_and_b32_e32 v197, 0xffff0000, v154
	v_add_co_u32_e32 v154, vcc, 0x20000, v168
	v_lshlrev_b32_e32 v198, 16, v155
	v_and_b32_e32 v199, 0xffff0000, v155
	v_addc_co_u32_e32 v155, vcc, 0, v169, vcc
	global_load_dwordx2 v[192:193], v[154:155], off
	v_add_co_u32_e32 v154, vcc, 0x21000, v170
	s_nop 1
	v_addc_co_u32_e32 v155, vcc, 0, v171, vcc
	global_load_dwordx2 v[190:191], v[154:155], off
	v_add_co_u32_e32 v154, vcc, 0x21000, v168
	s_nop 1
	v_addc_co_u32_e32 v155, vcc, 0, v169, vcc
	global_load_dwordx2 v[188:189], v[154:155], off
	v_add_co_u32_e32 v154, vcc, 0x22000, v170
	s_nop 1
	v_addc_co_u32_e32 v155, vcc, 0, v171, vcc
	global_load_dwordx2 v[186:187], v[154:155], off
	v_add_co_u32_e32 v154, vcc, 0x22000, v168
	s_nop 1
	v_addc_co_u32_e32 v155, vcc, 0, v169, vcc
	global_load_dwordx2 v[184:185], v[154:155], off
	v_add_co_u32_e32 v154, vcc, 0x23000, v170
	s_nop 1
	v_addc_co_u32_e32 v155, vcc, 0, v171, vcc
	global_load_dwordx2 v[182:183], v[154:155], off
	v_add_co_u32_e32 v154, vcc, 0x23000, v168
	s_nop 1
	v_addc_co_u32_e32 v155, vcc, 0, v169, vcc
	global_load_dwordx2 v[180:181], v[154:155], off
	v_add_co_u32_e32 v154, vcc, 0x30000, v170
	s_nop 1
	v_addc_co_u32_e32 v155, vcc, 0, v171, vcc
	global_load_dwordx2 v[178:179], v[154:155], off
	v_add_co_u32_e32 v154, vcc, 0x30000, v168
	s_nop 1
	v_addc_co_u32_e32 v155, vcc, 0, v169, vcc
	global_load_dwordx2 v[176:177], v[154:155], off
	v_add_co_u32_e32 v154, vcc, 0x31000, v170
	s_nop 1
	v_addc_co_u32_e32 v155, vcc, 0, v171, vcc
	global_load_dwordx2 v[174:175], v[154:155], off
	v_add_co_u32_e32 v154, vcc, 0x31000, v168
	s_nop 1
	v_addc_co_u32_e32 v155, vcc, 0, v169, vcc
	global_load_dwordx2 v[172:173], v[154:155], off
	v_add_co_u32_e32 v154, vcc, 0x32000, v170
	s_nop 1
	v_addc_co_u32_e32 v155, vcc, 0, v171, vcc
	global_load_dwordx2 v[160:161], v[154:155], off
	v_add_co_u32_e32 v154, vcc, 0x32000, v168
	s_nop 1
	v_addc_co_u32_e32 v155, vcc, 0, v169, vcc
	global_load_dwordx2 v[158:159], v[154:155], off
	v_add_co_u32_e32 v154, vcc, 0x33000, v170
	s_nop 1
	v_addc_co_u32_e32 v155, vcc, 0, v171, vcc
	global_load_dwordx2 v[156:157], v[154:155], off
	v_add_co_u32_e32 v154, vcc, 0x33000, v168
	s_nop 1
	v_addc_co_u32_e32 v155, vcc, 0, v169, vcc
	global_load_dwordx2 v[154:155], v[154:155], off
	v_mul_f32_e64 v194, v82, -v150
	v_mul_f32_e32 v194, 0x3fb8aa3b, v194
	v_exp_f32_e32 v194, v194
	s_waitcnt vmcnt(14)
	v_lshlrev_b32_e32 v195, 16, v192
	v_and_b32_e32 v192, 0xffff0000, v192
	v_add_f32_e32 v194, 1.0, v194
	v_rcp_f32_e32 v194, v194
	s_nop 0
	v_fmac_f32_e32 v196, v194, v195
	v_mul_f32_e64 v194, v86, -v150
	v_mul_f32_e32 v194, 0x3fb8aa3b, v194
	v_exp_f32_e32 v194, v194
	s_nop 0
	v_add_f32_e32 v194, 1.0, v194
	v_rcp_f32_e32 v194, v194
	s_nop 0
	v_fmac_f32_e32 v197, v194, v192
	v_mul_f32_e64 v192, v94, -v150
	v_mul_f32_e32 v192, 0x3fb8aa3b, v192
	v_mul_f32_e64 v150, v90, -v150
	v_exp_f32_e32 v192, v192
	v_mul_f32_e32 v150, 0x3fb8aa3b, v150
	v_exp_f32_e32 v150, v150
	v_lshlrev_b32_e32 v194, 16, v193
	v_add_f32_e32 v192, 1.0, v192
	v_rcp_f32_e32 v192, v192
	v_add_f32_e32 v150, 1.0, v150
	v_rcp_f32_e32 v150, v150
	v_fmac_f32_e32 v198, v192, v194
	v_and_b32_e32 v192, 0xffff0000, v193
	v_fmac_f32_e32 v199, v150, v192
	v_mul_f32_e32 v150, v197, v197
	v_fmac_f32_e32 v150, v196, v196
	v_fmac_f32_e32 v150, v198, v198
	v_fmac_f32_e32 v150, v199, v199
	v_add_co_u32_e32 v194, vcc, s11, v164
	s_nop 0
	v_add_f32_dpp v150, v150, v150 quad_perm:[1,0,3,2] row_mask:0xf bank_mask:0xf bound_ctrl:1
	v_cvt_pk_bf16_f32 v192, v196, v197
	v_cvt_pk_bf16_f32 v193, v198, v199
	v_add_f32_dpp v150, v150, v150 quad_perm:[2,3,0,1] row_mask:0xf bank_mask:0xf bound_ctrl:1
	v_addc_co_u32_e32 v195, vcc, 0, v165, vcc
	s_nop 0
	v_add_f32_dpp v150, v150, v150 row_ror:4 row_mask:0xf bank_mask:0xf bound_ctrl:1
	global_store_dwordx2 v[194:195], v[192:193], off nt
	s_nop 0
	v_mov_b32_dpp v192, v150 row_ror:8 row_mask:0xf bank_mask:0xf bound_ctrl:1
	s_and_saveexec_b64 s[4:5], s[0:1]
	s_cbranch_execz .LBB0_701
	v_add_f32_e32 v150, v150, v192
	global_atomic_add_f32 v[162:163], v150, off offset:128
; __device__ __forceinline__ float fdiv(float a, float b) { return a * __builtin_amdgcn_rcpf(b); }
; __device__ __forceinline__ float bf2f(u16 h) { return __uint_as_float(((unsigned)h) << 16); }
; __device__ __forceinline__ void gemm_tile(const Params& P, const GArgs& ga, const TileDesc& td, int wid_s) {
;     ...
;       static_for<8>([&](auto ic2) __attribute__((always_inline)) {
;         constexpr int idx = b0 + decltype(ic2)::v; constexpr int ai = idx >> 4, m = (idx >> 2) & 3, j = idx & 3;
;         constexpr int rl = ai * HALF + m * 16 + j; constexpr int q = decltype(ic2)::v;
;         const float rs = rsv[idx];
;         float4 v;
;         v.x = r[q].x + fdiv(1.f, 1.f + __expf(-rs * acc[ai][0][m][0][j])) * bf2f((u16)(pe[q].x & 0xffff));
;         v.y = r[q].y + fdiv(1.f, 1.f + __expf(-rs * acc[ai][0][m][1][j])) * bf2f((u16)(pe[q].x >> 16));
;         v.z = r[q].z + fdiv(1.f, 1.f + __expf(-rs * acc[ai][1][m][0][j])) * bf2f((u16)(pe[q].y & 0xffff));
;         v.w = r[q].w + fdiv(1.f, 1.f + __expf(-rs * acc[ai][1][m][1][j])) * bf2f((u16)(pe[q].y >> 16));
;         uint2 o; o.x = pack2(v.x, v.y); o.y = pack2(v.z, v.w);
;         *reinterpret_cast<uint2*>(h4b + (size_t)rl * DM) = o;
;         float s = red16(v.x * v.x + v.y * v.y + v.z * v.z + v.w * v.w);
;         if (efr == 0) unsafeAtomicAdd(sso + rl, s);
;       });
.LBB0_701:
	s_or_b64 exec, exec, s[4:5]
	v_mov_b32_e32 v150, s17
	v_fmamk_f32 v150, v151, 0x3a000000, v150
	v_rsq_f32_e32 v196, v150
	s_waitcnt vmcnt(14)
	v_lshlrev_b32_e32 v192, 16, v190
	v_and_b32_e32 v193, 0xffff0000, v190
	s_waitcnt vmcnt(13)
	v_lshlrev_b32_e32 v194, 16, v188
	v_mul_f32_e64 v150, v83, -v196
	v_mul_f32_e64 v151, v87, -v196
	v_mul_f32_e32 v150, 0x3fb8aa3b, v150
	v_mul_f32_e32 v151, 0x3fb8aa3b, v151
	v_exp_f32_e32 v150, v150
	v_exp_f32_e32 v151, v151
	v_and_b32_e32 v195, 0xffff0000, v188
	v_mul_f32_e64 v188, v95, -v196
	v_add_f32_e32 v150, 1.0, v150
	v_add_f32_e32 v151, 1.0, v151
	v_rcp_f32_e32 v150, v150
	v_rcp_f32_e32 v151, v151
	v_mul_f32_e32 v188, 0x3fb8aa3b, v188
	v_exp_f32_e32 v188, v188
	v_lshlrev_b32_e32 v190, 16, v191
	v_pk_fma_f32 v[150:151], v[150:151], v[194:195], v[192:193]
	v_mul_f32_e64 v193, v91, -v196
	v_mul_f32_e32 v193, 0x3fb8aa3b, v193
	v_exp_f32_e32 v193, v193
	v_add_f32_e32 v188, 1.0, v188
	v_rcp_f32_e32 v192, v188
	v_and_b32_e32 v191, 0xffff0000, v191
	v_add_f32_e32 v193, 1.0, v193
	v_rcp_f32_e32 v193, v193
	v_lshlrev_b32_e32 v188, 16, v189
	v_and_b32_e32 v189, 0xffff0000, v189
	s_mov_b32 s4, 0x21000
	v_pk_fma_f32 v[188:189], v[192:193], v[188:189], v[190:191]
	v_cvt_pk_bf16_f32 v190, v150, v151
	v_pk_mul_f32 v[150:151], v[150:151], v[150:151]
	v_cvt_pk_bf16_f32 v191, v188, v189
	v_pk_mul_f32 v[188:189], v[188:189], v[188:189]
	v_add_f32_e32 v150, v150, v151
	v_add_f32_e32 v150, v150, v188
	v_add_f32_e32 v150, v189, v150
	v_add_co_u32_e32 v192, vcc, s4, v164
	s_nop 0
	v_add_f32_dpp v150, v150, v150 quad_perm:[1,0,3,2] row_mask:0xf bank_mask:0xf bound_ctrl:1
	v_addc_co_u32_e32 v193, vcc, 0, v165, vcc
	s_nop 0
	v_add_f32_dpp v150, v150, v150 quad_perm:[2,3,0,1] row_mask:0xf bank_mask:0xf bound_ctrl:1
	global_store_dwordx2 v[192:193], v[190:191], off nt
	s_nop 0
	v_add_f32_dpp v150, v150, v150 row_ror:4 row_mask:0xf bank_mask:0xf bound_ctrl:1
	s_nop 1
	v_mov_b32_dpp v151, v150 row_ror:8 row_mask:0xf bank_mask:0xf bound_ctrl:1
	s_and_saveexec_b64 s[4:5], s[0:1]
	s_cbranch_execz .LBB0_703
	v_add_f32_e32 v150, v150, v151
	global_atomic_add_f32 v[162:163], v150, off offset:132
.LBB0_703:
	s_or_b64 exec, exec, s[4:5]
	v_mov_b32_e32 v188, s17
	v_fmamk_f32 v152, v152, 0x3a000000, v188
	v_rsq_f32_e32 v152, v152
	s_waitcnt vmcnt(12)
	v_lshlrev_b32_e32 v190, 16, v184
	v_and_b32_e32 v191, 0xffff0000, v184
	v_lshlrev_b32_e32 v150, 16, v186
	v_mul_f32_e64 v188, v84, -v152
	v_mul_f32_e64 v189, v88, -v152
	v_mul_f32_e32 v188, 0x3fb8aa3b, v188
	v_mul_f32_e32 v189, 0x3fb8aa3b, v189
	v_exp_f32_e32 v188, v188
	v_exp_f32_e32 v189, v189
	v_mul_f32_e64 v184, v96, -v152
	v_mul_f32_e64 v152, v92, -v152
	v_mul_f32_e32 v184, 0x3fb8aa3b, v184
	v_mul_f32_e32 v152, 0x3fb8aa3b, v152
	v_add_f32_e32 v188, 1.0, v188
	v_add_f32_e32 v189, 1.0, v189
	v_exp_f32_e32 v184, v184
	v_exp_f32_e32 v152, v152
	v_rcp_f32_e32 v188, v188
	v_rcp_f32_e32 v189, v189
	v_and_b32_e32 v151, 0xffff0000, v186
	v_add_f32_e32 v184, 1.0, v184
	v_add_f32_e32 v152, 1.0, v152
	v_pk_fma_f32 v[150:151], v[188:189], v[190:191], v[150:151]
	v_rcp_f32_e32 v188, v184
	v_rcp_f32_e32 v189, v152
	v_lshlrev_b32_e32 v186, 16, v187
	v_and_b32_e32 v187, 0xffff0000, v187
	v_lshlrev_b32_e32 v184, 16, v185
	v_and_b32_e32 v185, 0xffff0000, v185
	v_pk_fma_f32 v[184:185], v[188:189], v[184:185], v[186:187]
	v_cvt_pk_bf16_f32 v186, v150, v151
	v_pk_mul_f32 v[150:151], v[150:151], v[150:151]
	v_cvt_pk_bf16_f32 v187, v184, v185
	v_pk_mul_f32 v[184:185], v[184:185], v[184:185]
	v_add_f32_e32 v150, v150, v151
	v_add_f32_e32 v150, v150, v184
	v_add_f32_e32 v150, v185, v150
	s_mov_b32 s4, 0x22000
	v_add_co_u32_e32 v188, vcc, s4, v164
	v_add_f32_dpp v150, v150, v150 quad_perm:[1,0,3,2] row_mask:0xf bank_mask:0xf bound_ctrl:1
	s_nop 0
	v_addc_co_u32_e32 v189, vcc, 0, v165, vcc
	v_add_f32_dpp v150, v150, v150 quad_perm:[2,3,0,1] row_mask:0xf bank_mask:0xf bound_ctrl:1
	global_store_dwordx2 v[188:189], v[186:187], off nt
	s_nop 0
	v_add_f32_dpp v150, v150, v150 row_ror:4 row_mask:0xf bank_mask:0xf bound_ctrl:1
	s_nop 1
	v_mov_b32_dpp v151, v150 row_ror:8 row_mask:0xf bank_mask:0xf bound_ctrl:1
	s_and_saveexec_b64 s[4:5], s[0:1]
	s_cbranch_execz .LBB0_705
	v_add_f32_e32 v150, v150, v151
	global_atomic_add_f32 v[162:163], v150, off offset:136
.LBB0_705:
	s_or_b64 exec, exec, s[4:5]
	v_mov_b32_e32 v152, s17
	v_fmamk_f32 v152, v153, 0x3a000000, v152
	v_rsq_f32_e32 v186, v152
	s_waitcnt vmcnt(12)
	v_lshlrev_b32_e32 v150, 16, v182
	v_and_b32_e32 v151, 0xffff0000, v182
	s_waitcnt vmcnt(11)
	v_lshlrev_b32_e32 v184, 16, v180
	v_mul_f32_e64 v152, v85, -v186
	v_mul_f32_e64 v153, v89, -v186
	v_mul_f32_e32 v152, 0x3fb8aa3b, v152
	v_mul_f32_e32 v153, 0x3fb8aa3b, v153
	v_exp_f32_e32 v152, v152
	v_exp_f32_e32 v153, v153
	v_and_b32_e32 v185, 0xffff0000, v180
	v_lshlrev_b32_e32 v182, 16, v183
	v_add_f32_e32 v152, 1.0, v152
	v_add_f32_e32 v153, 1.0, v153
	v_rcp_f32_e32 v152, v152
	v_rcp_f32_e32 v153, v153
	v_and_b32_e32 v183, 0xffff0000, v183
	v_lshlrev_b32_e32 v180, 16, v181
	v_and_b32_e32 v181, 0xffff0000, v181
	v_pk_fma_f32 v[150:151], v[152:153], v[184:185], v[150:151]
	v_mul_f32_e64 v152, v97, -v186
	v_mul_f32_e64 v153, v93, -v186
	v_mul_f32_e32 v152, 0x3fb8aa3b, v152
	v_mul_f32_e32 v153, 0x3fb8aa3b, v153
	v_exp_f32_e32 v152, v152
	v_exp_f32_e32 v153, v153
	s_mov_b32 s4, 0x23000
	v_add_f32_e32 v152, 1.0, v152
	v_add_f32_e32 v153, 1.0, v153
	v_rcp_f32_e32 v152, v152
	v_rcp_f32_e32 v153, v153
	s_nop 0
	v_pk_fma_f32 v[152:153], v[152:153], v[180:181], v[182:183]
	v_cvt_pk_bf16_f32 v180, v150, v151
	v_pk_mul_f32 v[150:151], v[150:151], v[150:151]
	v_cvt_pk_bf16_f32 v181, v152, v153
	v_pk_mul_f32 v[152:153], v[152:153], v[152:153]
	v_add_f32_e32 v150, v150, v151
	v_add_f32_e32 v150, v150, v152
	v_add_f32_e32 v150, v153, v150
	v_add_co_u32_e32 v182, vcc, s4, v164
	s_nop 0
	v_add_f32_dpp v150, v150, v150 quad_perm:[1,0,3,2] row_mask:0xf bank_mask:0xf bound_ctrl:1
	v_addc_co_u32_e32 v183, vcc, 0, v165, vcc
	s_nop 0
	v_add_f32_dpp v150, v150, v150 quad_perm:[2,3,0,1] row_mask:0xf bank_mask:0xf bound_ctrl:1
	global_store_dwordx2 v[182:183], v[180:181], off nt
	s_nop 0
	v_add_f32_dpp v150, v150, v150 row_ror:4 row_mask:0xf bank_mask:0xf bound_ctrl:1
	s_nop 1
	v_mov_b32_dpp v151, v150 row_ror:8 row_mask:0xf bank_mask:0xf bound_ctrl:1
	s_and_saveexec_b64 s[4:5], s[0:1]
	s_cbranch_execz .LBB0_707
	v_add_f32_e32 v150, v150, v151
	global_atomic_add_f32 v[162:163], v150, off offset:140
; __device__ __forceinline__ float fdiv(float a, float b) { return a * __builtin_amdgcn_rcpf(b); }
; __device__ __forceinline__ float bf2f(u16 h) { return __uint_as_float(((unsigned)h) << 16); }
; __device__ __forceinline__ void gemm_tile(const Params& P, const GArgs& ga, const TileDesc& td, int wid_s) {
;     ...
;       static_for<8>([&](auto ic2) __attribute__((always_inline)) {
;         constexpr int idx = b0 + decltype(ic2)::v; constexpr int ai = idx >> 4, m = (idx >> 2) & 3, j = idx & 3;
;         constexpr int rl = ai * HALF + m * 16 + j; constexpr int q = decltype(ic2)::v;
;         const float rs = rsv[idx];
;         float4 v;
;         v.x = r[q].x + fdiv(1.f, 1.f + __expf(-rs * acc[ai][0][m][0][j])) * bf2f((u16)(pe[q].x & 0xffff));
;         v.y = r[q].y + fdiv(1.f, 1.f + __expf(-rs * acc[ai][0][m][1][j])) * bf2f((u16)(pe[q].x >> 16));
;         v.z = r[q].z + fdiv(1.f, 1.f + __expf(-rs * acc[ai][1][m][0][j])) * bf2f((u16)(pe[q].y & 0xffff));
;         v.w = r[q].w + fdiv(1.f, 1.f + __expf(-rs * acc[ai][1][m][1][j])) * bf2f((u16)(pe[q].y >> 16));
;         uint2 o; o.x = pack2(v.x, v.y); o.y = pack2(v.z, v.w);
;         *reinterpret_cast<uint2*>(h4b + (size_t)rl * DM) = o;
;         float s = red16(v.x * v.x + v.y * v.y + v.z * v.z + v.w * v.w);
;         if (efr == 0) unsafeAtomicAdd(sso + rl, s);
;       });
.LBB0_707:
	s_or_b64 exec, exec, s[4:5]
	s_waitcnt vmcnt(11)
	v_lshlrev_b32_e32 v150, 16, v178
	v_and_b32_e32 v151, 0xffff0000, v178
	v_mov_b32_e32 v178, s17
	v_fmamk_f32 v146, v146, 0x3a000000, v178
	v_rsq_f32_e32 v146, v146
	v_lshlrev_b32_e32 v152, 16, v179
	v_and_b32_e32 v153, 0xffff0000, v179
	s_waitcnt vmcnt(10)
	v_lshlrev_b32_e32 v180, 16, v176
	v_mul_f32_e64 v178, v66, -v146
	v_mul_f32_e64 v179, v70, -v146
	v_mul_f32_e32 v178, 0x3fb8aa3b, v178
	v_mul_f32_e32 v179, 0x3fb8aa3b, v179
	v_exp_f32_e32 v178, v178
	v_exp_f32_e32 v179, v179
	v_and_b32_e32 v181, 0xffff0000, v176
	v_mul_f32_e64 v176, v78, -v146
	v_mul_f32_e64 v146, v74, -v146
	v_mul_f32_e32 v176, 0x3fb8aa3b, v176
	v_mul_f32_e32 v146, 0x3fb8aa3b, v146
	v_add_f32_e32 v178, 1.0, v178
	v_add_f32_e32 v179, 1.0, v179
	v_exp_f32_e32 v176, v176
	v_exp_f32_e32 v146, v146
	v_rcp_f32_e32 v178, v178
	v_rcp_f32_e32 v179, v179
	v_add_f32_e32 v176, 1.0, v176
	v_add_f32_e32 v146, 1.0, v146
	s_mov_b32 s4, 0x30000
	v_pk_fma_f32 v[150:151], v[178:179], v[180:181], v[150:151]
	v_rcp_f32_e32 v178, v176
	v_rcp_f32_e32 v179, v146
	v_lshlrev_b32_e32 v176, 16, v177
	v_and_b32_e32 v177, 0xffff0000, v177
	v_pk_fma_f32 v[152:153], v[178:179], v[176:177], v[152:153]
	v_cvt_pk_bf16_f32 v176, v150, v151
	v_pk_mul_f32 v[150:151], v[150:151], v[150:151]
	v_cvt_pk_bf16_f32 v177, v152, v153
	v_pk_mul_f32 v[152:153], v[152:153], v[152:153]
	v_add_f32_e32 v146, v150, v151
	v_add_f32_e32 v146, v146, v152
	v_add_f32_e32 v146, v153, v146
	v_add_co_u32_e32 v178, vcc, s4, v164
	s_nop 0
	v_add_f32_dpp v146, v146, v146 quad_perm:[1,0,3,2] row_mask:0xf bank_mask:0xf bound_ctrl:1
	v_addc_co_u32_e32 v179, vcc, 0, v165, vcc
	s_nop 0
	v_add_f32_dpp v146, v146, v146 quad_perm:[2,3,0,1] row_mask:0xf bank_mask:0xf bound_ctrl:1
	global_store_dwordx2 v[178:179], v[176:177], off nt
	s_nop 0
	v_add_f32_dpp v146, v146, v146 row_ror:4 row_mask:0xf bank_mask:0xf bound_ctrl:1
	s_nop 1
	v_mov_b32_dpp v150, v146 row_ror:8 row_mask:0xf bank_mask:0xf bound_ctrl:1
	s_and_saveexec_b64 s[4:5], s[0:1]
	s_cbranch_execz .LBB0_709
	v_add_f32_e32 v146, v146, v150
	global_atomic_add_f32 v[162:163], v146, off offset:192
.LBB0_709:
	s_or_b64 exec, exec, s[4:5]
	v_mov_b32_e32 v146, s17
	v_fmamk_f32 v146, v147, 0x3a000000, v146
	v_rsq_f32_e32 v176, v146
	s_waitcnt vmcnt(10)
	v_lshlrev_b32_e32 v150, 16, v174
	v_and_b32_e32 v151, 0xffff0000, v174
	v_lshlrev_b32_e32 v152, 16, v175
	v_mul_f32_e64 v146, v67, -v176
	v_mul_f32_e64 v147, v71, -v176
	v_mul_f32_e32 v146, 0x3fb8aa3b, v146
	v_mul_f32_e32 v147, 0x3fb8aa3b, v147
	v_exp_f32_e32 v146, v146
	v_exp_f32_e32 v147, v147
	v_and_b32_e32 v153, 0xffff0000, v175
	s_waitcnt vmcnt(9)
	v_lshlrev_b32_e32 v174, 16, v172
	v_add_f32_e32 v146, 1.0, v146
	v_add_f32_e32 v147, 1.0, v147
	v_rcp_f32_e32 v146, v146
	v_rcp_f32_e32 v147, v147
	v_and_b32_e32 v175, 0xffff0000, v172
	v_lshlrev_b32_e32 v172, 16, v173
	v_and_b32_e32 v173, 0xffff0000, v173
	v_pk_fma_f32 v[146:147], v[146:147], v[174:175], v[150:151]
	v_mul_f32_e64 v150, v79, -v176
	v_mul_f32_e64 v151, v75, -v176
	v_mul_f32_e32 v150, 0x3fb8aa3b, v150
	v_mul_f32_e32 v151, 0x3fb8aa3b, v151
	v_exp_f32_e32 v150, v150
	v_exp_f32_e32 v151, v151
	v_add_f32_e32 v150, 1.0, v150
	v_add_f32_e32 v151, 1.0, v151
	v_rcp_f32_e32 v150, v150
	v_rcp_f32_e32 v151, v151
	s_nop 0
	v_pk_fma_f32 v[150:151], v[150:151], v[172:173], v[152:153]
	v_cvt_pk_bf16_f32 v152, v146, v147
	v_pk_mul_f32 v[146:147], v[146:147], v[146:147]
	v_cvt_pk_bf16_f32 v153, v150, v151
	v_pk_mul_f32 v[150:151], v[150:151], v[150:151]
	v_add_f32_e32 v146, v146, v147
	v_add_f32_e32 v146, v146, v150
	v_add_f32_e32 v146, v151, v146
	v_add_co_u32_e32 v172, vcc, s19, v164
	s_nop 0
	v_add_f32_dpp v146, v146, v146 quad_perm:[1,0,3,2] row_mask:0xf bank_mask:0xf bound_ctrl:1
	v_addc_co_u32_e32 v173, vcc, 0, v165, vcc
	s_nop 0
	v_add_f32_dpp v146, v146, v146 quad_perm:[2,3,0,1] row_mask:0xf bank_mask:0xf bound_ctrl:1
	global_store_dwordx2 v[172:173], v[152:153], off nt
	s_nop 0
	v_add_f32_dpp v146, v146, v146 row_ror:4 row_mask:0xf bank_mask:0xf bound_ctrl:1
	s_nop 1
	v_mov_b32_dpp v147, v146 row_ror:8 row_mask:0xf bank_mask:0xf bound_ctrl:1
	s_and_saveexec_b64 s[4:5], s[0:1]
	s_cbranch_execz .LBB0_711
	v_add_f32_e32 v146, v146, v147
	global_atomic_add_f32 v[162:163], v146, off offset:196
.LBB0_711:
	s_or_b64 exec, exec, s[4:5]
	v_mov_b32_e32 v152, s17
	v_fmamk_f32 v148, v148, 0x3a000000, v152
	v_rsq_f32_e32 v148, v148
	s_waitcnt vmcnt(9)
	v_lshlrev_b32_e32 v146, 16, v160
	v_and_b32_e32 v147, 0xffff0000, v160
	v_lshlrev_b32_e32 v150, 16, v161
	v_mul_f32_e64 v152, v68, -v148
	v_mul_f32_e64 v153, v72, -v148
	v_mul_f32_e32 v152, 0x3fb8aa3b, v152
	v_mul_f32_e32 v153, 0x3fb8aa3b, v153
	v_exp_f32_e32 v152, v152
	v_exp_f32_e32 v153, v153
	v_and_b32_e32 v151, 0xffff0000, v161
	s_waitcnt vmcnt(8)
	v_lshlrev_b32_e32 v160, 16, v158
	v_add_f32_e32 v152, 1.0, v152
	v_add_f32_e32 v153, 1.0, v153
	v_rcp_f32_e32 v152, v152
	v_rcp_f32_e32 v153, v153
	v_and_b32_e32 v161, 0xffff0000, v158
	v_lshlrev_b32_e32 v158, 16, v159
	v_and_b32_e32 v159, 0xffff0000, v159
	v_pk_fma_f32 v[146:147], v[152:153], v[160:161], v[146:147]
	v_mul_f32_e64 v152, v80, -v148
	v_mul_f32_e64 v148, v76, -v148
	v_mul_f32_e32 v152, 0x3fb8aa3b, v152
	v_mul_f32_e32 v148, 0x3fb8aa3b, v148
	v_exp_f32_e32 v152, v152
	v_exp_f32_e32 v148, v148
	s_mov_b32 s4, 0x32000
	v_add_f32_e32 v152, 1.0, v152
	v_add_f32_e32 v148, 1.0, v148
	v_rcp_f32_e32 v152, v152
	v_rcp_f32_e32 v153, v148
	s_nop 0
	v_pk_fma_f32 v[150:151], v[152:153], v[158:159], v[150:151]
	v_cvt_pk_bf16_f32 v152, v146, v147
	v_pk_mul_f32 v[146:147], v[146:147], v[146:147]
	v_cvt_pk_bf16_f32 v153, v150, v151
	v_pk_mul_f32 v[150:151], v[150:151], v[150:151]
	v_add_f32_e32 v146, v146, v147
	v_add_f32_e32 v146, v146, v150
	v_add_f32_e32 v146, v151, v146
	v_add_co_u32_e32 v158, vcc, s4, v164
	s_nop 0
	v_add_f32_dpp v146, v146, v146 quad_perm:[1,0,3,2] row_mask:0xf bank_mask:0xf bound_ctrl:1
	v_addc_co_u32_e32 v159, vcc, 0, v165, vcc
	s_nop 0
	v_add_f32_dpp v146, v146, v146 quad_perm:[2,3,0,1] row_mask:0xf bank_mask:0xf bound_ctrl:1
	global_store_dwordx2 v[158:159], v[152:153], off nt
	s_nop 0
	v_add_f32_dpp v146, v146, v146 row_ror:4 row_mask:0xf bank_mask:0xf bound_ctrl:1
	s_nop 1
	v_mov_b32_dpp v147, v146 row_ror:8 row_mask:0xf bank_mask:0xf bound_ctrl:1
	s_and_saveexec_b64 s[4:5], s[0:1]
	s_cbranch_execz .LBB0_713
	v_add_f32_e32 v146, v146, v147
	global_atomic_add_f32 v[162:163], v146, off offset:200
; __device__ __forceinline__ float fdiv(float a, float b) { return a * __builtin_amdgcn_rcpf(b); }
; __device__ __forceinline__ float bf2f(u16 h) { return __uint_as_float(((unsigned)h) << 16); }
; __device__ __forceinline__ void gemm_tile(const Params& P, const GArgs& ga, const TileDesc& td, int wid_s) {
;     ...
;       static_for<8>([&](auto ic2) __attribute__((always_inline)) {
;         constexpr int idx = b0 + decltype(ic2)::v; constexpr int ai = idx >> 4, m = (idx >> 2) & 3, j = idx & 3;
;         constexpr int rl = ai * HALF + m * 16 + j; constexpr int q = decltype(ic2)::v;
;         const uint2 t = *reinterpret_cast<const uint2*>(h3b + (size_t)rl * DM);
;         r[q] = make_float4(__uint_as_float(t.x << 16), __uint_as_float(t.x & 0xffff0000u),
;                            __uint_as_float(t.y << 16), __uint_as_float(t.y & 0xffff0000u));
;         pe[q] = *reinterpret_cast<const uint2*>(pd + (size_t)rl * DM);
;       });
;       __builtin_amdgcn_sched_barrier(0);
;       static_for<8>([&](auto ic2) __attribute__((always_inline)) {
;         constexpr int idx = b0 + decltype(ic2)::v; constexpr int ai = idx >> 4, m = (idx >> 2) & 3, j = idx & 3;
;         constexpr int rl = ai * HALF + m * 16 + j; constexpr int q = decltype(ic2)::v;
;         const float rs = rsv[idx];
;         float4 v;
;         v.x = r[q].x + fdiv(1.f, 1.f + __expf(-rs * acc[ai][0][m][0][j])) * bf2f((u16)(pe[q].x & 0xffff));
;         v.y = r[q].y + fdiv(1.f, 1.f + __expf(-rs * acc[ai][0][m][1][j])) * bf2f((u16)(pe[q].x >> 16));
;         v.z = r[q].z + fdiv(1.f, 1.f + __expf(-rs * acc[ai][1][m][0][j])) * bf2f((u16)(pe[q].y & 0xffff));
;         v.w = r[q].w + fdiv(1.f, 1.f + __expf(-rs * acc[ai][1][m][1][j])) * bf2f((u16)(pe[q].y >> 16));
;         uint2 o; o.x = pack2(v.x, v.y); o.y = pack2(v.z, v.w);
;         *reinterpret_cast<uint2*>(h4b + (size_t)rl * DM) = o;
;         float s = red16(v.x * v.x + v.y * v.y + v.z * v.z + v.w * v.w);
;         if (efr == 0) unsafeAtomicAdd(sso + rl, s);
;       });
.LBB0_713:
	s_or_b64 exec, exec, s[4:5]
	v_mov_b32_e32 v148, s17
	v_fmamk_f32 v148, v149, 0x3a000000, v148
	s_waitcnt vmcnt(8)
	v_lshlrev_b32_e32 v146, 16, v156
	v_and_b32_e32 v147, 0xffff0000, v156
	v_rsq_f32_e32 v156, v148
	s_waitcnt vmcnt(7)
	v_lshlrev_b32_e32 v152, 16, v154
	v_and_b32_e32 v153, 0xffff0000, v154
	v_lshlrev_b32_e32 v150, 16, v157
	v_mul_f32_e64 v148, v69, -v156
	v_mul_f32_e64 v149, v73, -v156
	v_mul_f32_e32 v148, 0x3fb8aa3b, v148
	v_mul_f32_e32 v149, 0x3fb8aa3b, v149
	v_exp_f32_e32 v148, v148
	v_exp_f32_e32 v149, v149
	v_and_b32_e32 v151, 0xffff0000, v157
	s_mov_b32 s4, 0x33000
	v_add_f32_e32 v148, 1.0, v148
	v_add_f32_e32 v149, 1.0, v149
	v_rcp_f32_e32 v148, v148
	v_rcp_f32_e32 v149, v149
	s_nop 0
	v_pk_fma_f32 v[146:147], v[148:149], v[152:153], v[146:147]
	v_mul_f32_e64 v148, v81, -v156
	v_mul_f32_e64 v149, v77, -v156
	v_mul_f32_e32 v148, 0x3fb8aa3b, v148
	v_mul_f32_e32 v149, 0x3fb8aa3b, v149
	v_exp_f32_e32 v148, v148
	v_exp_f32_e32 v149, v149
	v_lshlrev_b32_e32 v152, 16, v155
	v_and_b32_e32 v153, 0xffff0000, v155
	v_add_f32_e32 v148, 1.0, v148
	v_add_f32_e32 v149, 1.0, v149
	v_rcp_f32_e32 v148, v148
	v_rcp_f32_e32 v149, v149
	s_nop 0
	v_pk_fma_f32 v[148:149], v[148:149], v[152:153], v[150:151]
	v_cvt_pk_bf16_f32 v150, v146, v147
	v_pk_mul_f32 v[146:147], v[146:147], v[146:147]
	v_cvt_pk_bf16_f32 v151, v148, v149
	v_pk_mul_f32 v[148:149], v[148:149], v[148:149]
	v_add_f32_e32 v146, v146, v147
	v_add_f32_e32 v146, v146, v148
	v_add_f32_e32 v146, v149, v146
	v_add_co_u32_e32 v152, vcc, s4, v164
	s_nop 0
	v_add_f32_dpp v146, v146, v146 quad_perm:[1,0,3,2] row_mask:0xf bank_mask:0xf bound_ctrl:1
	v_addc_co_u32_e32 v153, vcc, 0, v165, vcc
	s_nop 0
	v_add_f32_dpp v146, v146, v146 quad_perm:[2,3,0,1] row_mask:0xf bank_mask:0xf bound_ctrl:1
	global_store_dwordx2 v[152:153], v[150:151], off nt
	s_nop 0
	v_add_f32_dpp v146, v146, v146 row_ror:4 row_mask:0xf bank_mask:0xf bound_ctrl:1
	s_nop 1
	v_mov_b32_dpp v147, v146 row_ror:8 row_mask:0xf bank_mask:0xf bound_ctrl:1
	s_and_saveexec_b64 s[4:5], s[0:1]
	s_cbranch_execz .LBB0_715
	v_add_f32_e32 v146, v146, v147
	global_atomic_add_f32 v[162:163], v146, off offset:204
.LBB0_715:
	s_or_b64 exec, exec, s[4:5]
	v_mov_b32_e32 v146, s17
	v_fmamk_f32 v142, v142, 0x3a000000, v146
	v_rsq_f32_e32 v142, v142
	v_add_co_u32_e32 v146, vcc, 0x80000, v170
	s_nop 1
	v_addc_co_u32_e32 v147, vcc, 0, v171, vcc
	global_load_dwordx2 v[146:147], v[146:147], off
	s_waitcnt vmcnt(0)
	v_lshlrev_b32_e32 v188, 16, v146
	v_and_b32_e32 v189, 0xffff0000, v146
	v_add_co_u32_e32 v146, vcc, 0x80000, v168
	v_lshlrev_b32_e32 v190, 16, v147
	v_and_b32_e32 v191, 0xffff0000, v147
	v_addc_co_u32_e32 v147, vcc, 0, v169, vcc
	global_load_dwordx2 v[184:185], v[146:147], off
	v_add_co_u32_e32 v146, vcc, 0x81000, v170
	s_nop 1
	v_addc_co_u32_e32 v147, vcc, 0, v171, vcc
	global_load_dwordx2 v[182:183], v[146:147], off
	v_add_co_u32_e32 v146, vcc, 0x81000, v168
	s_nop 1
	v_addc_co_u32_e32 v147, vcc, 0, v169, vcc
	global_load_dwordx2 v[180:181], v[146:147], off
	v_add_co_u32_e32 v146, vcc, 0x82000, v170
	s_nop 1
	v_addc_co_u32_e32 v147, vcc, 0, v171, vcc
	global_load_dwordx2 v[178:179], v[146:147], off
	v_add_co_u32_e32 v146, vcc, 0x82000, v168
	s_nop 1
	v_addc_co_u32_e32 v147, vcc, 0, v169, vcc
	global_load_dwordx2 v[176:177], v[146:147], off
	v_add_co_u32_e32 v146, vcc, 0x83000, v170
	s_nop 1
	v_addc_co_u32_e32 v147, vcc, 0, v171, vcc
	global_load_dwordx2 v[174:175], v[146:147], off
	v_add_co_u32_e32 v146, vcc, 0x83000, v168
	s_nop 1
	v_addc_co_u32_e32 v147, vcc, 0, v169, vcc
	global_load_dwordx2 v[172:173], v[146:147], off
	v_add_co_u32_e32 v146, vcc, 0x90000, v170
	s_nop 1
	v_addc_co_u32_e32 v147, vcc, 0, v171, vcc
	global_load_dwordx2 v[160:161], v[146:147], off
	v_add_co_u32_e32 v146, vcc, 0x90000, v168
	s_nop 1
	v_addc_co_u32_e32 v147, vcc, 0, v169, vcc
	global_load_dwordx2 v[158:159], v[146:147], off
	v_add_co_u32_e32 v146, vcc, 0x91000, v170
	s_nop 1
	v_addc_co_u32_e32 v147, vcc, 0, v171, vcc
	global_load_dwordx2 v[156:157], v[146:147], off
	v_add_co_u32_e32 v146, vcc, 0x91000, v168
	s_nop 1
	v_addc_co_u32_e32 v147, vcc, 0, v169, vcc
	global_load_dwordx2 v[154:155], v[146:147], off
	v_add_co_u32_e32 v146, vcc, 0x92000, v170
	s_nop 1
	v_addc_co_u32_e32 v147, vcc, 0, v171, vcc
	global_load_dwordx2 v[152:153], v[146:147], off
	v_add_co_u32_e32 v146, vcc, 0x92000, v168
	s_nop 1
	v_addc_co_u32_e32 v147, vcc, 0, v169, vcc
	global_load_dwordx2 v[150:151], v[146:147], off
	v_add_co_u32_e32 v146, vcc, 0x93000, v170
	s_nop 1
	v_addc_co_u32_e32 v147, vcc, 0, v171, vcc
	global_load_dwordx2 v[148:149], v[146:147], off
	v_add_co_u32_e32 v146, vcc, 0x93000, v168
	s_nop 1
	v_addc_co_u32_e32 v147, vcc, 0, v169, vcc
	global_load_dwordx2 v[146:147], v[146:147], off
	v_mul_f32_e64 v186, v50, -v142
	v_mul_f32_e32 v186, 0x3fb8aa3b, v186
	v_exp_f32_e32 v186, v186
	s_waitcnt vmcnt(14)
	v_lshlrev_b32_e32 v187, 16, v184
	v_and_b32_e32 v184, 0xffff0000, v184
	s_mov_b32 s4, 0x80000
	v_add_f32_e32 v186, 1.0, v186
	v_rcp_f32_e32 v186, v186
	s_nop 0
	v_fmac_f32_e32 v188, v186, v187
	v_mul_f32_e64 v186, v54, -v142
	v_mul_f32_e32 v186, 0x3fb8aa3b, v186
	v_exp_f32_e32 v186, v186
	s_nop 0
	v_add_f32_e32 v186, 1.0, v186
	v_rcp_f32_e32 v186, v186
	s_nop 0
	v_fmac_f32_e32 v189, v186, v184
	v_mul_f32_e64 v184, v62, -v142
	v_mul_f32_e32 v184, 0x3fb8aa3b, v184
	v_mul_f32_e64 v142, v58, -v142
	v_exp_f32_e32 v184, v184
	v_mul_f32_e32 v142, 0x3fb8aa3b, v142
	v_exp_f32_e32 v142, v142
	v_lshlrev_b32_e32 v186, 16, v185
	v_add_f32_e32 v184, 1.0, v184
	v_rcp_f32_e32 v184, v184
	v_add_f32_e32 v142, 1.0, v142
	v_rcp_f32_e32 v142, v142
	v_fmac_f32_e32 v190, v184, v186
	v_and_b32_e32 v184, 0xffff0000, v185
	v_fmac_f32_e32 v191, v142, v184
	v_mul_f32_e32 v142, v189, v189
	v_fmac_f32_e32 v142, v188, v188
	v_fmac_f32_e32 v142, v190, v190
	v_fmac_f32_e32 v142, v191, v191
	v_add_co_u32_e32 v186, vcc, s4, v164
	s_nop 0
	v_add_f32_dpp v142, v142, v142 quad_perm:[1,0,3,2] row_mask:0xf bank_mask:0xf bound_ctrl:1
	v_cvt_pk_bf16_f32 v184, v188, v189
	v_cvt_pk_bf16_f32 v185, v190, v191
	v_add_f32_dpp v142, v142, v142 quad_perm:[2,3,0,1] row_mask:0xf bank_mask:0xf bound_ctrl:1
	v_addc_co_u32_e32 v187, vcc, 0, v165, vcc
	s_nop 0
	v_add_f32_dpp v142, v142, v142 row_ror:4 row_mask:0xf bank_mask:0xf bound_ctrl:1
	global_store_dwordx2 v[186:187], v[184:185], off nt
	s_nop 0
	v_mov_b32_dpp v184, v142 row_ror:8 row_mask:0xf bank_mask:0xf bound_ctrl:1
	s_and_saveexec_b64 s[4:5], s[0:1]
	s_cbranch_execz .LBB0_717
	v_add_f32_e32 v142, v142, v184
	global_atomic_add_f32 v[162:163], v142, off offset:512
; __device__ __forceinline__ float fdiv(float a, float b) { return a * __builtin_amdgcn_rcpf(b); }
; __device__ __forceinline__ float bf2f(u16 h) { return __uint_as_float(((unsigned)h) << 16); }
; __device__ __forceinline__ void gemm_tile(const Params& P, const GArgs& ga, const TileDesc& td, int wid_s) {
;     ...
;       static_for<8>([&](auto ic2) __attribute__((always_inline)) {
;         constexpr int idx = b0 + decltype(ic2)::v; constexpr int ai = idx >> 4, m = (idx >> 2) & 3, j = idx & 3;
;         constexpr int rl = ai * HALF + m * 16 + j; constexpr int q = decltype(ic2)::v;
;         const float rs = rsv[idx];
;         float4 v;
;         v.x = r[q].x + fdiv(1.f, 1.f + __expf(-rs * acc[ai][0][m][0][j])) * bf2f((u16)(pe[q].x & 0xffff));
;         v.y = r[q].y + fdiv(1.f, 1.f + __expf(-rs * acc[ai][0][m][1][j])) * bf2f((u16)(pe[q].x >> 16));
;         v.z = r[q].z + fdiv(1.f, 1.f + __expf(-rs * acc[ai][1][m][0][j])) * bf2f((u16)(pe[q].y & 0xffff));
;         v.w = r[q].w + fdiv(1.f, 1.f + __expf(-rs * acc[ai][1][m][1][j])) * bf2f((u16)(pe[q].y >> 16));
;         uint2 o; o.x = pack2(v.x, v.y); o.y = pack2(v.z, v.w);
;         *reinterpret_cast<uint2*>(h4b + (size_t)rl * DM) = o;
;         float s = red16(v.x * v.x + v.y * v.y + v.z * v.z + v.w * v.w);
;         if (efr == 0) unsafeAtomicAdd(sso + rl, s);
;       });
.LBB0_717:
	s_or_b64 exec, exec, s[4:5]
	v_mov_b32_e32 v142, s17
	v_fmamk_f32 v142, v143, 0x3a000000, v142
	v_rsq_f32_e32 v188, v142
	s_waitcnt vmcnt(14)
	v_lshlrev_b32_e32 v184, 16, v182
	v_and_b32_e32 v185, 0xffff0000, v182
	s_waitcnt vmcnt(13)
	v_lshlrev_b32_e32 v186, 16, v180
	v_mul_f32_e64 v142, v51, -v188
	v_mul_f32_e64 v143, v55, -v188
	v_mul_f32_e32 v142, 0x3fb8aa3b, v142
	v_mul_f32_e32 v143, 0x3fb8aa3b, v143
	v_exp_f32_e32 v142, v142
	v_exp_f32_e32 v143, v143
	v_and_b32_e32 v187, 0xffff0000, v180
	v_mul_f32_e64 v180, v63, -v188
	v_add_f32_e32 v142, 1.0, v142
	v_add_f32_e32 v143, 1.0, v143
	v_rcp_f32_e32 v142, v142
	v_rcp_f32_e32 v143, v143
	v_mul_f32_e32 v180, 0x3fb8aa3b, v180
	v_exp_f32_e32 v180, v180
	v_lshlrev_b32_e32 v182, 16, v183
	v_pk_fma_f32 v[142:143], v[142:143], v[186:187], v[184:185]
	v_mul_f32_e64 v185, v59, -v188
	v_mul_f32_e32 v185, 0x3fb8aa3b, v185
	v_exp_f32_e32 v185, v185
	v_add_f32_e32 v180, 1.0, v180
	v_rcp_f32_e32 v184, v180
	v_and_b32_e32 v183, 0xffff0000, v183
	v_add_f32_e32 v185, 1.0, v185
	v_rcp_f32_e32 v185, v185
	v_lshlrev_b32_e32 v180, 16, v181
	v_and_b32_e32 v181, 0xffff0000, v181
	s_mov_b32 s4, 0x81000
	v_pk_fma_f32 v[180:181], v[184:185], v[180:181], v[182:183]
	v_cvt_pk_bf16_f32 v182, v142, v143
	v_pk_mul_f32 v[142:143], v[142:143], v[142:143]
	v_cvt_pk_bf16_f32 v183, v180, v181
	v_pk_mul_f32 v[180:181], v[180:181], v[180:181]
	v_add_f32_e32 v142, v142, v143
	v_add_f32_e32 v142, v142, v180
	v_add_f32_e32 v142, v181, v142
	v_add_co_u32_e32 v184, vcc, s4, v164
	s_nop 0
	v_add_f32_dpp v142, v142, v142 quad_perm:[1,0,3,2] row_mask:0xf bank_mask:0xf bound_ctrl:1
	v_addc_co_u32_e32 v185, vcc, 0, v165, vcc
	s_nop 0
	v_add_f32_dpp v142, v142, v142 quad_perm:[2,3,0,1] row_mask:0xf bank_mask:0xf bound_ctrl:1
	global_store_dwordx2 v[184:185], v[182:183], off nt
	s_nop 0
	v_add_f32_dpp v142, v142, v142 row_ror:4 row_mask:0xf bank_mask:0xf bound_ctrl:1
	s_nop 1
	v_mov_b32_dpp v143, v142 row_ror:8 row_mask:0xf bank_mask:0xf bound_ctrl:1
	s_and_saveexec_b64 s[4:5], s[0:1]
	s_cbranch_execz .LBB0_719
	v_add_f32_e32 v142, v142, v143
	global_atomic_add_f32 v[162:163], v142, off offset:516
.LBB0_719:
	s_or_b64 exec, exec, s[4:5]
	v_mov_b32_e32 v180, s17
	v_fmamk_f32 v144, v144, 0x3a000000, v180
	v_rsq_f32_e32 v144, v144
	s_waitcnt vmcnt(12)
	v_lshlrev_b32_e32 v182, 16, v176
	v_and_b32_e32 v183, 0xffff0000, v176
	v_lshlrev_b32_e32 v142, 16, v178
	v_mul_f32_e64 v180, v52, -v144
	v_mul_f32_e64 v181, v56, -v144
	v_mul_f32_e32 v180, 0x3fb8aa3b, v180
	v_mul_f32_e32 v181, 0x3fb8aa3b, v181
	v_exp_f32_e32 v180, v180
	v_exp_f32_e32 v181, v181
	v_mul_f32_e64 v176, v64, -v144
	v_mul_f32_e64 v144, v60, -v144
	v_mul_f32_e32 v176, 0x3fb8aa3b, v176
	v_mul_f32_e32 v144, 0x3fb8aa3b, v144
	v_add_f32_e32 v180, 1.0, v180
	v_add_f32_e32 v181, 1.0, v181
	v_exp_f32_e32 v176, v176
	v_exp_f32_e32 v144, v144
	v_rcp_f32_e32 v180, v180
	v_rcp_f32_e32 v181, v181
	v_and_b32_e32 v143, 0xffff0000, v178
	v_add_f32_e32 v176, 1.0, v176
	v_add_f32_e32 v144, 1.0, v144
	v_pk_fma_f32 v[142:143], v[180:181], v[182:183], v[142:143]
	v_rcp_f32_e32 v180, v176
	v_rcp_f32_e32 v181, v144
	v_lshlrev_b32_e32 v178, 16, v179
	v_and_b32_e32 v179, 0xffff0000, v179
	v_lshlrev_b32_e32 v176, 16, v177
	v_and_b32_e32 v177, 0xffff0000, v177
	v_pk_fma_f32 v[176:177], v[180:181], v[176:177], v[178:179]
	v_cvt_pk_bf16_f32 v178, v142, v143
	v_pk_mul_f32 v[142:143], v[142:143], v[142:143]
	v_cvt_pk_bf16_f32 v179, v176, v177
	v_pk_mul_f32 v[176:177], v[176:177], v[176:177]
	v_add_f32_e32 v142, v142, v143
	v_add_f32_e32 v142, v142, v176
	v_add_f32_e32 v142, v177, v142
	s_mov_b32 s4, 0x82000
	v_add_co_u32_e32 v180, vcc, s4, v164
	v_add_f32_dpp v142, v142, v142 quad_perm:[1,0,3,2] row_mask:0xf bank_mask:0xf bound_ctrl:1
	s_nop 0
	v_addc_co_u32_e32 v181, vcc, 0, v165, vcc
	v_add_f32_dpp v142, v142, v142 quad_perm:[2,3,0,1] row_mask:0xf bank_mask:0xf bound_ctrl:1
	global_store_dwordx2 v[180:181], v[178:179], off nt
	s_nop 0
	v_add_f32_dpp v142, v142, v142 row_ror:4 row_mask:0xf bank_mask:0xf bound_ctrl:1
	s_nop 1
	v_mov_b32_dpp v143, v142 row_ror:8 row_mask:0xf bank_mask:0xf bound_ctrl:1
	s_and_saveexec_b64 s[4:5], s[0:1]
	s_cbranch_execz .LBB0_721
	v_add_f32_e32 v142, v142, v143
	global_atomic_add_f32 v[162:163], v142, off offset:520
.LBB0_721:
	s_or_b64 exec, exec, s[4:5]
	v_mov_b32_e32 v144, s17
	v_fmamk_f32 v144, v145, 0x3a000000, v144
	v_rsq_f32_e32 v178, v144
	s_waitcnt vmcnt(12)
	v_lshlrev_b32_e32 v142, 16, v174
	v_and_b32_e32 v143, 0xffff0000, v174
	s_waitcnt vmcnt(11)
	v_lshlrev_b32_e32 v176, 16, v172
	v_mul_f32_e64 v144, v53, -v178
	v_mul_f32_e64 v145, v57, -v178
	v_mul_f32_e32 v144, 0x3fb8aa3b, v144
	v_mul_f32_e32 v145, 0x3fb8aa3b, v145
	v_exp_f32_e32 v144, v144
	v_exp_f32_e32 v145, v145
	v_and_b32_e32 v177, 0xffff0000, v172
	v_lshlrev_b32_e32 v174, 16, v175
	v_add_f32_e32 v144, 1.0, v144
	v_add_f32_e32 v145, 1.0, v145
	v_rcp_f32_e32 v144, v144
	v_rcp_f32_e32 v145, v145
	v_and_b32_e32 v175, 0xffff0000, v175
	v_lshlrev_b32_e32 v172, 16, v173
	v_and_b32_e32 v173, 0xffff0000, v173
	v_pk_fma_f32 v[142:143], v[144:145], v[176:177], v[142:143]
	v_mul_f32_e64 v144, v65, -v178
	v_mul_f32_e64 v145, v61, -v178
	v_mul_f32_e32 v144, 0x3fb8aa3b, v144
	v_mul_f32_e32 v145, 0x3fb8aa3b, v145
	v_exp_f32_e32 v144, v144
	v_exp_f32_e32 v145, v145
	s_mov_b32 s4, 0x83000
	v_add_f32_e32 v144, 1.0, v144
	v_add_f32_e32 v145, 1.0, v145
	v_rcp_f32_e32 v144, v144
	v_rcp_f32_e32 v145, v145
	s_nop 0
	v_pk_fma_f32 v[144:145], v[144:145], v[172:173], v[174:175]
	v_cvt_pk_bf16_f32 v172, v142, v143
	v_pk_mul_f32 v[142:143], v[142:143], v[142:143]
	v_cvt_pk_bf16_f32 v173, v144, v145
	v_pk_mul_f32 v[144:145], v[144:145], v[144:145]
	v_add_f32_e32 v142, v142, v143
	v_add_f32_e32 v142, v142, v144
	v_add_f32_e32 v142, v145, v142
	v_add_co_u32_e32 v174, vcc, s4, v164
	s_nop 0
	v_add_f32_dpp v142, v142, v142 quad_perm:[1,0,3,2] row_mask:0xf bank_mask:0xf bound_ctrl:1
	v_addc_co_u32_e32 v175, vcc, 0, v165, vcc
	s_nop 0
	v_add_f32_dpp v142, v142, v142 quad_perm:[2,3,0,1] row_mask:0xf bank_mask:0xf bound_ctrl:1
	global_store_dwordx2 v[174:175], v[172:173], off nt
	s_nop 0
	v_add_f32_dpp v142, v142, v142 row_ror:4 row_mask:0xf bank_mask:0xf bound_ctrl:1
	s_nop 1
	v_mov_b32_dpp v143, v142 row_ror:8 row_mask:0xf bank_mask:0xf bound_ctrl:1
	s_and_saveexec_b64 s[4:5], s[0:1]
	s_cbranch_execz .LBB0_723
	v_add_f32_e32 v142, v142, v143
	global_atomic_add_f32 v[162:163], v142, off offset:524
; __device__ __forceinline__ float fdiv(float a, float b) { return a * __builtin_amdgcn_rcpf(b); }
; __device__ __forceinline__ float bf2f(u16 h) { return __uint_as_float(((unsigned)h) << 16); }
; __device__ __forceinline__ void gemm_tile(const Params& P, const GArgs& ga, const TileDesc& td, int wid_s) {
;     ...
;       static_for<8>([&](auto ic2) __attribute__((always_inline)) {
;         constexpr int idx = b0 + decltype(ic2)::v; constexpr int ai = idx >> 4, m = (idx >> 2) & 3, j = idx & 3;
;         constexpr int rl = ai * HALF + m * 16 + j; constexpr int q = decltype(ic2)::v;
;         const float rs = rsv[idx];
;         float4 v;
;         v.x = r[q].x + fdiv(1.f, 1.f + __expf(-rs * acc[ai][0][m][0][j])) * bf2f((u16)(pe[q].x & 0xffff));
;         v.y = r[q].y + fdiv(1.f, 1.f + __expf(-rs * acc[ai][0][m][1][j])) * bf2f((u16)(pe[q].x >> 16));
;         v.z = r[q].z + fdiv(1.f, 1.f + __expf(-rs * acc[ai][1][m][0][j])) * bf2f((u16)(pe[q].y & 0xffff));
;         v.w = r[q].w + fdiv(1.f, 1.f + __expf(-rs * acc[ai][1][m][1][j])) * bf2f((u16)(pe[q].y >> 16));
;         uint2 o; o.x = pack2(v.x, v.y); o.y = pack2(v.z, v.w);
;         *reinterpret_cast<uint2*>(h4b + (size_t)rl * DM) = o;
;         float s = red16(v.x * v.x + v.y * v.y + v.z * v.z + v.w * v.w);
;         if (efr == 0) unsafeAtomicAdd(sso + rl, s);
;       });
.LBB0_723:
	s_or_b64 exec, exec, s[4:5]
	s_waitcnt vmcnt(11)
	v_lshlrev_b32_e32 v142, 16, v160
	v_and_b32_e32 v143, 0xffff0000, v160
	v_mov_b32_e32 v160, s17
	v_fmamk_f32 v138, v138, 0x3a000000, v160
	v_rsq_f32_e32 v138, v138
	v_lshlrev_b32_e32 v144, 16, v161
	v_and_b32_e32 v145, 0xffff0000, v161
	s_waitcnt vmcnt(10)
	v_lshlrev_b32_e32 v172, 16, v158
	v_mul_f32_e64 v160, v34, -v138
	v_mul_f32_e64 v161, v38, -v138
	v_mul_f32_e32 v160, 0x3fb8aa3b, v160
	v_mul_f32_e32 v161, 0x3fb8aa3b, v161
	v_exp_f32_e32 v160, v160
	v_exp_f32_e32 v161, v161
	v_and_b32_e32 v173, 0xffff0000, v158
	v_mul_f32_e64 v158, v46, -v138
	v_mul_f32_e64 v138, v42, -v138
	v_mul_f32_e32 v158, 0x3fb8aa3b, v158
	v_mul_f32_e32 v138, 0x3fb8aa3b, v138
	v_add_f32_e32 v160, 1.0, v160
	v_add_f32_e32 v161, 1.0, v161
	v_exp_f32_e32 v158, v158
	v_exp_f32_e32 v138, v138
	v_rcp_f32_e32 v160, v160
	v_rcp_f32_e32 v161, v161
	v_add_f32_e32 v158, 1.0, v158
	v_add_f32_e32 v138, 1.0, v138
	s_mov_b32 s4, 0x90000
	v_pk_fma_f32 v[142:143], v[160:161], v[172:173], v[142:143]
	v_rcp_f32_e32 v160, v158
	v_rcp_f32_e32 v161, v138
	v_lshlrev_b32_e32 v158, 16, v159
	v_and_b32_e32 v159, 0xffff0000, v159
	v_pk_fma_f32 v[144:145], v[160:161], v[158:159], v[144:145]
	v_cvt_pk_bf16_f32 v158, v142, v143
	v_pk_mul_f32 v[142:143], v[142:143], v[142:143]
	v_cvt_pk_bf16_f32 v159, v144, v145
	v_pk_mul_f32 v[144:145], v[144:145], v[144:145]
	v_add_f32_e32 v138, v142, v143
	v_add_f32_e32 v138, v138, v144
	v_add_f32_e32 v138, v145, v138
	v_add_co_u32_e32 v160, vcc, s4, v164
	s_nop 0
	v_add_f32_dpp v138, v138, v138 quad_perm:[1,0,3,2] row_mask:0xf bank_mask:0xf bound_ctrl:1
	v_addc_co_u32_e32 v161, vcc, 0, v165, vcc
	s_nop 0
	v_add_f32_dpp v138, v138, v138 quad_perm:[2,3,0,1] row_mask:0xf bank_mask:0xf bound_ctrl:1
	global_store_dwordx2 v[160:161], v[158:159], off nt
	s_nop 0
	v_add_f32_dpp v138, v138, v138 row_ror:4 row_mask:0xf bank_mask:0xf bound_ctrl:1
	s_nop 1
	v_mov_b32_dpp v142, v138 row_ror:8 row_mask:0xf bank_mask:0xf bound_ctrl:1
	s_and_saveexec_b64 s[4:5], s[0:1]
	s_cbranch_execz .LBB0_725
	v_add_f32_e32 v138, v138, v142
	global_atomic_add_f32 v[162:163], v138, off offset:576
.LBB0_725:
	s_or_b64 exec, exec, s[4:5]
	v_mov_b32_e32 v138, s17
	v_fmamk_f32 v138, v139, 0x3a000000, v138
	v_rsq_f32_e32 v158, v138
	s_waitcnt vmcnt(10)
	v_lshlrev_b32_e32 v142, 16, v156
	v_and_b32_e32 v143, 0xffff0000, v156
	v_lshlrev_b32_e32 v144, 16, v157
	v_mul_f32_e64 v138, v35, -v158
	v_mul_f32_e64 v139, v39, -v158
	v_mul_f32_e32 v138, 0x3fb8aa3b, v138
	v_mul_f32_e32 v139, 0x3fb8aa3b, v139
	v_exp_f32_e32 v138, v138
	v_exp_f32_e32 v139, v139
	v_and_b32_e32 v145, 0xffff0000, v157
	s_waitcnt vmcnt(9)
	v_lshlrev_b32_e32 v156, 16, v154
	v_add_f32_e32 v138, 1.0, v138
	v_add_f32_e32 v139, 1.0, v139
	v_rcp_f32_e32 v138, v138
	v_rcp_f32_e32 v139, v139
	v_and_b32_e32 v157, 0xffff0000, v154
	v_lshlrev_b32_e32 v154, 16, v155
	v_and_b32_e32 v155, 0xffff0000, v155
	v_pk_fma_f32 v[138:139], v[138:139], v[156:157], v[142:143]
	v_mul_f32_e64 v142, v47, -v158
	v_mul_f32_e64 v143, v43, -v158
	v_mul_f32_e32 v142, 0x3fb8aa3b, v142
	v_mul_f32_e32 v143, 0x3fb8aa3b, v143
	v_exp_f32_e32 v142, v142
	v_exp_f32_e32 v143, v143
	s_mov_b32 s4, 0x91000
	v_add_f32_e32 v142, 1.0, v142
	v_add_f32_e32 v143, 1.0, v143
	v_rcp_f32_e32 v142, v142
	v_rcp_f32_e32 v143, v143
	s_nop 0
	v_pk_fma_f32 v[142:143], v[142:143], v[154:155], v[144:145]
	v_cvt_pk_bf16_f32 v144, v138, v139
	v_pk_mul_f32 v[138:139], v[138:139], v[138:139]
	v_cvt_pk_bf16_f32 v145, v142, v143
	v_pk_mul_f32 v[142:143], v[142:143], v[142:143]
	v_add_f32_e32 v138, v138, v139
	v_add_f32_e32 v138, v138, v142
	v_add_f32_e32 v138, v143, v138
	v_add_co_u32_e32 v154, vcc, s4, v164
	s_nop 0
	v_add_f32_dpp v138, v138, v138 quad_perm:[1,0,3,2] row_mask:0xf bank_mask:0xf bound_ctrl:1
	v_addc_co_u32_e32 v155, vcc, 0, v165, vcc
	s_nop 0
	v_add_f32_dpp v138, v138, v138 quad_perm:[2,3,0,1] row_mask:0xf bank_mask:0xf bound_ctrl:1
	global_store_dwordx2 v[154:155], v[144:145], off nt
	s_nop 0
	v_add_f32_dpp v138, v138, v138 row_ror:4 row_mask:0xf bank_mask:0xf bound_ctrl:1
	s_nop 1
	v_mov_b32_dpp v139, v138 row_ror:8 row_mask:0xf bank_mask:0xf bound_ctrl:1
	s_and_saveexec_b64 s[4:5], s[0:1]
	s_cbranch_execz .LBB0_727
	v_add_f32_e32 v138, v138, v139
	global_atomic_add_f32 v[162:163], v138, off offset:580
.LBB0_727:
	s_or_b64 exec, exec, s[4:5]
	v_mov_b32_e32 v144, s17
	v_fmamk_f32 v140, v140, 0x3a000000, v144
	v_rsq_f32_e32 v140, v140
	s_waitcnt vmcnt(9)
	v_lshlrev_b32_e32 v138, 16, v152
	v_and_b32_e32 v139, 0xffff0000, v152
	v_lshlrev_b32_e32 v142, 16, v153
	v_mul_f32_e64 v144, v36, -v140
	v_mul_f32_e64 v145, v40, -v140
	v_mul_f32_e32 v144, 0x3fb8aa3b, v144
	v_mul_f32_e32 v145, 0x3fb8aa3b, v145
	v_exp_f32_e32 v144, v144
	v_exp_f32_e32 v145, v145
	v_and_b32_e32 v143, 0xffff0000, v153
	s_waitcnt vmcnt(8)
	v_lshlrev_b32_e32 v152, 16, v150
	v_add_f32_e32 v144, 1.0, v144
	v_add_f32_e32 v145, 1.0, v145
	v_rcp_f32_e32 v144, v144
	v_rcp_f32_e32 v145, v145
	v_and_b32_e32 v153, 0xffff0000, v150
	v_lshlrev_b32_e32 v150, 16, v151
	v_and_b32_e32 v151, 0xffff0000, v151
	v_pk_fma_f32 v[138:139], v[144:145], v[152:153], v[138:139]
	v_mul_f32_e64 v144, v48, -v140
	v_mul_f32_e64 v140, v44, -v140
	v_mul_f32_e32 v144, 0x3fb8aa3b, v144
	v_mul_f32_e32 v140, 0x3fb8aa3b, v140
	v_exp_f32_e32 v144, v144
	v_exp_f32_e32 v140, v140
	s_mov_b32 s4, 0x92000
	v_add_f32_e32 v144, 1.0, v144
	v_add_f32_e32 v140, 1.0, v140
	v_rcp_f32_e32 v144, v144
	v_rcp_f32_e32 v145, v140
	s_nop 0
	v_pk_fma_f32 v[142:143], v[144:145], v[150:151], v[142:143]
	v_cvt_pk_bf16_f32 v144, v138, v139
	v_pk_mul_f32 v[138:139], v[138:139], v[138:139]
	v_cvt_pk_bf16_f32 v145, v142, v143
	v_pk_mul_f32 v[142:143], v[142:143], v[142:143]
	v_add_f32_e32 v138, v138, v139
	v_add_f32_e32 v138, v138, v142
	v_add_f32_e32 v138, v143, v138
	v_add_co_u32_e32 v150, vcc, s4, v164
	s_nop 0
	v_add_f32_dpp v138, v138, v138 quad_perm:[1,0,3,2] row_mask:0xf bank_mask:0xf bound_ctrl:1
	v_addc_co_u32_e32 v151, vcc, 0, v165, vcc
	s_nop 0
	v_add_f32_dpp v138, v138, v138 quad_perm:[2,3,0,1] row_mask:0xf bank_mask:0xf bound_ctrl:1
	global_store_dwordx2 v[150:151], v[144:145], off nt
	s_nop 0
	v_add_f32_dpp v138, v138, v138 row_ror:4 row_mask:0xf bank_mask:0xf bound_ctrl:1
	s_nop 1
	v_mov_b32_dpp v139, v138 row_ror:8 row_mask:0xf bank_mask:0xf bound_ctrl:1
	s_and_saveexec_b64 s[4:5], s[0:1]
	s_cbranch_execz .LBB0_729
	v_add_f32_e32 v138, v138, v139
	global_atomic_add_f32 v[162:163], v138, off offset:584
; __device__ __forceinline__ float fdiv(float a, float b) { return a * __builtin_amdgcn_rcpf(b); }
; __device__ __forceinline__ float bf2f(u16 h) { return __uint_as_float(((unsigned)h) << 16); }
; __device__ __forceinline__ void gemm_tile(const Params& P, const GArgs& ga, const TileDesc& td, int wid_s) {
;     ...
;       static_for<8>([&](auto ic2) __attribute__((always_inline)) {
;         constexpr int idx = b0 + decltype(ic2)::v; constexpr int ai = idx >> 4, m = (idx >> 2) & 3, j = idx & 3;
;         constexpr int rl = ai * HALF + m * 16 + j; constexpr int q = decltype(ic2)::v;
;         const uint2 t = *reinterpret_cast<const uint2*>(h3b + (size_t)rl * DM);
;         r[q] = make_float4(__uint_as_float(t.x << 16), __uint_as_float(t.x & 0xffff0000u),
;                            __uint_as_float(t.y << 16), __uint_as_float(t.y & 0xffff0000u));
;         pe[q] = *reinterpret_cast<const uint2*>(pd + (size_t)rl * DM);
;       });
;       __builtin_amdgcn_sched_barrier(0);
;       static_for<8>([&](auto ic2) __attribute__((always_inline)) {
;         constexpr int idx = b0 + decltype(ic2)::v; constexpr int ai = idx >> 4, m = (idx >> 2) & 3, j = idx & 3;
;         constexpr int rl = ai * HALF + m * 16 + j; constexpr int q = decltype(ic2)::v;
;         const float rs = rsv[idx];
;         float4 v;
;         v.x = r[q].x + fdiv(1.f, 1.f + __expf(-rs * acc[ai][0][m][0][j])) * bf2f((u16)(pe[q].x & 0xffff));
;         v.y = r[q].y + fdiv(1.f, 1.f + __expf(-rs * acc[ai][0][m][1][j])) * bf2f((u16)(pe[q].x >> 16));
;         v.z = r[q].z + fdiv(1.f, 1.f + __expf(-rs * acc[ai][1][m][0][j])) * bf2f((u16)(pe[q].y & 0xffff));
;         v.w = r[q].w + fdiv(1.f, 1.f + __expf(-rs * acc[ai][1][m][1][j])) * bf2f((u16)(pe[q].y >> 16));
;         uint2 o; o.x = pack2(v.x, v.y); o.y = pack2(v.z, v.w);
;         *reinterpret_cast<uint2*>(h4b + (size_t)rl * DM) = o;
;         float s = red16(v.x * v.x + v.y * v.y + v.z * v.z + v.w * v.w);
;         if (efr == 0) unsafeAtomicAdd(sso + rl, s);
;       });
.LBB0_729:
	s_or_b64 exec, exec, s[4:5]
	v_mov_b32_e32 v140, s17
	v_fmamk_f32 v140, v141, 0x3a000000, v140
	s_waitcnt vmcnt(8)
	v_lshlrev_b32_e32 v138, 16, v148
	v_and_b32_e32 v139, 0xffff0000, v148
	v_rsq_f32_e32 v148, v140
	s_waitcnt vmcnt(7)
	v_lshlrev_b32_e32 v144, 16, v146
	v_and_b32_e32 v145, 0xffff0000, v146
	v_lshlrev_b32_e32 v142, 16, v149
	v_mul_f32_e64 v140, v37, -v148
	v_mul_f32_e64 v141, v41, -v148
	v_mul_f32_e32 v140, 0x3fb8aa3b, v140
	v_mul_f32_e32 v141, 0x3fb8aa3b, v141
	v_exp_f32_e32 v140, v140
	v_exp_f32_e32 v141, v141
	v_and_b32_e32 v143, 0xffff0000, v149
	s_mov_b32 s4, 0x93000
	v_add_f32_e32 v140, 1.0, v140
	v_add_f32_e32 v141, 1.0, v141
	v_rcp_f32_e32 v140, v140
	v_rcp_f32_e32 v141, v141
	s_nop 0
	v_pk_fma_f32 v[138:139], v[140:141], v[144:145], v[138:139]
	v_mul_f32_e64 v140, v49, -v148
	v_mul_f32_e64 v141, v45, -v148
	v_mul_f32_e32 v140, 0x3fb8aa3b, v140
	v_mul_f32_e32 v141, 0x3fb8aa3b, v141
	v_exp_f32_e32 v140, v140
	v_exp_f32_e32 v141, v141
	v_lshlrev_b32_e32 v144, 16, v147
	v_and_b32_e32 v145, 0xffff0000, v147
	v_add_f32_e32 v140, 1.0, v140
	v_add_f32_e32 v141, 1.0, v141
	v_rcp_f32_e32 v140, v140
	v_rcp_f32_e32 v141, v141
	s_nop 0
	v_pk_fma_f32 v[140:141], v[140:141], v[144:145], v[142:143]
	v_cvt_pk_bf16_f32 v142, v138, v139
	v_pk_mul_f32 v[138:139], v[138:139], v[138:139]
	v_cvt_pk_bf16_f32 v143, v140, v141
	v_pk_mul_f32 v[140:141], v[140:141], v[140:141]
	v_add_f32_e32 v138, v138, v139
	v_add_f32_e32 v138, v138, v140
	v_add_f32_e32 v138, v141, v138
	v_add_co_u32_e32 v144, vcc, s4, v164
	s_nop 0
	v_add_f32_dpp v138, v138, v138 quad_perm:[1,0,3,2] row_mask:0xf bank_mask:0xf bound_ctrl:1
	v_addc_co_u32_e32 v145, vcc, 0, v165, vcc
	s_nop 0
	v_add_f32_dpp v138, v138, v138 quad_perm:[2,3,0,1] row_mask:0xf bank_mask:0xf bound_ctrl:1
	global_store_dwordx2 v[144:145], v[142:143], off nt
	s_nop 0
	v_add_f32_dpp v138, v138, v138 row_ror:4 row_mask:0xf bank_mask:0xf bound_ctrl:1
	s_nop 1
	v_mov_b32_dpp v139, v138 row_ror:8 row_mask:0xf bank_mask:0xf bound_ctrl:1
	s_and_saveexec_b64 s[4:5], s[0:1]
	s_cbranch_execz .LBB0_731
	v_add_f32_e32 v138, v138, v139
	global_atomic_add_f32 v[162:163], v138, off offset:588
.LBB0_731:
	s_or_b64 exec, exec, s[4:5]
	v_mov_b32_e32 v138, s17
	v_fmamk_f32 v134, v134, 0x3a000000, v138
	v_rsq_f32_e32 v134, v134
	v_add_co_u32_e32 v138, vcc, 0xa0000, v170
	s_nop 1
	v_addc_co_u32_e32 v139, vcc, 0, v171, vcc
	global_load_dwordx2 v[138:139], v[138:139], off
	s_waitcnt vmcnt(0)
	v_lshlrev_b32_e32 v178, 16, v138
	v_and_b32_e32 v179, 0xffff0000, v138
	v_add_co_u32_e32 v138, vcc, 0xa0000, v168
	v_lshlrev_b32_e32 v180, 16, v139
	v_and_b32_e32 v181, 0xffff0000, v139
	v_addc_co_u32_e32 v139, vcc, 0, v169, vcc
	global_load_dwordx2 v[176:177], v[138:139], off
	v_add_co_u32_e32 v138, vcc, 0xa1000, v170
	s_nop 1
	v_addc_co_u32_e32 v139, vcc, 0, v171, vcc
	global_load_dwordx2 v[174:175], v[138:139], off
	v_add_co_u32_e32 v138, vcc, 0xa1000, v168
	s_nop 1
	v_addc_co_u32_e32 v139, vcc, 0, v169, vcc
	global_load_dwordx2 v[172:173], v[138:139], off
	v_add_co_u32_e32 v138, vcc, 0xa2000, v170
	s_nop 1
	v_addc_co_u32_e32 v139, vcc, 0, v171, vcc
	global_load_dwordx2 v[160:161], v[138:139], off
	v_add_co_u32_e32 v138, vcc, 0xa2000, v168
	s_nop 1
	v_addc_co_u32_e32 v139, vcc, 0, v169, vcc
	global_load_dwordx2 v[158:159], v[138:139], off
	v_add_co_u32_e32 v138, vcc, 0xa3000, v170
	s_nop 1
	v_addc_co_u32_e32 v139, vcc, 0, v171, vcc
	global_load_dwordx2 v[156:157], v[138:139], off
	v_add_co_u32_e32 v138, vcc, 0xa3000, v168
	s_nop 1
	v_addc_co_u32_e32 v139, vcc, 0, v169, vcc
	global_load_dwordx2 v[154:155], v[138:139], off
	v_add_co_u32_e32 v138, vcc, 0xb0000, v170
	s_nop 1
	v_addc_co_u32_e32 v139, vcc, 0, v171, vcc
	global_load_dwordx2 v[152:153], v[138:139], off
	v_add_co_u32_e32 v138, vcc, 0xb0000, v168
	s_nop 1
	v_addc_co_u32_e32 v139, vcc, 0, v169, vcc
	global_load_dwordx2 v[150:151], v[138:139], off
	v_add_co_u32_e32 v138, vcc, 0xb1000, v170
	s_nop 1
	v_addc_co_u32_e32 v139, vcc, 0, v171, vcc
	global_load_dwordx2 v[148:149], v[138:139], off
	v_add_co_u32_e32 v138, vcc, 0xb1000, v168
	s_nop 1
	v_addc_co_u32_e32 v139, vcc, 0, v169, vcc
	global_load_dwordx2 v[146:147], v[138:139], off
	v_add_co_u32_e32 v138, vcc, 0xb2000, v170
	s_nop 1
	v_addc_co_u32_e32 v139, vcc, 0, v171, vcc
	global_load_dwordx2 v[144:145], v[138:139], off
	v_add_co_u32_e32 v138, vcc, 0xb2000, v168
	s_nop 1
	v_addc_co_u32_e32 v139, vcc, 0, v169, vcc
	global_load_dwordx2 v[142:143], v[138:139], off
	v_add_co_u32_e32 v138, vcc, 0xb3000, v170
	s_nop 1
	v_addc_co_u32_e32 v139, vcc, 0, v171, vcc
	global_load_dwordx2 v[140:141], v[138:139], off
	v_add_co_u32_e32 v138, vcc, 0xb3000, v168
	s_nop 1
	v_addc_co_u32_e32 v139, vcc, 0, v169, vcc
	global_load_dwordx2 v[138:139], v[138:139], off
	v_mul_f32_e64 v168, v18, -v134
	v_mul_f32_e32 v168, 0x3fb8aa3b, v168
	v_exp_f32_e32 v168, v168
	s_waitcnt vmcnt(14)
	v_lshlrev_b32_e32 v169, 16, v176
	s_mov_b32 s4, 0xa0000
	v_add_co_u32_e32 v170, vcc, s4, v164
	v_add_f32_e32 v168, 1.0, v168
	v_rcp_f32_e32 v168, v168
	v_addc_co_u32_e32 v171, vcc, 0, v165, vcc
	v_fmac_f32_e32 v178, v168, v169
	v_mul_f32_e64 v168, v22, -v134
	v_mul_f32_e32 v168, 0x3fb8aa3b, v168
	v_exp_f32_e32 v168, v168
	v_and_b32_e32 v169, 0xffff0000, v176
	v_add_f32_e32 v168, 1.0, v168
	v_rcp_f32_e32 v168, v168
	s_nop 0
	v_fmac_f32_e32 v179, v168, v169
	v_mul_f32_e64 v168, v30, -v134
	v_mul_f32_e32 v168, 0x3fb8aa3b, v168
	v_mul_f32_e64 v134, v26, -v134
	v_exp_f32_e32 v168, v168
	v_mul_f32_e32 v134, 0x3fb8aa3b, v134
	v_exp_f32_e32 v134, v134
	v_lshlrev_b32_e32 v169, 16, v177
	v_add_f32_e32 v168, 1.0, v168
	v_rcp_f32_e32 v168, v168
	v_add_f32_e32 v134, 1.0, v134
	v_rcp_f32_e32 v134, v134
	v_fmac_f32_e32 v180, v168, v169
	v_and_b32_e32 v168, 0xffff0000, v177
	v_fmac_f32_e32 v181, v134, v168
	v_mul_f32_e32 v134, v179, v179
	v_fmac_f32_e32 v134, v178, v178
	v_fmac_f32_e32 v134, v180, v180
	v_fmac_f32_e32 v134, v181, v181
	v_cvt_pk_bf16_f32 v168, v178, v179
	v_cvt_pk_bf16_f32 v169, v180, v181
	v_add_f32_dpp v134, v134, v134 quad_perm:[1,0,3,2] row_mask:0xf bank_mask:0xf bound_ctrl:1
	global_store_dwordx2 v[170:171], v[168:169], off nt
	s_nop 0
	v_add_f32_dpp v134, v134, v134 quad_perm:[2,3,0,1] row_mask:0xf bank_mask:0xf bound_ctrl:1
	s_nop 1
	v_add_f32_dpp v134, v134, v134 row_ror:4 row_mask:0xf bank_mask:0xf bound_ctrl:1
	s_nop 1
	v_mov_b32_dpp v168, v134 row_ror:8 row_mask:0xf bank_mask:0xf bound_ctrl:1
	s_and_saveexec_b64 s[4:5], s[0:1]
	s_cbranch_execz .LBB0_733
	v_add_f32_e32 v134, v134, v168
	global_atomic_add_f32 v[162:163], v134, off offset:640
; __device__ __forceinline__ float fdiv(float a, float b) { return a * __builtin_amdgcn_rcpf(b); }
; __device__ __forceinline__ float bf2f(u16 h) { return __uint_as_float(((unsigned)h) << 16); }
; __device__ __forceinline__ void gemm_tile(const Params& P, const GArgs& ga, const TileDesc& td, int wid_s) {
;     ...
;       static_for<8>([&](auto ic2) __attribute__((always_inline)) {
;         constexpr int idx = b0 + decltype(ic2)::v; constexpr int ai = idx >> 4, m = (idx >> 2) & 3, j = idx & 3;
;         constexpr int rl = ai * HALF + m * 16 + j; constexpr int q = decltype(ic2)::v;
;         const float rs = rsv[idx];
;         float4 v;
;         v.x = r[q].x + fdiv(1.f, 1.f + __expf(-rs * acc[ai][0][m][0][j])) * bf2f((u16)(pe[q].x & 0xffff));
;         v.y = r[q].y + fdiv(1.f, 1.f + __expf(-rs * acc[ai][0][m][1][j])) * bf2f((u16)(pe[q].x >> 16));
;         v.z = r[q].z + fdiv(1.f, 1.f + __expf(-rs * acc[ai][1][m][0][j])) * bf2f((u16)(pe[q].y & 0xffff));
;         v.w = r[q].w + fdiv(1.f, 1.f + __expf(-rs * acc[ai][1][m][1][j])) * bf2f((u16)(pe[q].y >> 16));
;         uint2 o; o.x = pack2(v.x, v.y); o.y = pack2(v.z, v.w);
;         *reinterpret_cast<uint2*>(h4b + (size_t)rl * DM) = o;
;         float s = red16(v.x * v.x + v.y * v.y + v.z * v.z + v.w * v.w);
;         if (efr == 0) unsafeAtomicAdd(sso + rl, s);
;       });
.LBB0_733:
	s_or_b64 exec, exec, s[4:5]
	v_mov_b32_e32 v134, s17
	v_fmamk_f32 v134, v135, 0x3a000000, v134
	v_rsq_f32_e32 v176, v134
	s_waitcnt vmcnt(14)
	v_lshlrev_b32_e32 v168, 16, v174
	v_and_b32_e32 v169, 0xffff0000, v174
	v_lshlrev_b32_e32 v170, 16, v175
	v_mul_f32_e64 v134, v19, -v176
	v_mul_f32_e64 v135, v23, -v176
	v_mul_f32_e32 v134, 0x3fb8aa3b, v134
	v_mul_f32_e32 v135, 0x3fb8aa3b, v135
	v_exp_f32_e32 v134, v134
	v_exp_f32_e32 v135, v135
	v_and_b32_e32 v171, 0xffff0000, v175
	s_waitcnt vmcnt(13)
	v_lshlrev_b32_e32 v174, 16, v172
	v_add_f32_e32 v134, 1.0, v134
	v_add_f32_e32 v135, 1.0, v135
	v_rcp_f32_e32 v134, v134
	v_rcp_f32_e32 v135, v135
	v_and_b32_e32 v175, 0xffff0000, v172
	v_lshlrev_b32_e32 v172, 16, v173
	v_and_b32_e32 v173, 0xffff0000, v173
	v_pk_fma_f32 v[134:135], v[134:135], v[174:175], v[168:169]
	v_mul_f32_e64 v168, v31, -v176
	v_mul_f32_e64 v169, v27, -v176
	v_mul_f32_e32 v168, 0x3fb8aa3b, v168
	v_mul_f32_e32 v169, 0x3fb8aa3b, v169
	v_exp_f32_e32 v168, v168
	v_exp_f32_e32 v169, v169
	s_mov_b32 s4, 0xa1000
	v_add_f32_e32 v168, 1.0, v168
	v_add_f32_e32 v169, 1.0, v169
	v_rcp_f32_e32 v168, v168
	v_rcp_f32_e32 v169, v169
	s_nop 0
	v_pk_fma_f32 v[168:169], v[168:169], v[172:173], v[170:171]
	v_cvt_pk_bf16_f32 v170, v134, v135
	v_pk_mul_f32 v[134:135], v[134:135], v[134:135]
	v_cvt_pk_bf16_f32 v171, v168, v169
	v_pk_mul_f32 v[168:169], v[168:169], v[168:169]
	v_add_f32_e32 v134, v134, v135
	v_add_f32_e32 v134, v134, v168
	v_add_f32_e32 v134, v169, v134
	v_add_co_u32_e32 v172, vcc, s4, v164
	s_nop 0
	v_add_f32_dpp v134, v134, v134 quad_perm:[1,0,3,2] row_mask:0xf bank_mask:0xf bound_ctrl:1
	v_addc_co_u32_e32 v173, vcc, 0, v165, vcc
	s_nop 0
	v_add_f32_dpp v134, v134, v134 quad_perm:[2,3,0,1] row_mask:0xf bank_mask:0xf bound_ctrl:1
	global_store_dwordx2 v[172:173], v[170:171], off nt
	s_nop 0
	v_add_f32_dpp v134, v134, v134 row_ror:4 row_mask:0xf bank_mask:0xf bound_ctrl:1
	s_nop 1
	v_mov_b32_dpp v135, v134 row_ror:8 row_mask:0xf bank_mask:0xf bound_ctrl:1
	s_and_saveexec_b64 s[4:5], s[0:1]
	s_cbranch_execz .LBB0_735
	v_add_f32_e32 v134, v134, v135
	global_atomic_add_f32 v[162:163], v134, off offset:644
.LBB0_735:
	s_or_b64 exec, exec, s[4:5]
	v_mov_b32_e32 v168, s17
	v_fmamk_f32 v136, v136, 0x3a000000, v168
	v_rsq_f32_e32 v136, v136
	s_waitcnt vmcnt(12)
	v_lshlrev_b32_e32 v170, 16, v158
	v_and_b32_e32 v171, 0xffff0000, v158
	v_lshlrev_b32_e32 v134, 16, v160
	v_mul_f32_e64 v168, v20, -v136
	v_mul_f32_e64 v169, v24, -v136
	v_mul_f32_e32 v168, 0x3fb8aa3b, v168
	v_mul_f32_e32 v169, 0x3fb8aa3b, v169
	v_exp_f32_e32 v168, v168
	v_exp_f32_e32 v169, v169
	v_mul_f32_e64 v158, v32, -v136
	v_mul_f32_e64 v136, v28, -v136
	v_mul_f32_e32 v158, 0x3fb8aa3b, v158
	v_mul_f32_e32 v136, 0x3fb8aa3b, v136
	v_add_f32_e32 v168, 1.0, v168
	v_add_f32_e32 v169, 1.0, v169
	v_exp_f32_e32 v158, v158
	v_exp_f32_e32 v136, v136
	v_rcp_f32_e32 v168, v168
	v_rcp_f32_e32 v169, v169
	v_and_b32_e32 v135, 0xffff0000, v160
	v_add_f32_e32 v158, 1.0, v158
	v_add_f32_e32 v136, 1.0, v136
	v_pk_fma_f32 v[134:135], v[168:169], v[170:171], v[134:135]
	v_rcp_f32_e32 v168, v158
	v_rcp_f32_e32 v169, v136
	v_lshlrev_b32_e32 v160, 16, v161
	v_and_b32_e32 v161, 0xffff0000, v161
	v_lshlrev_b32_e32 v158, 16, v159
	v_and_b32_e32 v159, 0xffff0000, v159
	v_pk_fma_f32 v[158:159], v[168:169], v[158:159], v[160:161]
	v_cvt_pk_bf16_f32 v160, v134, v135
	v_pk_mul_f32 v[134:135], v[134:135], v[134:135]
	v_cvt_pk_bf16_f32 v161, v158, v159
	v_pk_mul_f32 v[158:159], v[158:159], v[158:159]
	v_add_f32_e32 v134, v134, v135
	v_add_f32_e32 v134, v134, v158
	v_add_f32_e32 v134, v159, v134
	s_mov_b32 s4, 0xa2000
	v_add_co_u32_e32 v168, vcc, s4, v164
	v_add_f32_dpp v134, v134, v134 quad_perm:[1,0,3,2] row_mask:0xf bank_mask:0xf bound_ctrl:1
	s_nop 0
	v_addc_co_u32_e32 v169, vcc, 0, v165, vcc
	v_add_f32_dpp v134, v134, v134 quad_perm:[2,3,0,1] row_mask:0xf bank_mask:0xf bound_ctrl:1
	global_store_dwordx2 v[168:169], v[160:161], off nt
	s_nop 0
	v_add_f32_dpp v134, v134, v134 row_ror:4 row_mask:0xf bank_mask:0xf bound_ctrl:1
	s_nop 1
	v_mov_b32_dpp v135, v134 row_ror:8 row_mask:0xf bank_mask:0xf bound_ctrl:1
	s_and_saveexec_b64 s[4:5], s[0:1]
	s_cbranch_execz .LBB0_737
	v_add_f32_e32 v134, v134, v135
	global_atomic_add_f32 v[162:163], v134, off offset:648
.LBB0_737:
	s_or_b64 exec, exec, s[4:5]
	v_mov_b32_e32 v136, s17
	v_fmamk_f32 v136, v137, 0x3a000000, v136
	v_rsq_f32_e32 v160, v136
	s_waitcnt vmcnt(12)
	v_lshlrev_b32_e32 v134, 16, v156
	v_and_b32_e32 v135, 0xffff0000, v156
	s_waitcnt vmcnt(11)
	v_lshlrev_b32_e32 v158, 16, v154
	v_mul_f32_e64 v136, v21, -v160
	v_mul_f32_e64 v137, v25, -v160
	v_mul_f32_e32 v136, 0x3fb8aa3b, v136
	v_mul_f32_e32 v137, 0x3fb8aa3b, v137
	v_exp_f32_e32 v136, v136
	v_exp_f32_e32 v137, v137
	v_and_b32_e32 v159, 0xffff0000, v154
	v_lshlrev_b32_e32 v156, 16, v157
	v_add_f32_e32 v136, 1.0, v136
	v_add_f32_e32 v137, 1.0, v137
	v_rcp_f32_e32 v136, v136
	v_rcp_f32_e32 v137, v137
	v_and_b32_e32 v157, 0xffff0000, v157
	v_lshlrev_b32_e32 v154, 16, v155
	v_and_b32_e32 v155, 0xffff0000, v155
	v_pk_fma_f32 v[134:135], v[136:137], v[158:159], v[134:135]
	v_mul_f32_e64 v136, v33, -v160
	v_mul_f32_e64 v137, v29, -v160
	v_mul_f32_e32 v136, 0x3fb8aa3b, v136
	v_mul_f32_e32 v137, 0x3fb8aa3b, v137
	v_exp_f32_e32 v136, v136
	v_exp_f32_e32 v137, v137
	s_mov_b32 s4, 0xa3000
	v_add_f32_e32 v136, 1.0, v136
	v_add_f32_e32 v137, 1.0, v137
	v_rcp_f32_e32 v136, v136
	v_rcp_f32_e32 v137, v137
	s_nop 0
	v_pk_fma_f32 v[136:137], v[136:137], v[154:155], v[156:157]
	v_cvt_pk_bf16_f32 v154, v134, v135
	v_pk_mul_f32 v[134:135], v[134:135], v[134:135]
	v_cvt_pk_bf16_f32 v155, v136, v137
	v_pk_mul_f32 v[136:137], v[136:137], v[136:137]
	v_add_f32_e32 v134, v134, v135
	v_add_f32_e32 v134, v134, v136
	v_add_f32_e32 v134, v137, v134
	v_add_co_u32_e32 v156, vcc, s4, v164
	s_nop 0
	v_add_f32_dpp v134, v134, v134 quad_perm:[1,0,3,2] row_mask:0xf bank_mask:0xf bound_ctrl:1
	v_addc_co_u32_e32 v157, vcc, 0, v165, vcc
	s_nop 0
	v_add_f32_dpp v134, v134, v134 quad_perm:[2,3,0,1] row_mask:0xf bank_mask:0xf bound_ctrl:1
	global_store_dwordx2 v[156:157], v[154:155], off nt
	s_nop 0
	v_add_f32_dpp v134, v134, v134 row_ror:4 row_mask:0xf bank_mask:0xf bound_ctrl:1
	s_nop 1
	v_mov_b32_dpp v135, v134 row_ror:8 row_mask:0xf bank_mask:0xf bound_ctrl:1
	s_and_saveexec_b64 s[4:5], s[0:1]
	s_cbranch_execz .LBB0_739
	v_add_f32_e32 v134, v134, v135
	global_atomic_add_f32 v[162:163], v134, off offset:652
; __device__ __forceinline__ float fdiv(float a, float b) { return a * __builtin_amdgcn_rcpf(b); }
; __device__ __forceinline__ float bf2f(u16 h) { return __uint_as_float(((unsigned)h) << 16); }
; __device__ __forceinline__ void gemm_tile(const Params& P, const GArgs& ga, const TileDesc& td, int wid_s) {
;     ...
;       static_for<8>([&](auto ic2) __attribute__((always_inline)) {
;         constexpr int idx = b0 + decltype(ic2)::v; constexpr int ai = idx >> 4, m = (idx >> 2) & 3, j = idx & 3;
;         constexpr int rl = ai * HALF + m * 16 + j; constexpr int q = decltype(ic2)::v;
;         const float rs = rsv[idx];
;         float4 v;
;         v.x = r[q].x + fdiv(1.f, 1.f + __expf(-rs * acc[ai][0][m][0][j])) * bf2f((u16)(pe[q].x & 0xffff));
;         v.y = r[q].y + fdiv(1.f, 1.f + __expf(-rs * acc[ai][0][m][1][j])) * bf2f((u16)(pe[q].x >> 16));
;         v.z = r[q].z + fdiv(1.f, 1.f + __expf(-rs * acc[ai][1][m][0][j])) * bf2f((u16)(pe[q].y & 0xffff));
;         v.w = r[q].w + fdiv(1.f, 1.f + __expf(-rs * acc[ai][1][m][1][j])) * bf2f((u16)(pe[q].y >> 16));
;         uint2 o; o.x = pack2(v.x, v.y); o.y = pack2(v.z, v.w);
;         *reinterpret_cast<uint2*>(h4b + (size_t)rl * DM) = o;
;         float s = red16(v.x * v.x + v.y * v.y + v.z * v.z + v.w * v.w);
;         if (efr == 0) unsafeAtomicAdd(sso + rl, s);
;       });
.LBB0_739:
	s_or_b64 exec, exec, s[4:5]
	s_waitcnt vmcnt(11)
	v_lshlrev_b32_e32 v134, 16, v152
	v_and_b32_e32 v135, 0xffff0000, v152
	v_mov_b32_e32 v152, s17
	v_fmamk_f32 v130, v130, 0x3a000000, v152
	v_rsq_f32_e32 v130, v130
	v_lshlrev_b32_e32 v136, 16, v153
	v_and_b32_e32 v137, 0xffff0000, v153
	s_waitcnt vmcnt(10)
	v_lshlrev_b32_e32 v154, 16, v150
	v_mul_f32_e64 v152, v2, -v130
	v_mul_f32_e64 v153, v6, -v130
	v_mul_f32_e32 v152, 0x3fb8aa3b, v152
	v_mul_f32_e32 v153, 0x3fb8aa3b, v153
	v_exp_f32_e32 v152, v152
	v_exp_f32_e32 v153, v153
	v_and_b32_e32 v155, 0xffff0000, v150
	v_mul_f32_e64 v150, v14, -v130
	v_mul_f32_e64 v130, v10, -v130
	v_mul_f32_e32 v150, 0x3fb8aa3b, v150
	v_mul_f32_e32 v130, 0x3fb8aa3b, v130
	v_add_f32_e32 v152, 1.0, v152
	v_add_f32_e32 v153, 1.0, v153
	v_exp_f32_e32 v150, v150
	v_exp_f32_e32 v130, v130
	v_rcp_f32_e32 v152, v152
	v_rcp_f32_e32 v153, v153
	v_add_f32_e32 v150, 1.0, v150
	v_add_f32_e32 v130, 1.0, v130
	s_mov_b32 s4, 0xb0000
	v_pk_fma_f32 v[134:135], v[152:153], v[154:155], v[134:135]
	v_rcp_f32_e32 v152, v150
	v_rcp_f32_e32 v153, v130
	v_lshlrev_b32_e32 v150, 16, v151
	v_and_b32_e32 v151, 0xffff0000, v151
	v_pk_fma_f32 v[136:137], v[152:153], v[150:151], v[136:137]
	v_cvt_pk_bf16_f32 v150, v134, v135
	v_pk_mul_f32 v[134:135], v[134:135], v[134:135]
	v_cvt_pk_bf16_f32 v151, v136, v137
	v_pk_mul_f32 v[136:137], v[136:137], v[136:137]
	v_add_f32_e32 v130, v134, v135
	v_add_f32_e32 v130, v130, v136
	v_add_f32_e32 v130, v137, v130
	v_add_co_u32_e32 v152, vcc, s4, v164
	s_nop 0
	v_add_f32_dpp v130, v130, v130 quad_perm:[1,0,3,2] row_mask:0xf bank_mask:0xf bound_ctrl:1
	v_addc_co_u32_e32 v153, vcc, 0, v165, vcc
	s_nop 0
	v_add_f32_dpp v130, v130, v130 quad_perm:[2,3,0,1] row_mask:0xf bank_mask:0xf bound_ctrl:1
	global_store_dwordx2 v[152:153], v[150:151], off nt
	s_nop 0
	v_add_f32_dpp v130, v130, v130 row_ror:4 row_mask:0xf bank_mask:0xf bound_ctrl:1
	s_nop 1
	v_mov_b32_dpp v134, v130 row_ror:8 row_mask:0xf bank_mask:0xf bound_ctrl:1
	s_and_saveexec_b64 s[4:5], s[0:1]
	s_cbranch_execz .LBB0_741
	v_add_f32_e32 v130, v130, v134
	global_atomic_add_f32 v[162:163], v130, off offset:704
.LBB0_741:
	s_or_b64 exec, exec, s[4:5]
	v_mov_b32_e32 v130, s17
	v_fmamk_f32 v130, v131, 0x3a000000, v130
	v_rsq_f32_e32 v150, v130
	s_waitcnt vmcnt(10)
	v_lshlrev_b32_e32 v134, 16, v148
	v_and_b32_e32 v135, 0xffff0000, v148
	v_lshlrev_b32_e32 v136, 16, v149
	v_mul_f32_e64 v130, v3, -v150
	v_mul_f32_e64 v131, v7, -v150
	v_mul_f32_e32 v130, 0x3fb8aa3b, v130
	v_mul_f32_e32 v131, 0x3fb8aa3b, v131
	v_exp_f32_e32 v130, v130
	v_exp_f32_e32 v131, v131
	v_and_b32_e32 v137, 0xffff0000, v149
	s_waitcnt vmcnt(9)
	v_lshlrev_b32_e32 v148, 16, v146
	v_add_f32_e32 v130, 1.0, v130
	v_add_f32_e32 v131, 1.0, v131
	v_rcp_f32_e32 v130, v130
	v_rcp_f32_e32 v131, v131
	v_and_b32_e32 v149, 0xffff0000, v146
	v_lshlrev_b32_e32 v146, 16, v147
	v_and_b32_e32 v147, 0xffff0000, v147
	v_pk_fma_f32 v[130:131], v[130:131], v[148:149], v[134:135]
	v_mul_f32_e64 v134, v15, -v150
	v_mul_f32_e64 v135, v11, -v150
	v_mul_f32_e32 v134, 0x3fb8aa3b, v134
	v_mul_f32_e32 v135, 0x3fb8aa3b, v135
	v_exp_f32_e32 v134, v134
	v_exp_f32_e32 v135, v135
	s_mov_b32 s4, 0xb1000
	v_add_f32_e32 v134, 1.0, v134
	v_add_f32_e32 v135, 1.0, v135
	v_rcp_f32_e32 v134, v134
	v_rcp_f32_e32 v135, v135
	s_nop 0
	v_pk_fma_f32 v[134:135], v[134:135], v[146:147], v[136:137]
	v_cvt_pk_bf16_f32 v136, v130, v131
	v_pk_mul_f32 v[130:131], v[130:131], v[130:131]
	v_cvt_pk_bf16_f32 v137, v134, v135
	v_pk_mul_f32 v[134:135], v[134:135], v[134:135]
	v_add_f32_e32 v130, v130, v131
	v_add_f32_e32 v130, v130, v134
	v_add_f32_e32 v130, v135, v130
	v_add_co_u32_e32 v146, vcc, s4, v164
	s_nop 0
	v_add_f32_dpp v130, v130, v130 quad_perm:[1,0,3,2] row_mask:0xf bank_mask:0xf bound_ctrl:1
	v_addc_co_u32_e32 v147, vcc, 0, v165, vcc
	s_nop 0
	v_add_f32_dpp v130, v130, v130 quad_perm:[2,3,0,1] row_mask:0xf bank_mask:0xf bound_ctrl:1
	global_store_dwordx2 v[146:147], v[136:137], off nt
	s_nop 0
	v_add_f32_dpp v130, v130, v130 row_ror:4 row_mask:0xf bank_mask:0xf bound_ctrl:1
	s_nop 1
	v_mov_b32_dpp v131, v130 row_ror:8 row_mask:0xf bank_mask:0xf bound_ctrl:1
	s_and_saveexec_b64 s[4:5], s[0:1]
	s_cbranch_execz .LBB0_743
	v_add_f32_e32 v130, v130, v131
	global_atomic_add_f32 v[162:163], v130, off offset:708
; __device__ __forceinline__ float fdiv(float a, float b) { return a * __builtin_amdgcn_rcpf(b); }
; __device__ __forceinline__ float bf2f(u16 h) { return __uint_as_float(((unsigned)h) << 16); }
; __device__ __forceinline__ void gemm_tile(const Params& P, const GArgs& ga, const TileDesc& td, int wid_s) {
;     ...
;       static_for<8>([&](auto ic2) __attribute__((always_inline)) {
;         constexpr int idx = b0 + decltype(ic2)::v; constexpr int ai = idx >> 4, m = (idx >> 2) & 3, j = idx & 3;
;         constexpr int rl = ai * HALF + m * 16 + j; constexpr int q = decltype(ic2)::v;
;         const float rs = rsv[idx];
;         float4 v;
;         v.x = r[q].x + fdiv(1.f, 1.f + __expf(-rs * acc[ai][0][m][0][j])) * bf2f((u16)(pe[q].x & 0xffff));
;         v.y = r[q].y + fdiv(1.f, 1.f + __expf(-rs * acc[ai][0][m][1][j])) * bf2f((u16)(pe[q].x >> 16));
;         v.z = r[q].z + fdiv(1.f, 1.f + __expf(-rs * acc[ai][1][m][0][j])) * bf2f((u16)(pe[q].y & 0xffff));
;         v.w = r[q].w + fdiv(1.f, 1.f + __expf(-rs * acc[ai][1][m][1][j])) * bf2f((u16)(pe[q].y >> 16));
;         uint2 o; o.x = pack2(v.x, v.y); o.y = pack2(v.z, v.w);
;         *reinterpret_cast<uint2*>(h4b + (size_t)rl * DM) = o;
;         float s = red16(v.x * v.x + v.y * v.y + v.z * v.z + v.w * v.w);
;         if (efr == 0) unsafeAtomicAdd(sso + rl, s);
;       });
.LBB0_743:
	s_or_b64 exec, exec, s[4:5]
	v_mov_b32_e32 v136, s17
	v_fmamk_f32 v132, v132, 0x3a000000, v136
	v_rsq_f32_e32 v132, v132
	s_waitcnt vmcnt(9)
	v_lshlrev_b32_e32 v130, 16, v144
	v_and_b32_e32 v131, 0xffff0000, v144
	v_lshlrev_b32_e32 v134, 16, v145
	v_mul_f32_e64 v136, v4, -v132
	v_mul_f32_e64 v137, v8, -v132
	v_mul_f32_e32 v136, 0x3fb8aa3b, v136
	v_mul_f32_e32 v137, 0x3fb8aa3b, v137
	v_exp_f32_e32 v136, v136
	v_exp_f32_e32 v137, v137
	v_and_b32_e32 v135, 0xffff0000, v145
	s_waitcnt vmcnt(8)
	v_lshlrev_b32_e32 v144, 16, v142
	v_add_f32_e32 v136, 1.0, v136
	v_add_f32_e32 v137, 1.0, v137
	v_rcp_f32_e32 v136, v136
	v_rcp_f32_e32 v137, v137
	v_and_b32_e32 v145, 0xffff0000, v142
	v_lshlrev_b32_e32 v142, 16, v143
	v_and_b32_e32 v143, 0xffff0000, v143
	v_pk_fma_f32 v[130:131], v[136:137], v[144:145], v[130:131]
	v_mul_f32_e64 v136, v16, -v132
	v_mul_f32_e64 v132, v12, -v132
	v_mul_f32_e32 v136, 0x3fb8aa3b, v136
	v_mul_f32_e32 v132, 0x3fb8aa3b, v132
	v_exp_f32_e32 v136, v136
	v_exp_f32_e32 v132, v132
	s_mov_b32 s4, 0xb2000
	v_add_f32_e32 v136, 1.0, v136
	v_add_f32_e32 v132, 1.0, v132
	v_rcp_f32_e32 v136, v136
	v_rcp_f32_e32 v137, v132
	s_nop 0
	v_pk_fma_f32 v[134:135], v[136:137], v[142:143], v[134:135]
	v_cvt_pk_bf16_f32 v136, v130, v131
	v_pk_mul_f32 v[130:131], v[130:131], v[130:131]
	v_cvt_pk_bf16_f32 v137, v134, v135
	v_pk_mul_f32 v[134:135], v[134:135], v[134:135]
	v_add_f32_e32 v130, v130, v131
	v_add_f32_e32 v130, v130, v134
	v_add_f32_e32 v130, v135, v130
	v_add_co_u32_e32 v142, vcc, s4, v164
	s_nop 0
	v_add_f32_dpp v130, v130, v130 quad_perm:[1,0,3,2] row_mask:0xf bank_mask:0xf bound_ctrl:1
	v_addc_co_u32_e32 v143, vcc, 0, v165, vcc
	s_nop 0
	v_add_f32_dpp v130, v130, v130 quad_perm:[2,3,0,1] row_mask:0xf bank_mask:0xf bound_ctrl:1
	global_store_dwordx2 v[142:143], v[136:137], off nt
	s_nop 0
	v_add_f32_dpp v130, v130, v130 row_ror:4 row_mask:0xf bank_mask:0xf bound_ctrl:1
	s_nop 1
	v_mov_b32_dpp v131, v130 row_ror:8 row_mask:0xf bank_mask:0xf bound_ctrl:1
	s_and_saveexec_b64 s[4:5], s[0:1]
	s_cbranch_execz .LBB0_745
	v_add_f32_e32 v130, v130, v131
	global_atomic_add_f32 v[162:163], v130, off offset:712
.LBB0_745:
	s_or_b64 exec, exec, s[4:5]
	v_mov_b32_e32 v132, s17
	v_fmamk_f32 v132, v133, 0x3a000000, v132
	s_waitcnt vmcnt(8)
	v_lshlrev_b32_e32 v130, 16, v140
	v_and_b32_e32 v131, 0xffff0000, v140
	v_rsq_f32_e32 v140, v132
	s_waitcnt vmcnt(7)
	v_lshlrev_b32_e32 v136, 16, v138
	v_and_b32_e32 v137, 0xffff0000, v138
	v_lshlrev_b32_e32 v134, 16, v141
	v_mul_f32_e64 v132, v5, -v140
	v_mul_f32_e64 v133, v9, -v140
	v_mul_f32_e32 v132, 0x3fb8aa3b, v132
	v_mul_f32_e32 v133, 0x3fb8aa3b, v133
	v_exp_f32_e32 v132, v132
	v_exp_f32_e32 v133, v133
	v_and_b32_e32 v135, 0xffff0000, v141
	s_mov_b32 s4, 0xb3000
	v_add_f32_e32 v132, 1.0, v132
	v_add_f32_e32 v133, 1.0, v133
	v_rcp_f32_e32 v132, v132
	v_rcp_f32_e32 v133, v133
	s_nop 0
	v_pk_fma_f32 v[130:131], v[132:133], v[136:137], v[130:131]
	v_mul_f32_e64 v132, v17, -v140
	v_mul_f32_e64 v133, v13, -v140
	v_mul_f32_e32 v132, 0x3fb8aa3b, v132
	v_mul_f32_e32 v133, 0x3fb8aa3b, v133
	v_exp_f32_e32 v132, v132
	v_exp_f32_e32 v133, v133
	v_lshlrev_b32_e32 v136, 16, v139
	v_and_b32_e32 v137, 0xffff0000, v139
	v_add_f32_e32 v132, 1.0, v132
	v_add_f32_e32 v133, 1.0, v133
	v_rcp_f32_e32 v132, v132
	v_rcp_f32_e32 v133, v133
	s_nop 0
	v_pk_fma_f32 v[132:133], v[132:133], v[136:137], v[134:135]
	v_cvt_pk_bf16_f32 v134, v130, v131
	v_pk_mul_f32 v[130:131], v[130:131], v[130:131]
	v_cvt_pk_bf16_f32 v135, v132, v133
	v_pk_mul_f32 v[132:133], v[132:133], v[132:133]
	v_add_f32_e32 v130, v130, v131
	v_add_f32_e32 v130, v130, v132
	v_add_f32_e32 v130, v133, v130
	v_add_co_u32_e32 v136, vcc, s4, v164
	s_nop 0
	v_add_f32_dpp v130, v130, v130 quad_perm:[1,0,3,2] row_mask:0xf bank_mask:0xf bound_ctrl:1
	v_addc_co_u32_e32 v137, vcc, 0, v165, vcc
	s_nop 0
	v_add_f32_dpp v130, v130, v130 quad_perm:[2,3,0,1] row_mask:0xf bank_mask:0xf bound_ctrl:1
	global_store_dwordx2 v[136:137], v[134:135], off nt
	s_nop 0
	v_add_f32_dpp v130, v130, v130 row_ror:4 row_mask:0xf bank_mask:0xf bound_ctrl:1
	s_nop 1
	v_mov_b32_dpp v131, v130 row_ror:8 row_mask:0xf bank_mask:0xf bound_ctrl:1
	s_and_saveexec_b64 s[4:5], s[0:1]
	s_cbranch_execz .LBB0_747
	v_add_f32_e32 v130, v130, v131
	global_atomic_add_f32 v[162:163], v130, off offset:716
